# GEMM K-loops: LDS-DMA issue rebalanced 3/5 between load segments (A piece-1 stage deferred to the next SP1 segment, SP2 waits vmcnt(7))
# speedup vs baseline: 1.0120x; 1.0045x over previous
; #define PG8_STAGE(bufoff, gbase, voff) do { _Pragma("unroll") for (int _i = 0; _i < 2; ++_i) \
;         __builtin_amdgcn_global_load_lds((const unsigned*)((const char*)(gbase) + (voff)[_i]), (PG8_LAS unsigned*)(lds + (bufoff) + ldsw + _i * 8192), 16, 0, 0); } while (0)
; #define PG8_WAIT_V(n) asm volatile("s_waitcnt vmcnt(" #n ")" ::: "memory")
; template <class Epi, class Sched, bool ALIGN_EPI = false, bool SP2 = false>
; __device__ __forceinline__ void gemm_phase(PG8_LAS unsigned char* lds, const Gemm g, const Sched& S, const Epi& E, const int tid_in) {
;     ...
;     const int tid = tid_l, wid = __builtin_amdgcn_readfirstlane(tid >> 6), lane = tid & 63, wr = wid >> 2, wc = wid & 3, fr = lane & 15, fq = lane >> 4;
;     const int K = g.K, nt = K / BK;
;     unsigned voffA[2], voffB[2];
; #pragma unroll
;     for (int i = 0; i < 2; ++i) { int R, C; stage_rc(tid * 16 + i * 8192, R, C); const int Rb = perm_row<Epi::PMODE>(R);
;         voffA[i] = (unsigned)(R * K + C) * 2u; voffB[i] = (unsigned)(Rb * K + C) * 2u; }
;     const size_t kstep = (size_t)(BK * 2);
;     const size_t hstep = (size_t)HALF * K * 2;
;     const size_t tstep = 2 * hstep;
;     const unsigned ldsw = (unsigned)wid * 1024u;
;     const int aoff = lds_byte(wr * 64 + fr, fq * 8), boff = lds_byte(wc * 32 + fr, fq * 8);
;     ...
;     Unit cur, nxt; int ui = 0;
;     if (!S.next(0, cur)) return;
;     f32x4 acc[2][2][4][2];
; #pragma unroll
;     for (int a = 0; a < 2; ++a)
; #pragma unroll
;         for (int b = 0; b < 2; ++b)
; #pragma unroll
;             for (int m = 0; m < 4; ++m)
; #pragma unroll
;                 for (int n = 0; n < 2; ++n) acc[a][b][m][n] = (f32x4){0.f, 0.f, 0.f, 0.f};
;     bf16x8 At[4][2], B0[2][2], B1[2][2];
;     const char* cA = (const char*)g.A + (size_t)cur.pm * tstep; const char* cB = (const char*)g.Bt + (size_t)cur.pn * tstep;
;     S.a_ready(cur);
;     if constexpr (Epi::PREF) E.prefetch(cur, 0, lds, wid, lane);
;     if constexpr (SP2) {
;         PG8_STAGE(PG8_SB(0, 0), cB, voffB); PG8_STAGE(PG8_SB(0, 1), cB + hstep, voffB); PG8_STAGE(PG8_SA(0, 0), cA, voffA); PG8_STAGE(PG8_SA(0, 1), cA + hstep, voffA);
;         if (wr == 1) PG8_BAR;
;         PG8_WAIT_V(2); PG8_BAR;
;         PG8_STAGE(PG8_SB(1, 0), cB + kstep, voffB); PG8_STAGE(PG8_SA(1, 0), cA + kstep, voffA); PG8_STAGE(PG8_SB(1, 1), cB + hstep + kstep, voffB);
;         PG8_WAIT_V(6); PG8_BAR;
.LBB0_346:
	s_add_u32 s6, s20, 0x35000000
	s_addc_u32 s7, s21, 0
	s_add_u32 s20, s20, 0x3b000000
	v_lshrrev_b32_e32 v16, 1, v14
	s_addc_u32 s21, s21, 0
	v_and_b32_e32 v16, 24, v16
	s_lshl_b32 s23, s23, 5
	v_and_b32_e32 v15, 15, v14
	v_lshlrev_b32_e32 v17, 1, v16
	v_lshlrev_b32_e32 v14, 2, v14
	s_and_b32 s26, s23, 0x60
	s_add_i32 m0, s44, 0x18000
	v_lshl_add_u64 v[6:7], v[6:7], 0, s[12:13]
	v_lshl_or_b32 v21, s24, 6, v15
	v_lshl_or_b32 v15, v15, 6, v17
	s_lshl_b32 s24, s24, 13
	v_and_b32_e32 v14, 32, v14
	s_lshl_b32 s23, s26, 7
	s_waitcnt vmcnt(2)
	s_barrier
	global_load_lds_dwordx4 v[6:7], off
	v_lshl_add_u64 v[4:5], v[4:5], 0, s[12:13]
	s_add_i32 m0, s44, 0x1a000
	s_add_i32 s48, s44, 0x8000
	s_add_i32 s49, s44, 0xa000
	v_bitop3_b32 v17, v15, s24, v14 bitop3:0xde
	global_load_lds_dwordx4 v[4:5], off
	v_lshl_add_u64 v[0:1], v[0:1], 0, s[12:13]
	s_mov_b32 m0, s48
	s_add_u32 s100, s34, 0x80
	s_addc_u32 s101, s35, 0
	s_add_u32 s24, s38, 0x80080
	global_load_lds_dwordx4 v[0:1], off
	v_lshl_add_u64 v[0:1], v[2:3], 0, s[12:13]
	s_mov_b32 m0, s49
	s_addc_u32 s25, s39, 0
	global_load_lds_dwordx4 v[0:1], off
	s_add_i32 m0, s44, 0x1c000
	v_lshl_add_u64 v[0:1], s[24:25], 0, v[134:135]
	global_load_lds_dwordx4 v[0:1], off
	v_lshl_add_u64 v[0:1], s[24:25], 0, v[130:131]
	s_add_i32 m0, s44, 0x1e000
	s_cmpk_lt_u32 s22, 0x100
	global_load_lds_dwordx4 v[0:1], off
	v_lshlrev_b32_e32 v0, 15, v12
	v_and_b32_e32 v0, 0xffff0000, v0
	v_lshl_add_u32 v0, v11, 12, v0
	v_and_b32_e32 v1, 1, v12
	v_lshl_or_b32 v0, v1, 6, v0
	v_lshl_add_u32 v138, v13, 1, v0
	v_lshlrev_b32_e32 v0, 15, v8
	v_and_b32_e32 v0, 0xffff0000, v0
	s_waitcnt vmcnt(6)
	v_lshl_add_u32 v0, v9, 12, v0
	v_and_b32_e32 v1, 1, v8
	v_lshl_or_b32 v0, v1, 6, v0
	v_readlane_b32 s24, v254, 13
	v_bitop3_b32 v142, v15, s23, v14 bitop3:0xde
	s_cselect_b64 s[22:23], -1, 0
	v_or_b32_e32 v143, s26, v16
	v_mov_b32_e32 v139, v20
	v_lshl_add_u32 v140, v10, 1, v0
	v_mov_b32_e32 v141, v20
	s_mov_b32 s50, 0
	v_add_u32_e32 v144, 0, v17
	v_readlane_b32 s52, v254, 27
	s_mov_b32 s51, s24
	s_barrier
	v_readlane_b32 s25, v254, 14
	s_branch .LBB0_349

; #define PG8_STAGE(bufoff, gbase, voff) do { _Pragma("unroll") for (int _i = 0; _i < 2; ++_i) \
;         __builtin_amdgcn_global_load_lds((const unsigned*)((const char*)(gbase) + (voff)[_i]), (PG8_LAS unsigned*)(lds + (bufoff) + ldsw + _i * 8192), 16, 0, 0); } while (0)
; #define PG8_LDA(dst, b, h) do { _Pragma("unroll") for (int m = 0; m < 4; ++m) _Pragma("unroll") for (int k = 0; k < 2; ++k) dst[m][k] = *(const PG8_LAS bf16x8*)(lds + PG8_SA(b, h) + aoff + m * 2048 + k * 1024); } while (0)
; #define PG8_LDB(dst, b, h) do { _Pragma("unroll") for (int n = 0; n < 2; ++n) _Pragma("unroll") for (int k = 0; k < 2; ++k) dst[n][k] = *(const PG8_LAS bf16x8*)(lds + PG8_SB(b, h) + boff + n * 2048 + k * 1024); } while (0)
; #define PG8_WAIT_V(n) asm volatile("s_waitcnt vmcnt(" #n ")" ::: "memory")
; #define PG8_WAIT_L(n) asm volatile("s_waitcnt lgkmcnt(" #n ")" ::: "memory")
; template <class Epi, class Sched, bool ALIGN_EPI = false, bool SP2 = false>
; __device__ __forceinline__ void gemm_phase(PG8_LAS unsigned char* lds, const Gemm g, const Sched& S, const Epi& E, const int tid_in) {
;     ...
;         const bool has_next = S.next(ui + 1, nxt);
;         const char* nA = has_next ? (const char*)g.A + (size_t)nxt.pm * tstep : cA; const char* nB = has_next ? (const char*)g.Bt + (size_t)nxt.pn * tstep : cB;
;         for (int t = 0; t < nt; t += 2) {
;             if constexpr (Epi::KSPLIT > 0) { if (t == Epi::KSPLIT / BK) E.midk(acc, cur, wr, wc, fr, fq); }
;             const bool last = (t == nt - 2);
;             const char* a1 = cA + (size_t)(t + 1) * kstep;
;             const char* a2 = last ? nA : cA + (size_t)(t + 2) * kstep; const char* b2 = last ? nB : cB + (size_t)(t + 2) * kstep;
;             const char* a3 = a2 + kstep; const char* b3 = b2 + kstep;
;             if (last && has_next) S.a_ready(nxt);
;             if constexpr (SP2) {
;             PG8_LDB(B0, 0, 0); PG8_LDB(B1, 0, 1); PG8_SCHED; PG8_LDA(At, 0, 0); PG8_STAGE(PG8_SA(1, 1), a1 + hstep, voffA);
;             PG8_WAIT_V(8); PG8_WAIT_L(0); PG8_BAR; PG8_MMA(0, 0, At, B0); PG8_MMA(0, 1, At, B1); PG8_BAR; PG8_SCHED;
;             PG8_LDA(At, 0, 1); PG8_STAGE(PG8_SB(0, 0), b2, voffB); PG8_STAGE(PG8_SB(0, 1), b2 + hstep, voffB); PG8_STAGE(PG8_SA(0, 0), a2, voffA);
;             PG8_WAIT_V(8); PG8_WAIT_L(0); PG8_BAR; PG8_MMA(1, 0, At, B0); PG8_MMA(1, 1, At, B1); PG8_BAR; PG8_SCHED;
.LBB0_352:
	s_mov_b32 m0, s49
	s_nop 0
	global_load_lds_dwordx4 v132, s[100:101]
	s_add_u32 s38, s34, 0xfff80080
	s_addc_u32 s39, s35, -1
	s_add_i32 s58, 0, 0x10000
	s_cmp_eq_u32 s57, 28
	s_cselect_b32 s43, s27, s39
	s_cselect_b32 s42, s53, s38
	v_add_u32_e32 v145, s58, v142
	s_cselect_b32 s39, s25, s56
	s_cselect_b32 s38, s54, s55
	s_add_i32 s60, 0, 0x14000
	ds_read_b128 v[146:149], v145
	ds_read_b128 v[150:153], v145 offset:1024
	ds_read_b128 v[154:157], v145 offset:2048
	ds_read_b128 v[158:161], v145 offset:3072
	v_add_u32_e32 v145, s60, v142
	ds_read_b128 v[162:165], v145
	ds_read_b128 v[166:169], v145 offset:1024
	ds_read_b128 v[170:173], v145 offset:2048
	ds_read_b128 v[174:177], v145 offset:3072
	s_add_i32 m0, s44, 0xc000
	ds_read_b128 v[178:181], v144
	ds_read_b128 v[182:185], v144 offset:1024
	ds_read_b128 v[186:189], v144 offset:2048
	ds_read_b128 v[190:193], v144 offset:3072
	ds_read_b128 v[194:197], v144 offset:4096
	ds_read_b128 v[198:201], v144 offset:5120
	ds_read_b128 v[202:205], v144 offset:6144
	ds_read_b128 v[208:211], v144 offset:7168
	global_load_lds_dwordx4 v138, s[34:35]
	s_add_i32 m0, s44, 0xe000
	s_nop 0
	global_load_lds_dwordx4 v140, s[34:35]
	s_waitcnt vmcnt(8)
	s_waitcnt lgkmcnt(0)
	s_barrier
	s_setprio 1
	s_waitcnt lgkmcnt(0)
	v_mfma_f32_16x16x32_bf16 v[126:129], v[146:149], v[178:181], v[126:129]
	v_mfma_f32_16x16x32_bf16 v[122:125], v[154:157], v[178:181], v[122:125]
	v_mfma_f32_16x16x32_bf16 v[114:117], v[146:149], v[186:189], v[114:117]
	v_mfma_f32_16x16x32_bf16 v[106:109], v[154:157], v[186:189], v[106:109]
	v_mfma_f32_16x16x32_bf16 v[98:101], v[146:149], v[194:197], v[98:101]
	v_mfma_f32_16x16x32_bf16 v[90:93], v[154:157], v[194:197], v[90:93]
	v_mfma_f32_16x16x32_bf16 v[82:85], v[146:149], v[202:205], v[82:85]
	v_mfma_f32_16x16x32_bf16 v[74:77], v[154:157], v[202:205], v[74:77]
	v_mfma_f32_16x16x32_bf16 v[126:129], v[150:153], v[182:185], v[126:129]
	v_mfma_f32_16x16x32_bf16 v[122:125], v[158:161], v[182:185], v[122:125]
	v_mfma_f32_16x16x32_bf16 v[114:117], v[150:153], v[190:193], v[114:117]
	v_mfma_f32_16x16x32_bf16 v[106:109], v[158:161], v[190:193], v[106:109]
	v_mfma_f32_16x16x32_bf16 v[98:101], v[150:153], v[198:201], v[98:101]
	v_mfma_f32_16x16x32_bf16 v[90:93], v[158:161], v[198:201], v[90:93]
	v_mfma_f32_16x16x32_bf16 v[82:85], v[150:153], v[208:211], v[82:85]
	v_mfma_f32_16x16x32_bf16 v[74:77], v[158:161], v[208:211], v[74:77]
	s_setprio 0
	s_setprio 1
	v_mfma_f32_16x16x32_bf16 v[118:121], v[162:165], v[178:181], v[118:121]
	v_mfma_f32_16x16x32_bf16 v[110:113], v[170:173], v[178:181], v[110:113]
	v_mfma_f32_16x16x32_bf16 v[102:105], v[162:165], v[186:189], v[102:105]
	v_mfma_f32_16x16x32_bf16 v[94:97], v[170:173], v[186:189], v[94:97]
	v_mfma_f32_16x16x32_bf16 v[86:89], v[162:165], v[194:197], v[86:89]
	v_mfma_f32_16x16x32_bf16 v[78:81], v[170:173], v[194:197], v[78:81]
	v_mfma_f32_16x16x32_bf16 v[70:73], v[162:165], v[202:205], v[70:73]
	v_mfma_f32_16x16x32_bf16 v[66:69], v[170:173], v[202:205], v[66:69]
	v_mfma_f32_16x16x32_bf16 v[118:121], v[166:169], v[182:185], v[118:121]
	v_mfma_f32_16x16x32_bf16 v[110:113], v[174:177], v[182:185], v[110:113]
	v_mfma_f32_16x16x32_bf16 v[102:105], v[166:169], v[190:193], v[102:105]
	v_mfma_f32_16x16x32_bf16 v[94:97], v[174:177], v[190:193], v[94:97]
	v_mfma_f32_16x16x32_bf16 v[86:89], v[166:169], v[198:201], v[86:89]
	v_mfma_f32_16x16x32_bf16 v[78:81], v[174:177], v[198:201], v[78:81]
	v_mfma_f32_16x16x32_bf16 v[70:73], v[166:169], v[208:211], v[70:73]
	v_mfma_f32_16x16x32_bf16 v[66:69], v[174:177], v[208:211], v[66:69]
	s_setprio 0
	s_barrier
	s_add_i32 s58, s58, s19
	s_add_u32 s98, s38, 0x80
	s_addc_u32 s99, s39, 0
	s_mov_b32 m0, s58
	ds_read_b128 v[178:181], v144 offset:16384
	ds_read_b128 v[182:185], v144 offset:17408
	ds_read_b128 v[186:189], v144 offset:18432
	ds_read_b128 v[190:193], v144 offset:19456
	ds_read_b128 v[194:197], v144 offset:20480
	ds_read_b128 v[198:201], v144 offset:21504
	ds_read_b128 v[202:205], v144 offset:22528
	ds_read_b128 v[208:211], v144 offset:23552
	global_load_lds_dwordx4 v134, s[38:39]
	s_add_i32 m0, s58, 0x2000
	s_add_u32 s58, s38, 0x80000
	s_addc_u32 s59, s39, 0
	s_add_i32 s60, s60, s19
	global_load_lds_dwordx4 v130, s[38:39]
	s_mov_b32 m0, s60
	s_add_u32 s100, s42, 0x80
	s_addc_u32 s101, s43, 0
	global_load_lds_dwordx4 v134, s[58:59]
	s_add_i32 m0, s60, 0x2000
	s_nop 0
	global_load_lds_dwordx4 v130, s[58:59]
	s_mov_b32 m0, s44
	s_nop 0
	global_load_lds_dwordx4 v136, s[42:43]
	s_waitcnt vmcnt(7)
	s_waitcnt lgkmcnt(0)
	s_barrier
; #define PG8_STAGE(bufoff, gbase, voff) do { _Pragma("unroll") for (int _i = 0; _i < 2; ++_i) \
;         __builtin_amdgcn_global_load_lds((const unsigned*)((const char*)(gbase) + (voff)[_i]), (PG8_LAS unsigned*)(lds + (bufoff) + ldsw + _i * 8192), 16, 0, 0); } while (0)
; #define PG8_LDA(dst, b, h) do { _Pragma("unroll") for (int m = 0; m < 4; ++m) _Pragma("unroll") for (int k = 0; k < 2; ++k) dst[m][k] = *(const PG8_LAS bf16x8*)(lds + PG8_SA(b, h) + aoff + m * 2048 + k * 1024); } while (0)
; #define PG8_LDB(dst, b, h) do { _Pragma("unroll") for (int n = 0; n < 2; ++n) _Pragma("unroll") for (int k = 0; k < 2; ++k) dst[n][k] = *(const PG8_LAS bf16x8*)(lds + PG8_SB(b, h) + boff + n * 2048 + k * 1024); } while (0)
; #define PG8_MMA(ai, bj, At, Bt) do { __builtin_amdgcn_s_setprio(1); _Pragma("unroll") for (int m = 0; m < 4; ++m) _Pragma("unroll") for (int n = 0; n < 2; ++n) _Pragma("unroll") for (int k = 0; k < 2; ++k) \
;         acc[ai][bj][m][n] = __builtin_amdgcn_mfma_f32_16x16x32_bf16(Bt[n][k], At[m][k], acc[ai][bj][m][n], 0, 0, 0); __builtin_amdgcn_s_setprio(0); } while (0)
; #define PG8_WAIT_V(n) asm volatile("s_waitcnt vmcnt(" #n ")" ::: "memory")
; #define PG8_WAIT_L(n) asm volatile("s_waitcnt lgkmcnt(" #n ")" ::: "memory")
; #define PG8_BAR __builtin_amdgcn_s_barrier()
; #define PG8_SCHED __builtin_amdgcn_sched_barrier(0)
; template <class Epi, class Sched, bool ALIGN_EPI = false, bool SP2 = false>
; __device__ __forceinline__ void gemm_phase(PG8_LAS unsigned char* lds, const Gemm g, const Sched& S, const Epi& E, const int tid_in) {
;     ...
;             PG8_WAIT_V(8); PG8_WAIT_L(0); PG8_BAR; PG8_MMA(1, 0, At, B0); PG8_MMA(1, 1, At, B1); PG8_BAR; PG8_SCHED;
;             PG8_LDB(B0, 1, 0); PG8_LDB(B1, 1, 1); PG8_SCHED; PG8_LDA(At, 1, 0); PG8_STAGE(PG8_SA(0, 1), a2 + hstep, voffA);
;             PG8_WAIT_V(8); PG8_WAIT_L(0); PG8_BAR; PG8_MMA(0, 0, At, B0); PG8_MMA(0, 1, At, B1); PG8_BAR; PG8_SCHED;
	s_setprio 1
	s_waitcnt lgkmcnt(0)
	v_mfma_f32_16x16x32_bf16 v[62:65], v[146:149], v[178:181], v[62:65]
	v_mfma_f32_16x16x32_bf16 v[58:61], v[154:157], v[178:181], v[58:61]
	v_mfma_f32_16x16x32_bf16 v[50:53], v[146:149], v[186:189], v[50:53]
	v_mfma_f32_16x16x32_bf16 v[42:45], v[154:157], v[186:189], v[42:45]
	v_mfma_f32_16x16x32_bf16 v[34:37], v[146:149], v[194:197], v[34:37]
	v_mfma_f32_16x16x32_bf16 v[26:29], v[154:157], v[194:197], v[26:29]
	v_mfma_f32_16x16x32_bf16 v[16:19], v[146:149], v[202:205], v[16:19]
	v_mfma_f32_16x16x32_bf16 v[8:11], v[154:157], v[202:205], v[8:11]
	v_mfma_f32_16x16x32_bf16 v[62:65], v[150:153], v[182:185], v[62:65]
	v_mfma_f32_16x16x32_bf16 v[58:61], v[158:161], v[182:185], v[58:61]
	v_mfma_f32_16x16x32_bf16 v[50:53], v[150:153], v[190:193], v[50:53]
	v_mfma_f32_16x16x32_bf16 v[42:45], v[158:161], v[190:193], v[42:45]
	v_mfma_f32_16x16x32_bf16 v[34:37], v[150:153], v[198:201], v[34:37]
	v_mfma_f32_16x16x32_bf16 v[26:29], v[158:161], v[198:201], v[26:29]
	v_mfma_f32_16x16x32_bf16 v[16:19], v[150:153], v[208:211], v[16:19]
	v_mfma_f32_16x16x32_bf16 v[8:11], v[158:161], v[208:211], v[8:11]
	s_setprio 0
	s_setprio 1
	v_mfma_f32_16x16x32_bf16 v[54:57], v[162:165], v[178:181], v[54:57]
	v_mfma_f32_16x16x32_bf16 v[46:49], v[170:173], v[178:181], v[46:49]
	v_mfma_f32_16x16x32_bf16 v[38:41], v[162:165], v[186:189], v[38:41]
	v_mfma_f32_16x16x32_bf16 v[30:33], v[170:173], v[186:189], v[30:33]
	v_mfma_f32_16x16x32_bf16 v[22:25], v[162:165], v[194:197], v[22:25]
	v_mfma_f32_16x16x32_bf16 v[12:15], v[170:173], v[194:197], v[12:15]
	v_mfma_f32_16x16x32_bf16 v[4:7], v[162:165], v[202:205], v[4:7]
	v_mfma_f32_16x16x32_bf16 v[0:3], v[170:173], v[202:205], v[0:3]
	v_mfma_f32_16x16x32_bf16 v[54:57], v[166:169], v[182:185], v[54:57]
	v_mfma_f32_16x16x32_bf16 v[46:49], v[174:177], v[182:185], v[46:49]
	v_mfma_f32_16x16x32_bf16 v[38:41], v[166:169], v[190:193], v[38:41]
	v_mfma_f32_16x16x32_bf16 v[30:33], v[174:177], v[190:193], v[30:33]
	v_mfma_f32_16x16x32_bf16 v[22:25], v[166:169], v[198:201], v[22:25]
	v_mfma_f32_16x16x32_bf16 v[12:15], v[174:177], v[198:201], v[12:15]
	v_mfma_f32_16x16x32_bf16 v[4:7], v[166:169], v[208:211], v[4:7]
	v_mfma_f32_16x16x32_bf16 v[0:3], v[174:177], v[208:211], v[0:3]
	s_setprio 0
	s_barrier
	s_add_i32 s58, 0, 0x18000
	v_add_u32_e32 v145, s58, v142
	s_add_i32 s59, 0, 0x1c000
	ds_read_b128 v[146:149], v145
	ds_read_b128 v[150:153], v145 offset:1024
	ds_read_b128 v[154:157], v145 offset:2048
	ds_read_b128 v[158:161], v145 offset:3072
	v_add_u32_e32 v145, s59, v142
	ds_read_b128 v[162:165], v145
	ds_read_b128 v[166:169], v145 offset:1024
	ds_read_b128 v[170:173], v145 offset:2048
	ds_read_b128 v[174:177], v145 offset:3072
	s_mov_b32 m0, s45
	s_nop 0
	global_load_lds_dwordx4 v132, s[42:43]
	s_add_u32 s42, s42, 0x80000
	s_addc_u32 s43, s43, 0
	s_mov_b32 m0, s46
	ds_read_b128 v[178:181], v144 offset:32768
	ds_read_b128 v[182:185], v144 offset:33792
	ds_read_b128 v[186:189], v144 offset:34816
	ds_read_b128 v[190:193], v144 offset:35840
	ds_read_b128 v[194:197], v144 offset:36864
	ds_read_b128 v[198:201], v144 offset:37888
	ds_read_b128 v[202:205], v144 offset:38912
	ds_read_b128 v[208:211], v144 offset:39936
	global_load_lds_dwordx4 v136, s[42:43]
	s_mov_b32 m0, s47
	s_nop 0
	global_load_lds_dwordx4 v132, s[42:43]
	s_waitcnt vmcnt(8)
	s_waitcnt lgkmcnt(0)
	s_barrier
; #define PG8_STAGE(bufoff, gbase, voff) do { _Pragma("unroll") for (int _i = 0; _i < 2; ++_i) \
;         __builtin_amdgcn_global_load_lds((const unsigned*)((const char*)(gbase) + (voff)[_i]), (PG8_LAS unsigned*)(lds + (bufoff) + ldsw + _i * 8192), 16, 0, 0); } while (0)
; #define PG8_LDA(dst, b, h) do { _Pragma("unroll") for (int m = 0; m < 4; ++m) _Pragma("unroll") for (int k = 0; k < 2; ++k) dst[m][k] = *(const PG8_LAS bf16x8*)(lds + PG8_SA(b, h) + aoff + m * 2048 + k * 1024); } while (0)
; #define PG8_LDB(dst, b, h) do { _Pragma("unroll") for (int n = 0; n < 2; ++n) _Pragma("unroll") for (int k = 0; k < 2; ++k) dst[n][k] = *(const PG8_LAS bf16x8*)(lds + PG8_SB(b, h) + boff + n * 2048 + k * 1024); } while (0)
; #define PG8_MMA(ai, bj, At, Bt) do { __builtin_amdgcn_s_setprio(1); _Pragma("unroll") for (int m = 0; m < 4; ++m) _Pragma("unroll") for (int n = 0; n < 2; ++n) _Pragma("unroll") for (int k = 0; k < 2; ++k) \
;         acc[ai][bj][m][n] = __builtin_amdgcn_mfma_f32_16x16x32_bf16(Bt[n][k], At[m][k], acc[ai][bj][m][n], 0, 0, 0); __builtin_amdgcn_s_setprio(0); } while (0)
; #define PG8_WAIT_V(n) asm volatile("s_waitcnt vmcnt(" #n ")" ::: "memory")
; #define PG8_WAIT_L(n) asm volatile("s_waitcnt lgkmcnt(" #n ")" ::: "memory")
; #define PG8_BAR __builtin_amdgcn_s_barrier()
; #define PG8_SCHED __builtin_amdgcn_sched_barrier(0)
; template <class Epi, class Sched, bool ALIGN_EPI = false, bool SP2 = false>
; __device__ __forceinline__ void gemm_phase(PG8_LAS unsigned char* lds, const Gemm g, const Sched& S, const Epi& E, const int tid_in) {
;     ...
;             PG8_LDB(B0, 1, 0); PG8_LDB(B1, 1, 1); PG8_SCHED; PG8_LDA(At, 1, 0); PG8_STAGE(PG8_SA(0, 1), a2 + hstep, voffA);
;             PG8_WAIT_V(8); PG8_WAIT_L(0); PG8_BAR; PG8_MMA(0, 0, At, B0); PG8_MMA(0, 1, At, B1); PG8_BAR; PG8_SCHED;
;             PG8_LDA(At, 1, 1); PG8_STAGE(PG8_SB(1, 0), b3, voffB); PG8_STAGE(PG8_SB(1, 1), b3 + hstep, voffB); PG8_STAGE(PG8_SA(1, 0), a3, voffA);
;             PG8_WAIT_V(8); PG8_WAIT_L(0); PG8_BAR; PG8_MMA(1, 0, At, B0); PG8_MMA(1, 1, At, B1); PG8_BAR; PG8_SCHED;
	s_setprio 1
	s_waitcnt lgkmcnt(0)
	v_mfma_f32_16x16x32_bf16 v[126:129], v[146:149], v[178:181], v[126:129]
	v_mfma_f32_16x16x32_bf16 v[122:125], v[154:157], v[178:181], v[122:125]
	v_mfma_f32_16x16x32_bf16 v[114:117], v[146:149], v[186:189], v[114:117]
	v_mfma_f32_16x16x32_bf16 v[106:109], v[154:157], v[186:189], v[106:109]
	v_mfma_f32_16x16x32_bf16 v[98:101], v[146:149], v[194:197], v[98:101]
	v_mfma_f32_16x16x32_bf16 v[90:93], v[154:157], v[194:197], v[90:93]
	v_mfma_f32_16x16x32_bf16 v[82:85], v[146:149], v[202:205], v[82:85]
	v_mfma_f32_16x16x32_bf16 v[74:77], v[154:157], v[202:205], v[74:77]
	v_mfma_f32_16x16x32_bf16 v[126:129], v[150:153], v[182:185], v[126:129]
	v_mfma_f32_16x16x32_bf16 v[122:125], v[158:161], v[182:185], v[122:125]
	v_mfma_f32_16x16x32_bf16 v[114:117], v[150:153], v[190:193], v[114:117]
	v_mfma_f32_16x16x32_bf16 v[106:109], v[158:161], v[190:193], v[106:109]
	v_mfma_f32_16x16x32_bf16 v[98:101], v[150:153], v[198:201], v[98:101]
	v_mfma_f32_16x16x32_bf16 v[90:93], v[158:161], v[198:201], v[90:93]
	v_mfma_f32_16x16x32_bf16 v[82:85], v[150:153], v[208:211], v[82:85]
	v_mfma_f32_16x16x32_bf16 v[74:77], v[158:161], v[208:211], v[74:77]
	s_setprio 0
	s_setprio 1
	v_mfma_f32_16x16x32_bf16 v[118:121], v[162:165], v[178:181], v[118:121]
	v_mfma_f32_16x16x32_bf16 v[110:113], v[170:173], v[178:181], v[110:113]
	v_mfma_f32_16x16x32_bf16 v[102:105], v[162:165], v[186:189], v[102:105]
	v_mfma_f32_16x16x32_bf16 v[94:97], v[170:173], v[186:189], v[94:97]
	v_mfma_f32_16x16x32_bf16 v[86:89], v[162:165], v[194:197], v[86:89]
	v_mfma_f32_16x16x32_bf16 v[78:81], v[170:173], v[194:197], v[78:81]
	v_mfma_f32_16x16x32_bf16 v[70:73], v[162:165], v[202:205], v[70:73]
	v_mfma_f32_16x16x32_bf16 v[66:69], v[170:173], v[202:205], v[66:69]
	v_mfma_f32_16x16x32_bf16 v[118:121], v[166:169], v[182:185], v[118:121]
	v_mfma_f32_16x16x32_bf16 v[110:113], v[174:177], v[182:185], v[110:113]
	v_mfma_f32_16x16x32_bf16 v[102:105], v[166:169], v[190:193], v[102:105]
	v_mfma_f32_16x16x32_bf16 v[94:97], v[174:177], v[190:193], v[94:97]
	v_mfma_f32_16x16x32_bf16 v[86:89], v[166:169], v[198:201], v[86:89]
	v_mfma_f32_16x16x32_bf16 v[78:81], v[174:177], v[198:201], v[78:81]
	v_mfma_f32_16x16x32_bf16 v[70:73], v[166:169], v[208:211], v[70:73]
	v_mfma_f32_16x16x32_bf16 v[66:69], v[174:177], v[208:211], v[66:69]
	s_setprio 0
	s_barrier
	s_add_i32 s42, s58, s19
	s_mov_b32 m0, s42
	ds_read_b128 v[178:181], v144 offset:49152
	ds_read_b128 v[182:185], v144 offset:50176
	ds_read_b128 v[186:189], v144 offset:51200
	ds_read_b128 v[190:193], v144 offset:52224
	ds_read_b128 v[194:197], v144 offset:53248
	ds_read_b128 v[198:201], v144 offset:54272
	ds_read_b128 v[202:205], v144 offset:55296
	ds_read_b128 v[208:211], v144 offset:56320
	global_load_lds_dwordx4 v134, s[98:99]
	s_add_i32 m0, s42, 0x2000
	s_add_u32 s38, s38, 0x80080
	s_addc_u32 s39, s39, 0
	s_add_i32 s42, s59, s19
	global_load_lds_dwordx4 v130, s[98:99]
	s_mov_b32 m0, s42
	s_nop 0
	global_load_lds_dwordx4 v134, s[38:39]
	s_add_i32 m0, s42, 0x2000
	s_nop 0
	global_load_lds_dwordx4 v130, s[38:39]
	s_mov_b32 m0, s48
	s_nop 0
	global_load_lds_dwordx4 v136, s[100:101]
	s_waitcnt vmcnt(7)
	s_waitcnt lgkmcnt(0)
	s_barrier
	s_setprio 1
	s_waitcnt lgkmcnt(0)
	v_mfma_f32_16x16x32_bf16 v[62:65], v[146:149], v[178:181], v[62:65]
	v_mfma_f32_16x16x32_bf16 v[58:61], v[154:157], v[178:181], v[58:61]
	v_mfma_f32_16x16x32_bf16 v[50:53], v[146:149], v[186:189], v[50:53]
	v_mfma_f32_16x16x32_bf16 v[42:45], v[154:157], v[186:189], v[42:45]
	v_mfma_f32_16x16x32_bf16 v[34:37], v[146:149], v[194:197], v[34:37]
	v_mfma_f32_16x16x32_bf16 v[26:29], v[154:157], v[194:197], v[26:29]
	v_mfma_f32_16x16x32_bf16 v[16:19], v[146:149], v[202:205], v[16:19]
	v_mfma_f32_16x16x32_bf16 v[8:11], v[154:157], v[202:205], v[8:11]
	v_mfma_f32_16x16x32_bf16 v[62:65], v[150:153], v[182:185], v[62:65]
	v_mfma_f32_16x16x32_bf16 v[58:61], v[158:161], v[182:185], v[58:61]
	v_mfma_f32_16x16x32_bf16 v[50:53], v[150:153], v[190:193], v[50:53]
	v_mfma_f32_16x16x32_bf16 v[42:45], v[158:161], v[190:193], v[42:45]
	v_mfma_f32_16x16x32_bf16 v[34:37], v[150:153], v[198:201], v[34:37]
	v_mfma_f32_16x16x32_bf16 v[26:29], v[158:161], v[198:201], v[26:29]
	v_mfma_f32_16x16x32_bf16 v[16:19], v[150:153], v[208:211], v[16:19]
	v_mfma_f32_16x16x32_bf16 v[8:11], v[158:161], v[208:211], v[8:11]
	s_setprio 0
	s_setprio 1
	v_mfma_f32_16x16x32_bf16 v[54:57], v[162:165], v[178:181], v[54:57]
	v_mfma_f32_16x16x32_bf16 v[46:49], v[170:173], v[178:181], v[46:49]
	v_mfma_f32_16x16x32_bf16 v[38:41], v[162:165], v[186:189], v[38:41]
	v_mfma_f32_16x16x32_bf16 v[30:33], v[170:173], v[186:189], v[30:33]
	v_mfma_f32_16x16x32_bf16 v[22:25], v[162:165], v[194:197], v[22:25]
	v_mfma_f32_16x16x32_bf16 v[12:15], v[170:173], v[194:197], v[12:15]
	v_mfma_f32_16x16x32_bf16 v[4:7], v[162:165], v[202:205], v[4:7]
	v_mfma_f32_16x16x32_bf16 v[0:3], v[170:173], v[202:205], v[0:3]
	v_mfma_f32_16x16x32_bf16 v[54:57], v[166:169], v[182:185], v[54:57]
	v_mfma_f32_16x16x32_bf16 v[46:49], v[174:177], v[182:185], v[46:49]
	v_mfma_f32_16x16x32_bf16 v[38:41], v[166:169], v[190:193], v[38:41]
	v_mfma_f32_16x16x32_bf16 v[30:33], v[174:177], v[190:193], v[30:33]
	v_mfma_f32_16x16x32_bf16 v[22:25], v[166:169], v[198:201], v[22:25]
	v_mfma_f32_16x16x32_bf16 v[12:15], v[174:177], v[198:201], v[12:15]
	v_mfma_f32_16x16x32_bf16 v[4:7], v[166:169], v[208:211], v[4:7]
	v_mfma_f32_16x16x32_bf16 v[0:3], v[174:177], v[208:211], v[0:3]
	s_setprio 0
	s_barrier
	s_add_i32 s57, s57, 2
	s_add_u32 s34, s34, 0x100
	s_addc_u32 s35, s35, 0
	s_add_u32 s55, s55, 0x100
	s_addc_u32 s56, s56, 0
	s_cmp_gt_u32 s57, 29
	s_cbranch_scc0 .LBB0_352
	s_and_b64 vcc, exec, s[22:23]
	s_cbranch_vccz .LBB0_355
	s_barrier

; #define PG8_STAGE(bufoff, gbase, voff) do { _Pragma("unroll") for (int _i = 0; _i < 2; ++_i) \
;         __builtin_amdgcn_global_load_lds((const unsigned*)((const char*)(gbase) + (voff)[_i]), (PG8_LAS unsigned*)(lds + (bufoff) + ldsw + _i * 8192), 16, 0, 0); } while (0)
; #define PG8_WAIT_V(n) asm volatile("s_waitcnt vmcnt(" #n ")" ::: "memory")
; template <class Epi, class Sched, bool ALIGN_EPI = false, bool SP2 = false>
; __device__ __forceinline__ void gemm_phase(PG8_LAS unsigned char* lds, const Gemm g, const Sched& S, const Epi& E, const int tid_in) {
;     ...
;     const int tid = tid_l, wid = __builtin_amdgcn_readfirstlane(tid >> 6), lane = tid & 63, wr = wid >> 2, wc = wid & 3, fr = lane & 15, fq = lane >> 4;
;     const int K = g.K, nt = K / BK;
;     unsigned voffA[2], voffB[2];
; #pragma unroll
;     for (int i = 0; i < 2; ++i) { int R, C; stage_rc(tid * 16 + i * 8192, R, C); const int Rb = perm_row<Epi::PMODE>(R);
;         voffA[i] = (unsigned)(R * K + C) * 2u; voffB[i] = (unsigned)(Rb * K + C) * 2u; }
;     const size_t kstep = (size_t)(BK * 2);
;     const size_t hstep = (size_t)HALF * K * 2;
;     const size_t tstep = 2 * hstep;
;     const unsigned ldsw = (unsigned)wid * 1024u;
;     const int aoff = lds_byte(wr * 64 + fr, fq * 8), boff = lds_byte(wc * 32 + fr, fq * 8);
;     ...
;     Unit cur, nxt; int ui = 0;
;     if (!S.next(0, cur)) return;
;     f32x4 acc[2][2][4][2];
; #pragma unroll
;     for (int a = 0; a < 2; ++a)
; #pragma unroll
;         for (int b = 0; b < 2; ++b)
; #pragma unroll
;             for (int m = 0; m < 4; ++m)
; #pragma unroll
;                 for (int n = 0; n < 2; ++n) acc[a][b][m][n] = (f32x4){0.f, 0.f, 0.f, 0.f};
;     bf16x8 At[4][2], B0[2][2], B1[2][2];
;     const char* cA = (const char*)g.A + (size_t)cur.pm * tstep; const char* cB = (const char*)g.Bt + (size_t)cur.pn * tstep;
;     S.a_ready(cur);
;     if constexpr (Epi::PREF) E.prefetch(cur, 0, lds, wid, lane);
;     if constexpr (SP2) {
;         PG8_STAGE(PG8_SB(0, 0), cB, voffB); PG8_STAGE(PG8_SB(0, 1), cB + hstep, voffB); PG8_STAGE(PG8_SA(0, 0), cA, voffA); PG8_STAGE(PG8_SA(0, 1), cA + hstep, voffA);
;         if (wr == 1) PG8_BAR;
;         PG8_WAIT_V(2); PG8_BAR;
;         PG8_STAGE(PG8_SB(1, 0), cB + kstep, voffB); PG8_STAGE(PG8_SA(1, 0), cA + kstep, voffA); PG8_STAGE(PG8_SB(1, 1), cB + hstep + kstep, voffB);
;         PG8_WAIT_V(6); PG8_BAR;
.LBB0_364:
	v_bfe_u32 v16, v14, 4, 2
	v_and_b32_e32 v15, 15, v14
	v_lshlrev_b32_e32 v18, 4, v16
	v_lshlrev_b32_e32 v14, 2, v14
	s_sext_i32_i16 s31, s6
	s_and_b32 s24, s22, 3
	v_lshl_or_b32 v17, s23, 6, v15
	v_lshl_or_b32 v15, v15, 6, v18
	s_lshl_b32 s6, s23, 13
	v_and_b32_e32 v14, 32, v14
	s_add_i32 m0, s44, 0x18000
	v_lshl_add_u64 v[6:7], v[6:7], 0, s[12:13]
	v_bitop3_b32 v18, v15, s6, v14 bitop3:0xde
	s_lshl_b32 s6, s24, 12
	s_waitcnt vmcnt(2)
	s_barrier
	global_load_lds_dwordx4 v[6:7], off
	v_lshl_add_u64 v[4:5], v[4:5], 0, s[12:13]
	s_add_i32 m0, s44, 0x1a000
	s_add_i32 s48, s44, 0x8000
	s_add_i32 s49, s44, 0xa000
	global_load_lds_dwordx4 v[4:5], off
	v_lshl_add_u64 v[0:1], v[0:1], 0, s[12:13]
	s_mov_b32 m0, s48
	s_add_u32 s100, s34, 0x80
	s_addc_u32 s101, s35, 0
	s_add_u32 s22, s38, 0x80080
	global_load_lds_dwordx4 v[0:1], off
	v_lshl_add_u64 v[0:1], v[2:3], 0, s[12:13]
	s_mov_b32 m0, s49
	s_addc_u32 s23, s39, 0
	global_load_lds_dwordx4 v[0:1], off
	s_add_i32 m0, s44, 0x1c000
	v_lshl_add_u64 v[0:1], s[22:23], 0, v[132:133]
	global_load_lds_dwordx4 v[0:1], off
	v_lshl_add_u64 v[0:1], s[22:23], 0, v[136:137]
	s_add_i32 m0, s44, 0x1e000
	s_cmpk_lt_u32 s7, 0x100
	global_load_lds_dwordx4 v[0:1], off
	v_lshlrev_b32_e32 v0, 11, v16
	v_mov_b32_e32 v1, v20
	v_lshl_add_u64 v[0:1], s[20:21], 0, v[0:1]
	s_mov_b64 s[20:21], 0x3b000000
	v_lshl_add_u64 v[138:139], v[0:1], 0, s[20:21]
	v_lshlrev_b32_e32 v0, 15, v8
	v_and_b32_e32 v0, 0xffff0000, v0
	v_lshl_add_u32 v0, v9, 12, v0
	v_and_b32_e32 v1, 1, v8
	v_lshl_or_b32 v0, v1, 6, v0
	v_lshl_add_u32 v140, v10, 1, v0
	v_lshlrev_b32_e32 v0, 15, v11
	v_and_b32_e32 v0, 0xffff0000, v0
	s_waitcnt vmcnt(6)
	v_lshl_add_u32 v0, v12, 12, v0
	v_and_b32_e32 v1, 1, v11
	v_bitop3_b32 v21, v15, s6, v14 bitop3:0xde
	s_cselect_b64 s[6:7], -1, 0
	s_lshl_b32 s22, s24, 3
	v_lshl_or_b32 v0, v1, 6, v0
	v_add_u32_e32 v146, 0x200, v17
	v_mov_b32_e32 v141, v20
	v_lshl_add_u32 v142, v13, 1, v0
	v_mov_b32_e32 v143, v20
	s_mov_b32 s50, 0
	v_add_u32_e32 v147, 0, v18
	s_lshl_b32 s20, s22, 1
	s_barrier
	s_branch .LBB0_367

; #define PG8_STAGE(bufoff, gbase, voff) do { _Pragma("unroll") for (int _i = 0; _i < 2; ++_i) \
;         __builtin_amdgcn_global_load_lds((const unsigned*)((const char*)(gbase) + (voff)[_i]), (PG8_LAS unsigned*)(lds + (bufoff) + ldsw + _i * 8192), 16, 0, 0); } while (0)
; #define PG8_LDA(dst, b, h) do { _Pragma("unroll") for (int m = 0; m < 4; ++m) _Pragma("unroll") for (int k = 0; k < 2; ++k) dst[m][k] = *(const PG8_LAS bf16x8*)(lds + PG8_SA(b, h) + aoff + m * 2048 + k * 1024); } while (0)
; #define PG8_LDB(dst, b, h) do { _Pragma("unroll") for (int n = 0; n < 2; ++n) _Pragma("unroll") for (int k = 0; k < 2; ++k) dst[n][k] = *(const PG8_LAS bf16x8*)(lds + PG8_SB(b, h) + boff + n * 2048 + k * 1024); } while (0)
; #define PG8_WAIT_V(n) asm volatile("s_waitcnt vmcnt(" #n ")" ::: "memory")
; #define PG8_WAIT_L(n) asm volatile("s_waitcnt lgkmcnt(" #n ")" ::: "memory")
; template <class Epi, class Sched, bool ALIGN_EPI = false, bool SP2 = false>
; __device__ __forceinline__ void gemm_phase(PG8_LAS unsigned char* lds, const Gemm g, const Sched& S, const Epi& E, const int tid_in) {
;     ...
;         const bool has_next = S.next(ui + 1, nxt);
;         const char* nA = has_next ? (const char*)g.A + (size_t)nxt.pm * tstep : cA; const char* nB = has_next ? (const char*)g.Bt + (size_t)nxt.pn * tstep : cB;
;         for (int t = 0; t < nt; t += 2) {
;             if constexpr (Epi::KSPLIT > 0) { if (t == Epi::KSPLIT / BK) E.midk(acc, cur, wr, wc, fr, fq); }
;             const bool last = (t == nt - 2);
;             const char* a1 = cA + (size_t)(t + 1) * kstep;
;             const char* a2 = last ? nA : cA + (size_t)(t + 2) * kstep; const char* b2 = last ? nB : cB + (size_t)(t + 2) * kstep;
;             const char* a3 = a2 + kstep; const char* b3 = b2 + kstep;
;             if (last && has_next) S.a_ready(nxt);
;             if constexpr (SP2) {
;             PG8_LDB(B0, 0, 0); PG8_LDB(B1, 0, 1); PG8_SCHED; PG8_LDA(At, 0, 0); PG8_STAGE(PG8_SA(1, 1), a1 + hstep, voffA);
;             PG8_WAIT_V(8); PG8_WAIT_L(0); PG8_BAR; PG8_MMA(0, 0, At, B0); PG8_MMA(0, 1, At, B1); PG8_BAR; PG8_SCHED;
;             PG8_LDA(At, 0, 1); PG8_STAGE(PG8_SB(0, 0), b2, voffB); PG8_STAGE(PG8_SB(0, 1), b2 + hstep, voffB); PG8_STAGE(PG8_SA(0, 0), a2, voffA);
;             PG8_WAIT_V(8); PG8_WAIT_L(0); PG8_BAR; PG8_MMA(1, 0, At, B0); PG8_MMA(1, 1, At, B1); PG8_BAR; PG8_SCHED;
.LBB0_374:
	s_mov_b32 m0, s49
	s_nop 0
	global_load_lds_dwordx4 v134, s[100:101]
	s_add_u32 s38, s34, 0xfff80080
	s_addc_u32 s39, s35, -1
	s_add_i32 s55, 0, 0x10000
	s_cmp_eq_u32 s54, 28
	s_cselect_b32 s43, s21, s39
	s_cselect_b32 s42, s25, s38
	v_add_u32_e32 v144, s55, v21
	s_cselect_b32 s39, s23, s53
	s_cselect_b32 s38, s51, s52
	s_add_i32 s58, 0, 0x14000
	ds_read_b128 v[148:151], v144
	ds_read_b128 v[152:155], v144 offset:1024
	ds_read_b128 v[156:159], v144 offset:2048
	ds_read_b128 v[160:163], v144 offset:3072
	v_add_u32_e32 v144, s58, v21
	ds_read_b128 v[164:167], v144
	ds_read_b128 v[168:171], v144 offset:1024
	ds_read_b128 v[172:175], v144 offset:2048
	ds_read_b128 v[176:179], v144 offset:3072
	s_add_i32 m0, s44, 0xc000
	ds_read_b128 v[180:183], v147
	ds_read_b128 v[184:187], v147 offset:1024
	ds_read_b128 v[188:191], v147 offset:2048
	ds_read_b128 v[192:195], v147 offset:3072
	ds_read_b128 v[196:199], v147 offset:4096
	ds_read_b128 v[200:203], v147 offset:5120
	ds_read_b128 v[208:211], v147 offset:6144
	ds_read_b128 v[212:215], v147 offset:7168
	global_load_lds_dwordx4 v140, s[34:35]
	s_add_i32 m0, s44, 0xe000
	s_nop 0
	global_load_lds_dwordx4 v142, s[34:35]
	s_waitcnt vmcnt(8)
	s_waitcnt lgkmcnt(0)
	s_barrier
	s_setprio 1
	s_waitcnt lgkmcnt(0)
	v_mfma_f32_16x16x32_bf16 v[126:129], v[148:151], v[180:183], v[126:129]
	v_mfma_f32_16x16x32_bf16 v[122:125], v[156:159], v[180:183], v[122:125]
	v_mfma_f32_16x16x32_bf16 v[118:121], v[148:151], v[188:191], v[118:121]
	v_mfma_f32_16x16x32_bf16 v[110:113], v[156:159], v[188:191], v[110:113]
	v_mfma_f32_16x16x32_bf16 v[102:105], v[148:151], v[196:199], v[102:105]
	v_mfma_f32_16x16x32_bf16 v[94:97], v[156:159], v[196:199], v[94:97]
	v_mfma_f32_16x16x32_bf16 v[86:89], v[148:151], v[208:211], v[86:89]
	v_mfma_f32_16x16x32_bf16 v[78:81], v[156:159], v[208:211], v[78:81]
	v_mfma_f32_16x16x32_bf16 v[126:129], v[152:155], v[184:187], v[126:129]
	v_mfma_f32_16x16x32_bf16 v[122:125], v[160:163], v[184:187], v[122:125]
	v_mfma_f32_16x16x32_bf16 v[118:121], v[152:155], v[192:195], v[118:121]
	v_mfma_f32_16x16x32_bf16 v[110:113], v[160:163], v[192:195], v[110:113]
	v_mfma_f32_16x16x32_bf16 v[102:105], v[152:155], v[200:203], v[102:105]
	v_mfma_f32_16x16x32_bf16 v[94:97], v[160:163], v[200:203], v[94:97]
	v_mfma_f32_16x16x32_bf16 v[86:89], v[152:155], v[212:215], v[86:89]
	v_mfma_f32_16x16x32_bf16 v[78:81], v[160:163], v[212:215], v[78:81]
	s_setprio 0
	s_setprio 1
	v_mfma_f32_16x16x32_bf16 v[114:117], v[164:167], v[180:183], v[114:117]
	v_mfma_f32_16x16x32_bf16 v[106:109], v[172:175], v[180:183], v[106:109]
	v_mfma_f32_16x16x32_bf16 v[98:101], v[164:167], v[188:191], v[98:101]
	v_mfma_f32_16x16x32_bf16 v[90:93], v[172:175], v[188:191], v[90:93]
	v_mfma_f32_16x16x32_bf16 v[82:85], v[164:167], v[196:199], v[82:85]
	v_mfma_f32_16x16x32_bf16 v[74:77], v[172:175], v[196:199], v[74:77]
	v_mfma_f32_16x16x32_bf16 v[70:73], v[164:167], v[208:211], v[70:73]
	v_mfma_f32_16x16x32_bf16 v[66:69], v[172:175], v[208:211], v[66:69]
	v_mfma_f32_16x16x32_bf16 v[114:117], v[168:171], v[184:187], v[114:117]
	v_mfma_f32_16x16x32_bf16 v[106:109], v[176:179], v[184:187], v[106:109]
	v_mfma_f32_16x16x32_bf16 v[98:101], v[168:171], v[192:195], v[98:101]
	v_mfma_f32_16x16x32_bf16 v[90:93], v[176:179], v[192:195], v[90:93]
	v_mfma_f32_16x16x32_bf16 v[82:85], v[168:171], v[200:203], v[82:85]
	v_mfma_f32_16x16x32_bf16 v[74:77], v[176:179], v[200:203], v[74:77]
	v_mfma_f32_16x16x32_bf16 v[70:73], v[168:171], v[212:215], v[70:73]
	v_mfma_f32_16x16x32_bf16 v[66:69], v[176:179], v[212:215], v[66:69]
	s_setprio 0
	s_barrier
	s_add_i32 s55, s55, s19
	s_add_u32 s98, s38, 0x80
	s_addc_u32 s99, s39, 0
	s_mov_b32 m0, s55
	ds_read_b128 v[180:183], v147 offset:16384
	ds_read_b128 v[184:187], v147 offset:17408
	ds_read_b128 v[188:191], v147 offset:18432
	ds_read_b128 v[192:195], v147 offset:19456
	ds_read_b128 v[196:199], v147 offset:20480
	ds_read_b128 v[200:203], v147 offset:21504
	ds_read_b128 v[208:211], v147 offset:22528
	ds_read_b128 v[212:215], v147 offset:23552
	global_load_lds_dwordx4 v132, s[38:39]
	s_add_i32 m0, s55, 0x2000
	s_add_u32 s56, s38, 0x80000
	s_addc_u32 s57, s39, 0
	s_add_i32 s55, s58, s19
	global_load_lds_dwordx4 v136, s[38:39]
	s_mov_b32 m0, s55
	s_add_u32 s100, s42, 0x80
	s_addc_u32 s101, s43, 0
	global_load_lds_dwordx4 v132, s[56:57]
	s_add_i32 m0, s55, 0x2000
	s_nop 0
	global_load_lds_dwordx4 v136, s[56:57]
	s_mov_b32 m0, s44
	s_nop 0
	global_load_lds_dwordx4 v130, s[42:43]
	s_waitcnt vmcnt(7)
	s_waitcnt lgkmcnt(0)
	s_barrier
; #define PG8_STAGE(bufoff, gbase, voff) do { _Pragma("unroll") for (int _i = 0; _i < 2; ++_i) \
;         __builtin_amdgcn_global_load_lds((const unsigned*)((const char*)(gbase) + (voff)[_i]), (PG8_LAS unsigned*)(lds + (bufoff) + ldsw + _i * 8192), 16, 0, 0); } while (0)
; #define PG8_LDA(dst, b, h) do { _Pragma("unroll") for (int m = 0; m < 4; ++m) _Pragma("unroll") for (int k = 0; k < 2; ++k) dst[m][k] = *(const PG8_LAS bf16x8*)(lds + PG8_SA(b, h) + aoff + m * 2048 + k * 1024); } while (0)
; #define PG8_LDB(dst, b, h) do { _Pragma("unroll") for (int n = 0; n < 2; ++n) _Pragma("unroll") for (int k = 0; k < 2; ++k) dst[n][k] = *(const PG8_LAS bf16x8*)(lds + PG8_SB(b, h) + boff + n * 2048 + k * 1024); } while (0)
; #define PG8_MMA(ai, bj, At, Bt) do { __builtin_amdgcn_s_setprio(1); _Pragma("unroll") for (int m = 0; m < 4; ++m) _Pragma("unroll") for (int n = 0; n < 2; ++n) _Pragma("unroll") for (int k = 0; k < 2; ++k) \
;         acc[ai][bj][m][n] = __builtin_amdgcn_mfma_f32_16x16x32_bf16(Bt[n][k], At[m][k], acc[ai][bj][m][n], 0, 0, 0); __builtin_amdgcn_s_setprio(0); } while (0)
; #define PG8_WAIT_V(n) asm volatile("s_waitcnt vmcnt(" #n ")" ::: "memory")
; #define PG8_WAIT_L(n) asm volatile("s_waitcnt lgkmcnt(" #n ")" ::: "memory")
; #define PG8_BAR __builtin_amdgcn_s_barrier()
; #define PG8_SCHED __builtin_amdgcn_sched_barrier(0)
; template <class Epi, class Sched, bool ALIGN_EPI = false, bool SP2 = false>
; __device__ __forceinline__ void gemm_phase(PG8_LAS unsigned char* lds, const Gemm g, const Sched& S, const Epi& E, const int tid_in) {
;     ...
;             PG8_WAIT_V(8); PG8_WAIT_L(0); PG8_BAR; PG8_MMA(1, 0, At, B0); PG8_MMA(1, 1, At, B1); PG8_BAR; PG8_SCHED;
;             PG8_LDB(B0, 1, 0); PG8_LDB(B1, 1, 1); PG8_SCHED; PG8_LDA(At, 1, 0); PG8_STAGE(PG8_SA(0, 1), a2 + hstep, voffA);
;             PG8_WAIT_V(8); PG8_WAIT_L(0); PG8_BAR; PG8_MMA(0, 0, At, B0); PG8_MMA(0, 1, At, B1); PG8_BAR; PG8_SCHED;
	s_setprio 1
	s_waitcnt lgkmcnt(0)
	v_mfma_f32_16x16x32_bf16 v[62:65], v[148:151], v[180:183], v[62:65]
	v_mfma_f32_16x16x32_bf16 v[58:61], v[156:159], v[180:183], v[58:61]
	v_mfma_f32_16x16x32_bf16 v[54:57], v[148:151], v[188:191], v[54:57]
	v_mfma_f32_16x16x32_bf16 v[46:49], v[156:159], v[188:191], v[46:49]
	v_mfma_f32_16x16x32_bf16 v[38:41], v[148:151], v[196:199], v[38:41]
	v_mfma_f32_16x16x32_bf16 v[30:33], v[156:159], v[196:199], v[30:33]
	v_mfma_f32_16x16x32_bf16 v[22:25], v[148:151], v[208:211], v[22:25]
	v_mfma_f32_16x16x32_bf16 v[12:15], v[156:159], v[208:211], v[12:15]
	v_mfma_f32_16x16x32_bf16 v[62:65], v[152:155], v[184:187], v[62:65]
	v_mfma_f32_16x16x32_bf16 v[58:61], v[160:163], v[184:187], v[58:61]
	v_mfma_f32_16x16x32_bf16 v[54:57], v[152:155], v[192:195], v[54:57]
	v_mfma_f32_16x16x32_bf16 v[46:49], v[160:163], v[192:195], v[46:49]
	v_mfma_f32_16x16x32_bf16 v[38:41], v[152:155], v[200:203], v[38:41]
	v_mfma_f32_16x16x32_bf16 v[30:33], v[160:163], v[200:203], v[30:33]
	v_mfma_f32_16x16x32_bf16 v[22:25], v[152:155], v[212:215], v[22:25]
	v_mfma_f32_16x16x32_bf16 v[12:15], v[160:163], v[212:215], v[12:15]
	s_setprio 0
	s_setprio 1
	v_mfma_f32_16x16x32_bf16 v[50:53], v[164:167], v[180:183], v[50:53]
	v_mfma_f32_16x16x32_bf16 v[42:45], v[172:175], v[180:183], v[42:45]
	v_mfma_f32_16x16x32_bf16 v[34:37], v[164:167], v[188:191], v[34:37]
	v_mfma_f32_16x16x32_bf16 v[26:29], v[172:175], v[188:191], v[26:29]
	v_mfma_f32_16x16x32_bf16 v[16:19], v[164:167], v[196:199], v[16:19]
	v_mfma_f32_16x16x32_bf16 v[8:11], v[172:175], v[196:199], v[8:11]
	v_mfma_f32_16x16x32_bf16 v[4:7], v[164:167], v[208:211], v[4:7]
	v_mfma_f32_16x16x32_bf16 v[0:3], v[172:175], v[208:211], v[0:3]
	v_mfma_f32_16x16x32_bf16 v[50:53], v[168:171], v[184:187], v[50:53]
	v_mfma_f32_16x16x32_bf16 v[42:45], v[176:179], v[184:187], v[42:45]
	v_mfma_f32_16x16x32_bf16 v[34:37], v[168:171], v[192:195], v[34:37]
	v_mfma_f32_16x16x32_bf16 v[26:29], v[176:179], v[192:195], v[26:29]
	v_mfma_f32_16x16x32_bf16 v[16:19], v[168:171], v[200:203], v[16:19]
	v_mfma_f32_16x16x32_bf16 v[8:11], v[176:179], v[200:203], v[8:11]
	v_mfma_f32_16x16x32_bf16 v[4:7], v[168:171], v[212:215], v[4:7]
	v_mfma_f32_16x16x32_bf16 v[0:3], v[176:179], v[212:215], v[0:3]
	s_setprio 0
	s_barrier
	s_add_i32 s55, 0, 0x18000
	s_add_i32 s56, 0, 0x1c000
	v_add_u32_e32 v160, s55, v21
	v_add_u32_e32 v176, s56, v21
	ds_read_b128 v[148:151], v160
	ds_read_b128 v[152:155], v160 offset:1024
	ds_read_b128 v[156:159], v160 offset:2048
	ds_read_b128 v[160:163], v160 offset:3072
	ds_read_b128 v[164:167], v176
	ds_read_b128 v[168:171], v176 offset:1024
	ds_read_b128 v[172:175], v176 offset:2048
	ds_read_b128 v[176:179], v176 offset:3072
	s_mov_b32 m0, s45
	s_nop 0
	global_load_lds_dwordx4 v134, s[42:43]
	s_add_u32 s42, s42, 0x80000
	s_addc_u32 s43, s43, 0
	s_mov_b32 m0, s46
	ds_read_b128 v[180:183], v147 offset:32768
	ds_read_b128 v[184:187], v147 offset:33792
	ds_read_b128 v[188:191], v147 offset:34816
	ds_read_b128 v[192:195], v147 offset:35840
	ds_read_b128 v[196:199], v147 offset:36864
	ds_read_b128 v[200:203], v147 offset:37888
	ds_read_b128 v[208:211], v147 offset:38912
	ds_read_b128 v[212:215], v147 offset:39936
	global_load_lds_dwordx4 v130, s[42:43]
	s_mov_b32 m0, s47
	s_nop 0
	global_load_lds_dwordx4 v134, s[42:43]
	s_waitcnt vmcnt(8)
	s_waitcnt lgkmcnt(0)
	s_barrier
	s_setprio 1
	s_waitcnt lgkmcnt(0)
	v_mfma_f32_16x16x32_bf16 v[126:129], v[148:151], v[180:183], v[126:129]
	v_mfma_f32_16x16x32_bf16 v[122:125], v[156:159], v[180:183], v[122:125]
	v_mfma_f32_16x16x32_bf16 v[118:121], v[148:151], v[188:191], v[118:121]
	v_mfma_f32_16x16x32_bf16 v[110:113], v[156:159], v[188:191], v[110:113]
	v_mfma_f32_16x16x32_bf16 v[102:105], v[148:151], v[196:199], v[102:105]
	v_mfma_f32_16x16x32_bf16 v[94:97], v[156:159], v[196:199], v[94:97]
	v_mfma_f32_16x16x32_bf16 v[86:89], v[148:151], v[208:211], v[86:89]
	v_mfma_f32_16x16x32_bf16 v[78:81], v[156:159], v[208:211], v[78:81]
	v_mfma_f32_16x16x32_bf16 v[126:129], v[152:155], v[184:187], v[126:129]
	v_mfma_f32_16x16x32_bf16 v[122:125], v[160:163], v[184:187], v[122:125]
	v_mfma_f32_16x16x32_bf16 v[118:121], v[152:155], v[192:195], v[118:121]
	v_mfma_f32_16x16x32_bf16 v[110:113], v[160:163], v[192:195], v[110:113]
	v_mfma_f32_16x16x32_bf16 v[102:105], v[152:155], v[200:203], v[102:105]
	v_mfma_f32_16x16x32_bf16 v[94:97], v[160:163], v[200:203], v[94:97]
	v_mfma_f32_16x16x32_bf16 v[86:89], v[152:155], v[212:215], v[86:89]
	v_mfma_f32_16x16x32_bf16 v[78:81], v[160:163], v[212:215], v[78:81]
	s_setprio 0
	s_setprio 1
	v_mfma_f32_16x16x32_bf16 v[114:117], v[164:167], v[180:183], v[114:117]
	v_mfma_f32_16x16x32_bf16 v[106:109], v[172:175], v[180:183], v[106:109]
	v_mfma_f32_16x16x32_bf16 v[98:101], v[164:167], v[188:191], v[98:101]
	v_mfma_f32_16x16x32_bf16 v[90:93], v[172:175], v[188:191], v[90:93]
	v_mfma_f32_16x16x32_bf16 v[82:85], v[164:167], v[196:199], v[82:85]
	v_mfma_f32_16x16x32_bf16 v[74:77], v[172:175], v[196:199], v[74:77]
	v_mfma_f32_16x16x32_bf16 v[70:73], v[164:167], v[208:211], v[70:73]
	v_mfma_f32_16x16x32_bf16 v[66:69], v[172:175], v[208:211], v[66:69]
	v_mfma_f32_16x16x32_bf16 v[114:117], v[168:171], v[184:187], v[114:117]
	v_mfma_f32_16x16x32_bf16 v[106:109], v[176:179], v[184:187], v[106:109]
	v_mfma_f32_16x16x32_bf16 v[98:101], v[168:171], v[192:195], v[98:101]
	v_mfma_f32_16x16x32_bf16 v[90:93], v[176:179], v[192:195], v[90:93]
	v_mfma_f32_16x16x32_bf16 v[82:85], v[168:171], v[200:203], v[82:85]
	v_mfma_f32_16x16x32_bf16 v[74:77], v[176:179], v[200:203], v[74:77]
	v_mfma_f32_16x16x32_bf16 v[70:73], v[168:171], v[212:215], v[70:73]
	v_mfma_f32_16x16x32_bf16 v[66:69], v[176:179], v[212:215], v[66:69]
	s_setprio 0
	s_barrier
; #define PG8_STAGE(bufoff, gbase, voff) do { _Pragma("unroll") for (int _i = 0; _i < 2; ++_i) \
;         __builtin_amdgcn_global_load_lds((const unsigned*)((const char*)(gbase) + (voff)[_i]), (PG8_LAS unsigned*)(lds + (bufoff) + ldsw + _i * 8192), 16, 0, 0); } while (0)
; #define PG8_LDA(dst, b, h) do { _Pragma("unroll") for (int m = 0; m < 4; ++m) _Pragma("unroll") for (int k = 0; k < 2; ++k) dst[m][k] = *(const PG8_LAS bf16x8*)(lds + PG8_SA(b, h) + aoff + m * 2048 + k * 1024); } while (0)
; #define PG8_MMA(ai, bj, At, Bt) do { __builtin_amdgcn_s_setprio(1); _Pragma("unroll") for (int m = 0; m < 4; ++m) _Pragma("unroll") for (int n = 0; n < 2; ++n) _Pragma("unroll") for (int k = 0; k < 2; ++k) \
;         acc[ai][bj][m][n] = __builtin_amdgcn_mfma_f32_16x16x32_bf16(Bt[n][k], At[m][k], acc[ai][bj][m][n], 0, 0, 0); __builtin_amdgcn_s_setprio(0); } while (0)
; #define PG8_WAIT_V(n) asm volatile("s_waitcnt vmcnt(" #n ")" ::: "memory")
; #define PG8_WAIT_L(n) asm volatile("s_waitcnt lgkmcnt(" #n ")" ::: "memory")
; #define PG8_BAR __builtin_amdgcn_s_barrier()
; #define PG8_SCHED __builtin_amdgcn_sched_barrier(0)
; template <class Epi, class Sched, bool ALIGN_EPI = false, bool SP2 = false>
; __device__ __forceinline__ void gemm_phase(PG8_LAS unsigned char* lds, const Gemm g, const Sched& S, const Epi& E, const int tid_in) {
;     ...
;             PG8_LDA(At, 1, 1); PG8_STAGE(PG8_SB(1, 0), b3, voffB); PG8_STAGE(PG8_SB(1, 1), b3 + hstep, voffB); PG8_STAGE(PG8_SA(1, 0), a3, voffA);
;             PG8_WAIT_V(8); PG8_WAIT_L(0); PG8_BAR; PG8_MMA(1, 0, At, B0); PG8_MMA(1, 1, At, B1); PG8_BAR; PG8_SCHED;
	s_add_i32 s42, s55, s19
	s_mov_b32 m0, s42
	ds_read_b128 v[180:183], v147 offset:49152
	ds_read_b128 v[184:187], v147 offset:50176
	ds_read_b128 v[188:191], v147 offset:51200
	ds_read_b128 v[192:195], v147 offset:52224
	ds_read_b128 v[196:199], v147 offset:53248
	ds_read_b128 v[200:203], v147 offset:54272
	ds_read_b128 v[208:211], v147 offset:55296
	ds_read_b128 v[212:215], v147 offset:56320
	global_load_lds_dwordx4 v132, s[98:99]
	s_add_i32 m0, s42, 0x2000
	s_add_u32 s38, s38, 0x80080
	s_addc_u32 s39, s39, 0
	s_add_i32 s42, s56, s19
	global_load_lds_dwordx4 v136, s[98:99]
	s_mov_b32 m0, s42
	s_nop 0
	global_load_lds_dwordx4 v132, s[38:39]
	s_add_i32 m0, s42, 0x2000
	s_nop 0
	global_load_lds_dwordx4 v136, s[38:39]
	s_mov_b32 m0, s48
	s_nop 0
	global_load_lds_dwordx4 v130, s[100:101]
	s_waitcnt vmcnt(7)
	s_waitcnt lgkmcnt(0)
	s_barrier
	s_setprio 1
	s_waitcnt lgkmcnt(0)
	v_mfma_f32_16x16x32_bf16 v[62:65], v[148:151], v[180:183], v[62:65]
	v_mfma_f32_16x16x32_bf16 v[58:61], v[156:159], v[180:183], v[58:61]
	v_mfma_f32_16x16x32_bf16 v[54:57], v[148:151], v[188:191], v[54:57]
	v_mfma_f32_16x16x32_bf16 v[46:49], v[156:159], v[188:191], v[46:49]
	v_mfma_f32_16x16x32_bf16 v[38:41], v[148:151], v[196:199], v[38:41]
	v_mfma_f32_16x16x32_bf16 v[30:33], v[156:159], v[196:199], v[30:33]
	v_mfma_f32_16x16x32_bf16 v[22:25], v[148:151], v[208:211], v[22:25]
	v_mfma_f32_16x16x32_bf16 v[12:15], v[156:159], v[208:211], v[12:15]
	v_mfma_f32_16x16x32_bf16 v[62:65], v[152:155], v[184:187], v[62:65]
	v_mfma_f32_16x16x32_bf16 v[58:61], v[160:163], v[184:187], v[58:61]
	v_mfma_f32_16x16x32_bf16 v[54:57], v[152:155], v[192:195], v[54:57]
	v_mfma_f32_16x16x32_bf16 v[46:49], v[160:163], v[192:195], v[46:49]
	v_mfma_f32_16x16x32_bf16 v[38:41], v[152:155], v[200:203], v[38:41]
	v_mfma_f32_16x16x32_bf16 v[30:33], v[160:163], v[200:203], v[30:33]
	v_mfma_f32_16x16x32_bf16 v[22:25], v[152:155], v[212:215], v[22:25]
	v_mfma_f32_16x16x32_bf16 v[12:15], v[160:163], v[212:215], v[12:15]
	s_setprio 0
	s_setprio 1
	v_mfma_f32_16x16x32_bf16 v[50:53], v[164:167], v[180:183], v[50:53]
	v_mfma_f32_16x16x32_bf16 v[42:45], v[172:175], v[180:183], v[42:45]
	v_mfma_f32_16x16x32_bf16 v[34:37], v[164:167], v[188:191], v[34:37]
	v_mfma_f32_16x16x32_bf16 v[26:29], v[172:175], v[188:191], v[26:29]
	v_mfma_f32_16x16x32_bf16 v[16:19], v[164:167], v[196:199], v[16:19]
	v_mfma_f32_16x16x32_bf16 v[8:11], v[172:175], v[196:199], v[8:11]
	v_mfma_f32_16x16x32_bf16 v[4:7], v[164:167], v[208:211], v[4:7]
	v_mfma_f32_16x16x32_bf16 v[0:3], v[172:175], v[208:211], v[0:3]
	v_mfma_f32_16x16x32_bf16 v[50:53], v[168:171], v[184:187], v[50:53]
	v_mfma_f32_16x16x32_bf16 v[42:45], v[176:179], v[184:187], v[42:45]
	v_mfma_f32_16x16x32_bf16 v[34:37], v[168:171], v[192:195], v[34:37]
	v_mfma_f32_16x16x32_bf16 v[26:29], v[176:179], v[192:195], v[26:29]
	v_mfma_f32_16x16x32_bf16 v[16:19], v[168:171], v[200:203], v[16:19]
	v_mfma_f32_16x16x32_bf16 v[8:11], v[176:179], v[200:203], v[8:11]
	v_mfma_f32_16x16x32_bf16 v[4:7], v[168:171], v[212:215], v[4:7]
	v_mfma_f32_16x16x32_bf16 v[0:3], v[176:179], v[212:215], v[0:3]
	s_setprio 0
	s_barrier
	s_add_i32 s54, s54, 2
	s_add_u32 s34, s34, 0x100
	s_addc_u32 s35, s35, 0
	s_add_u32 s52, s52, 0x100
	s_addc_u32 s53, s53, 0
	s_cmp_gt_u32 s54, 29
	s_cbranch_scc0 .LBB0_374
	s_and_b64 vcc, exec, s[6:7]
	v_readlane_b32 s52, v255, 9
	v_readlane_b32 s53, v255, 10
	s_cbranch_vccz .LBB0_377
	s_barrier

; #define PG8_STAGE(bufoff, gbase, voff) do { _Pragma("unroll") for (int _i = 0; _i < 2; ++_i) \
;         __builtin_amdgcn_global_load_lds((const unsigned*)((const char*)(gbase) + (voff)[_i]), (PG8_LAS unsigned*)(lds + (bufoff) + ldsw + _i * 8192), 16, 0, 0); } while (0)
; #define PG8_WAIT_V(n) asm volatile("s_waitcnt vmcnt(" #n ")" ::: "memory")
; template <class Epi, class Sched, bool ALIGN_EPI = false, bool SP2 = false>
; __device__ __forceinline__ void gemm_phase(PG8_LAS unsigned char* lds, const Gemm g, const Sched& S, const Epi& E, const int tid_in) {
;     ...
;     const int tid = tid_l, wid = __builtin_amdgcn_readfirstlane(tid >> 6), lane = tid & 63, wr = wid >> 2, wc = wid & 3, fr = lane & 15, fq = lane >> 4;
;     const int K = g.K, nt = K / BK;
;     unsigned voffA[2], voffB[2];
; #pragma unroll
;     for (int i = 0; i < 2; ++i) { int R, C; stage_rc(tid * 16 + i * 8192, R, C); const int Rb = perm_row<Epi::PMODE>(R);
;         voffA[i] = (unsigned)(R * K + C) * 2u; voffB[i] = (unsigned)(Rb * K + C) * 2u; }
;     const size_t kstep = (size_t)(BK * 2);
;     const size_t hstep = (size_t)HALF * K * 2;
;     const size_t tstep = 2 * hstep;
;     const unsigned ldsw = (unsigned)wid * 1024u;
;     const int aoff = lds_byte(wr * 64 + fr, fq * 8), boff = lds_byte(wc * 32 + fr, fq * 8);
;     ...
;     Unit cur, nxt; int ui = 0;
;     if (!S.next(0, cur)) return;
;     f32x4 acc[2][2][4][2];
; #pragma unroll
;     for (int a = 0; a < 2; ++a)
; #pragma unroll
;         for (int b = 0; b < 2; ++b)
; #pragma unroll
;             for (int m = 0; m < 4; ++m)
; #pragma unroll
;                 for (int n = 0; n < 2; ++n) acc[a][b][m][n] = (f32x4){0.f, 0.f, 0.f, 0.f};
;     bf16x8 At[4][2], B0[2][2], B1[2][2];
;     const char* cA = (const char*)g.A + (size_t)cur.pm * tstep; const char* cB = (const char*)g.Bt + (size_t)cur.pn * tstep;
;     S.a_ready(cur);
;     if constexpr (Epi::PREF) E.prefetch(cur, 0, lds, wid, lane);
;     if constexpr (SP2) {
;         PG8_STAGE(PG8_SB(0, 0), cB, voffB); PG8_STAGE(PG8_SB(0, 1), cB + hstep, voffB); PG8_STAGE(PG8_SA(0, 0), cA, voffA); PG8_STAGE(PG8_SA(0, 1), cA + hstep, voffA);
;         if (wr == 1) PG8_BAR;
;         PG8_WAIT_V(2); PG8_BAR;
;         PG8_STAGE(PG8_SB(1, 0), cB + kstep, voffB); PG8_STAGE(PG8_SA(1, 0), cA + kstep, voffA); PG8_STAGE(PG8_SB(1, 1), cB + hstep + kstep, voffB);
;         PG8_WAIT_V(6); PG8_BAR;
.LBB0_384:
	v_bfe_u32 v16, v13, 4, 2
	v_and_b32_e32 v15, 15, v13
	v_lshlrev_b32_e32 v18, 4, v16
	v_lshlrev_b32_e32 v13, 2, v13
	s_and_b32 s24, s22, 3
	v_lshl_or_b32 v17, s7, 6, v15
	v_lshl_or_b32 v15, v15, 6, v18
	s_lshl_b32 s7, s7, 13
	v_and_b32_e32 v13, 32, v13
	s_add_i32 m0, s38, 0x18000
	v_lshl_add_u64 v[6:7], v[6:7], 0, s[12:13]
	v_bitop3_b32 v18, v15, s7, v13 bitop3:0xde
	s_lshl_b32 s7, s24, 12
	s_waitcnt vmcnt(2)
	s_barrier
	global_load_lds_dwordx4 v[6:7], off
	v_lshl_add_u64 v[4:5], v[4:5], 0, s[12:13]
	s_add_i32 m0, s38, 0x1a000
	s_add_i32 s44, s38, 0x8000
	s_add_i32 s45, s38, 0xa000
	global_load_lds_dwordx4 v[4:5], off
	v_lshl_add_u64 v[0:1], v[0:1], 0, s[12:13]
	s_mov_b32 m0, s44
	s_add_u32 s100, s28, 0x80
	s_addc_u32 s101, s29, 0
	s_add_u32 s22, s30, 0x80080
	global_load_lds_dwordx4 v[0:1], off
	v_lshl_add_u64 v[0:1], v[2:3], 0, s[12:13]
	s_mov_b32 m0, s45
	s_addc_u32 s23, s31, 0
	global_load_lds_dwordx4 v[0:1], off
	s_add_i32 m0, s38, 0x1c000
	v_lshl_add_u64 v[0:1], s[22:23], 0, v[134:135]
	global_load_lds_dwordx4 v[0:1], off
	v_lshl_add_u64 v[0:1], s[22:23], 0, v[130:131]
	s_add_i32 m0, s38, 0x1e000
	s_cmpk_lt_u32 s6, 0x100
	global_load_lds_dwordx4 v[0:1], off
	v_lshlrev_b32_e32 v0, 9, v16
	v_lshl_or_b32 v0, s24, 11, v0
	v_mov_b32_e32 v1, v20
	v_lshl_add_u64 v[0:1], s[20:21], 0, v[0:1]
	s_mov_b64 s[20:21], 0x3b000000
	v_lshl_add_u64 v[138:139], v[0:1], 0, s[20:21]
	v_lshlrev_b32_e32 v0, 15, v12
	v_and_b32_e32 v0, 0xffff0000, v0
	v_lshl_add_u32 v0, v11, 12, v0
	v_and_b32_e32 v1, 1, v12
	v_lshl_or_b32 v0, v1, 6, v0
	v_lshl_add_u32 v140, v14, 1, v0
	v_lshlrev_b32_e32 v0, 15, v8
	v_and_b32_e32 v0, 0xffff0000, v0
	s_waitcnt vmcnt(6)
	v_lshl_add_u32 v0, v9, 12, v0
	v_and_b32_e32 v1, 1, v8
	v_lshl_or_b32 v0, v1, 6, v0
	v_readlane_b32 s20, v254, 31
	v_bitop3_b32 v21, v15, s7, v13 bitop3:0xde
	s_cselect_b64 s[6:7], -1, 0
	v_add_u32_e32 v146, 0x400, v17
	v_mov_b32_e32 v141, v20
	v_lshl_add_u32 v142, v10, 1, v0
	v_mov_b32_e32 v143, v20
	s_mov_b32 s46, 0
	v_add_u32_e32 v147, 0, v18
	v_readlane_b32 s47, v254, 28
	s_mov_b32 s48, s20
	s_barrier
	v_readlane_b32 s21, v254, 32
	s_branch .LBB0_387

; #define PG8_STAGE(bufoff, gbase, voff) do { _Pragma("unroll") for (int _i = 0; _i < 2; ++_i) \
;         __builtin_amdgcn_global_load_lds((const unsigned*)((const char*)(gbase) + (voff)[_i]), (PG8_LAS unsigned*)(lds + (bufoff) + ldsw + _i * 8192), 16, 0, 0); } while (0)
; #define PG8_LDA(dst, b, h) do { _Pragma("unroll") for (int m = 0; m < 4; ++m) _Pragma("unroll") for (int k = 0; k < 2; ++k) dst[m][k] = *(const PG8_LAS bf16x8*)(lds + PG8_SA(b, h) + aoff + m * 2048 + k * 1024); } while (0)
; #define PG8_LDB(dst, b, h) do { _Pragma("unroll") for (int n = 0; n < 2; ++n) _Pragma("unroll") for (int k = 0; k < 2; ++k) dst[n][k] = *(const PG8_LAS bf16x8*)(lds + PG8_SB(b, h) + boff + n * 2048 + k * 1024); } while (0)
; #define PG8_WAIT_V(n) asm volatile("s_waitcnt vmcnt(" #n ")" ::: "memory")
; #define PG8_WAIT_L(n) asm volatile("s_waitcnt lgkmcnt(" #n ")" ::: "memory")
; template <class Epi, class Sched, bool ALIGN_EPI = false, bool SP2 = false>
; __device__ __forceinline__ void gemm_phase(PG8_LAS unsigned char* lds, const Gemm g, const Sched& S, const Epi& E, const int tid_in) {
;     ...
;         const bool has_next = S.next(ui + 1, nxt);
;         const char* nA = has_next ? (const char*)g.A + (size_t)nxt.pm * tstep : cA; const char* nB = has_next ? (const char*)g.Bt + (size_t)nxt.pn * tstep : cB;
;         for (int t = 0; t < nt; t += 2) {
;             if constexpr (Epi::KSPLIT > 0) { if (t == Epi::KSPLIT / BK) E.midk(acc, cur, wr, wc, fr, fq); }
;             const bool last = (t == nt - 2);
;             const char* a1 = cA + (size_t)(t + 1) * kstep;
;             const char* a2 = last ? nA : cA + (size_t)(t + 2) * kstep; const char* b2 = last ? nB : cB + (size_t)(t + 2) * kstep;
;             const char* a3 = a2 + kstep; const char* b3 = b2 + kstep;
;             if (last && has_next) S.a_ready(nxt);
;             if constexpr (SP2) {
;             PG8_LDB(B0, 0, 0); PG8_LDB(B1, 0, 1); PG8_SCHED; PG8_LDA(At, 0, 0); PG8_STAGE(PG8_SA(1, 1), a1 + hstep, voffA);
;             PG8_WAIT_V(8); PG8_WAIT_L(0); PG8_BAR; PG8_MMA(0, 0, At, B0); PG8_MMA(0, 1, At, B1); PG8_BAR; PG8_SCHED;
;             PG8_LDA(At, 0, 1); PG8_STAGE(PG8_SB(0, 0), b2, voffB); PG8_STAGE(PG8_SB(0, 1), b2 + hstep, voffB); PG8_STAGE(PG8_SA(0, 0), a2, voffA);
;             PG8_WAIT_V(8); PG8_WAIT_L(0); PG8_BAR; PG8_MMA(1, 0, At, B0); PG8_MMA(1, 1, At, B1); PG8_BAR; PG8_SCHED;
.LBB0_394:
	s_mov_b32 m0, s45
	s_nop 0
	global_load_lds_dwordx4 v132, s[100:101]
	s_add_u32 s30, s28, 0xfff80080
	s_addc_u32 s31, s29, -1
	s_add_i32 s54, 0, 0x10000
	s_cmp_eq_u32 s53, 28
	s_cselect_b32 s35, s23, s31
	s_cselect_b32 s34, s49, s30
	v_add_u32_e32 v144, s54, v21
	s_cselect_b32 s31, s21, s52
	s_cselect_b32 s30, s50, s51
	s_add_i32 s56, 0, 0x14000
	ds_read_b128 v[148:151], v144
	ds_read_b128 v[152:155], v144 offset:1024
	ds_read_b128 v[156:159], v144 offset:2048
	ds_read_b128 v[160:163], v144 offset:3072
	v_add_u32_e32 v144, s56, v21
	ds_read_b128 v[164:167], v144
	ds_read_b128 v[168:171], v144 offset:1024
	ds_read_b128 v[172:175], v144 offset:2048
	ds_read_b128 v[176:179], v144 offset:3072
	s_add_i32 m0, s38, 0xc000
	ds_read_b128 v[180:183], v147
	ds_read_b128 v[184:187], v147 offset:1024
	ds_read_b128 v[188:191], v147 offset:2048
	ds_read_b128 v[192:195], v147 offset:3072
	ds_read_b128 v[196:199], v147 offset:4096
	ds_read_b128 v[200:203], v147 offset:5120
	ds_read_b128 v[208:211], v147 offset:6144
	ds_read_b128 v[212:215], v147 offset:7168
	global_load_lds_dwordx4 v140, s[28:29]
	s_add_i32 m0, s38, 0xe000
	s_nop 0
	global_load_lds_dwordx4 v142, s[28:29]
	s_waitcnt vmcnt(8)
	s_waitcnt lgkmcnt(0)
	s_barrier
	s_setprio 1
	s_waitcnt lgkmcnt(0)
	v_mfma_f32_16x16x32_bf16 v[126:129], v[148:151], v[180:183], v[126:129]
	v_mfma_f32_16x16x32_bf16 v[122:125], v[156:159], v[180:183], v[122:125]
	v_mfma_f32_16x16x32_bf16 v[118:121], v[148:151], v[188:191], v[118:121]
	v_mfma_f32_16x16x32_bf16 v[110:113], v[156:159], v[188:191], v[110:113]
	v_mfma_f32_16x16x32_bf16 v[102:105], v[148:151], v[196:199], v[102:105]
	v_mfma_f32_16x16x32_bf16 v[94:97], v[156:159], v[196:199], v[94:97]
	v_mfma_f32_16x16x32_bf16 v[86:89], v[148:151], v[208:211], v[86:89]
	v_mfma_f32_16x16x32_bf16 v[78:81], v[156:159], v[208:211], v[78:81]
	v_mfma_f32_16x16x32_bf16 v[126:129], v[152:155], v[184:187], v[126:129]
	v_mfma_f32_16x16x32_bf16 v[122:125], v[160:163], v[184:187], v[122:125]
	v_mfma_f32_16x16x32_bf16 v[118:121], v[152:155], v[192:195], v[118:121]
	v_mfma_f32_16x16x32_bf16 v[110:113], v[160:163], v[192:195], v[110:113]
	v_mfma_f32_16x16x32_bf16 v[102:105], v[152:155], v[200:203], v[102:105]
	v_mfma_f32_16x16x32_bf16 v[94:97], v[160:163], v[200:203], v[94:97]
	v_mfma_f32_16x16x32_bf16 v[86:89], v[152:155], v[212:215], v[86:89]
	v_mfma_f32_16x16x32_bf16 v[78:81], v[160:163], v[212:215], v[78:81]
	s_setprio 0
	s_setprio 1
	v_mfma_f32_16x16x32_bf16 v[114:117], v[164:167], v[180:183], v[114:117]
	v_mfma_f32_16x16x32_bf16 v[106:109], v[172:175], v[180:183], v[106:109]
	v_mfma_f32_16x16x32_bf16 v[98:101], v[164:167], v[188:191], v[98:101]
	v_mfma_f32_16x16x32_bf16 v[90:93], v[172:175], v[188:191], v[90:93]
	v_mfma_f32_16x16x32_bf16 v[82:85], v[164:167], v[196:199], v[82:85]
	v_mfma_f32_16x16x32_bf16 v[74:77], v[172:175], v[196:199], v[74:77]
	v_mfma_f32_16x16x32_bf16 v[70:73], v[164:167], v[208:211], v[70:73]
	v_mfma_f32_16x16x32_bf16 v[66:69], v[172:175], v[208:211], v[66:69]
	v_mfma_f32_16x16x32_bf16 v[114:117], v[168:171], v[184:187], v[114:117]
	v_mfma_f32_16x16x32_bf16 v[106:109], v[176:179], v[184:187], v[106:109]
	v_mfma_f32_16x16x32_bf16 v[98:101], v[168:171], v[192:195], v[98:101]
	v_mfma_f32_16x16x32_bf16 v[90:93], v[176:179], v[192:195], v[90:93]
	v_mfma_f32_16x16x32_bf16 v[82:85], v[168:171], v[200:203], v[82:85]
	v_mfma_f32_16x16x32_bf16 v[74:77], v[176:179], v[200:203], v[74:77]
	v_mfma_f32_16x16x32_bf16 v[70:73], v[168:171], v[212:215], v[70:73]
	v_mfma_f32_16x16x32_bf16 v[66:69], v[176:179], v[212:215], v[66:69]
	s_setprio 0
	s_barrier
	s_add_i32 s54, s54, s19
	s_add_u32 s98, s30, 0x80
	s_addc_u32 s99, s31, 0
	s_mov_b32 m0, s54
	ds_read_b128 v[180:183], v147 offset:16384
	ds_read_b128 v[184:187], v147 offset:17408
	ds_read_b128 v[188:191], v147 offset:18432
	ds_read_b128 v[192:195], v147 offset:19456
	ds_read_b128 v[196:199], v147 offset:20480
	ds_read_b128 v[200:203], v147 offset:21504
	ds_read_b128 v[208:211], v147 offset:22528
	ds_read_b128 v[212:215], v147 offset:23552
	global_load_lds_dwordx4 v134, s[30:31]
	s_add_i32 m0, s54, 0x2000
	s_add_u32 s54, s30, 0x80000
	s_addc_u32 s55, s31, 0
	s_add_i32 s56, s56, s19
	global_load_lds_dwordx4 v130, s[30:31]
	s_mov_b32 m0, s56
	s_add_u32 s100, s34, 0x80
	s_addc_u32 s101, s35, 0
	global_load_lds_dwordx4 v134, s[54:55]
	s_add_i32 m0, s56, 0x2000
	s_nop 0
	global_load_lds_dwordx4 v130, s[54:55]
	s_mov_b32 m0, s38
	s_nop 0
	global_load_lds_dwordx4 v136, s[34:35]
	s_waitcnt vmcnt(7)
	s_waitcnt lgkmcnt(0)
	s_barrier
; #define PG8_STAGE(bufoff, gbase, voff) do { _Pragma("unroll") for (int _i = 0; _i < 2; ++_i) \
;         __builtin_amdgcn_global_load_lds((const unsigned*)((const char*)(gbase) + (voff)[_i]), (PG8_LAS unsigned*)(lds + (bufoff) + ldsw + _i * 8192), 16, 0, 0); } while (0)
; #define PG8_LDA(dst, b, h) do { _Pragma("unroll") for (int m = 0; m < 4; ++m) _Pragma("unroll") for (int k = 0; k < 2; ++k) dst[m][k] = *(const PG8_LAS bf16x8*)(lds + PG8_SA(b, h) + aoff + m * 2048 + k * 1024); } while (0)
; #define PG8_LDB(dst, b, h) do { _Pragma("unroll") for (int n = 0; n < 2; ++n) _Pragma("unroll") for (int k = 0; k < 2; ++k) dst[n][k] = *(const PG8_LAS bf16x8*)(lds + PG8_SB(b, h) + boff + n * 2048 + k * 1024); } while (0)
; #define PG8_MMA(ai, bj, At, Bt) do { __builtin_amdgcn_s_setprio(1); _Pragma("unroll") for (int m = 0; m < 4; ++m) _Pragma("unroll") for (int n = 0; n < 2; ++n) _Pragma("unroll") for (int k = 0; k < 2; ++k) \
;         acc[ai][bj][m][n] = __builtin_amdgcn_mfma_f32_16x16x32_bf16(Bt[n][k], At[m][k], acc[ai][bj][m][n], 0, 0, 0); __builtin_amdgcn_s_setprio(0); } while (0)
; #define PG8_WAIT_V(n) asm volatile("s_waitcnt vmcnt(" #n ")" ::: "memory")
; #define PG8_WAIT_L(n) asm volatile("s_waitcnt lgkmcnt(" #n ")" ::: "memory")
; #define PG8_BAR __builtin_amdgcn_s_barrier()
; #define PG8_SCHED __builtin_amdgcn_sched_barrier(0)
; template <class Epi, class Sched, bool ALIGN_EPI = false, bool SP2 = false>
; __device__ __forceinline__ void gemm_phase(PG8_LAS unsigned char* lds, const Gemm g, const Sched& S, const Epi& E, const int tid_in) {
;     ...
;             PG8_WAIT_V(8); PG8_WAIT_L(0); PG8_BAR; PG8_MMA(1, 0, At, B0); PG8_MMA(1, 1, At, B1); PG8_BAR; PG8_SCHED;
;             PG8_LDB(B0, 1, 0); PG8_LDB(B1, 1, 1); PG8_SCHED; PG8_LDA(At, 1, 0); PG8_STAGE(PG8_SA(0, 1), a2 + hstep, voffA);
;             PG8_WAIT_V(8); PG8_WAIT_L(0); PG8_BAR; PG8_MMA(0, 0, At, B0); PG8_MMA(0, 1, At, B1); PG8_BAR; PG8_SCHED;
	s_setprio 1
	s_waitcnt lgkmcnt(0)
	v_mfma_f32_16x16x32_bf16 v[62:65], v[148:151], v[180:183], v[62:65]
	v_mfma_f32_16x16x32_bf16 v[58:61], v[156:159], v[180:183], v[58:61]
	v_mfma_f32_16x16x32_bf16 v[54:57], v[148:151], v[188:191], v[54:57]
	v_mfma_f32_16x16x32_bf16 v[46:49], v[156:159], v[188:191], v[46:49]
	v_mfma_f32_16x16x32_bf16 v[38:41], v[148:151], v[196:199], v[38:41]
	v_mfma_f32_16x16x32_bf16 v[30:33], v[156:159], v[196:199], v[30:33]
	v_mfma_f32_16x16x32_bf16 v[22:25], v[148:151], v[208:211], v[22:25]
	v_mfma_f32_16x16x32_bf16 v[12:15], v[156:159], v[208:211], v[12:15]
	v_mfma_f32_16x16x32_bf16 v[62:65], v[152:155], v[184:187], v[62:65]
	v_mfma_f32_16x16x32_bf16 v[58:61], v[160:163], v[184:187], v[58:61]
	v_mfma_f32_16x16x32_bf16 v[54:57], v[152:155], v[192:195], v[54:57]
	v_mfma_f32_16x16x32_bf16 v[46:49], v[160:163], v[192:195], v[46:49]
	v_mfma_f32_16x16x32_bf16 v[38:41], v[152:155], v[200:203], v[38:41]
	v_mfma_f32_16x16x32_bf16 v[30:33], v[160:163], v[200:203], v[30:33]
	v_mfma_f32_16x16x32_bf16 v[22:25], v[152:155], v[212:215], v[22:25]
	v_mfma_f32_16x16x32_bf16 v[12:15], v[160:163], v[212:215], v[12:15]
	s_setprio 0
	s_setprio 1
	v_mfma_f32_16x16x32_bf16 v[50:53], v[164:167], v[180:183], v[50:53]
	v_mfma_f32_16x16x32_bf16 v[42:45], v[172:175], v[180:183], v[42:45]
	v_mfma_f32_16x16x32_bf16 v[34:37], v[164:167], v[188:191], v[34:37]
	v_mfma_f32_16x16x32_bf16 v[26:29], v[172:175], v[188:191], v[26:29]
	v_mfma_f32_16x16x32_bf16 v[16:19], v[164:167], v[196:199], v[16:19]
	v_mfma_f32_16x16x32_bf16 v[8:11], v[172:175], v[196:199], v[8:11]
	v_mfma_f32_16x16x32_bf16 v[4:7], v[164:167], v[208:211], v[4:7]
	v_mfma_f32_16x16x32_bf16 v[0:3], v[172:175], v[208:211], v[0:3]
	v_mfma_f32_16x16x32_bf16 v[50:53], v[168:171], v[184:187], v[50:53]
	v_mfma_f32_16x16x32_bf16 v[42:45], v[176:179], v[184:187], v[42:45]
	v_mfma_f32_16x16x32_bf16 v[34:37], v[168:171], v[192:195], v[34:37]
	v_mfma_f32_16x16x32_bf16 v[26:29], v[176:179], v[192:195], v[26:29]
	v_mfma_f32_16x16x32_bf16 v[16:19], v[168:171], v[200:203], v[16:19]
	v_mfma_f32_16x16x32_bf16 v[8:11], v[176:179], v[200:203], v[8:11]
	v_mfma_f32_16x16x32_bf16 v[4:7], v[168:171], v[212:215], v[4:7]
	v_mfma_f32_16x16x32_bf16 v[0:3], v[176:179], v[212:215], v[0:3]
	s_setprio 0
	s_barrier
	s_add_i32 s54, 0, 0x18000
	s_add_i32 s55, 0, 0x1c000
	v_add_u32_e32 v160, s54, v21
	v_add_u32_e32 v176, s55, v21
	ds_read_b128 v[148:151], v160
	ds_read_b128 v[152:155], v160 offset:1024
	ds_read_b128 v[156:159], v160 offset:2048
	ds_read_b128 v[160:163], v160 offset:3072
	ds_read_b128 v[164:167], v176
	ds_read_b128 v[168:171], v176 offset:1024
	ds_read_b128 v[172:175], v176 offset:2048
	ds_read_b128 v[176:179], v176 offset:3072
	s_mov_b32 m0, s39
	s_nop 0
	global_load_lds_dwordx4 v132, s[34:35]
	s_add_u32 s34, s34, 0x80000
	s_addc_u32 s35, s35, 0
	s_mov_b32 m0, s42
	ds_read_b128 v[180:183], v147 offset:32768
	ds_read_b128 v[184:187], v147 offset:33792
	ds_read_b128 v[188:191], v147 offset:34816
	ds_read_b128 v[192:195], v147 offset:35840
	ds_read_b128 v[196:199], v147 offset:36864
	ds_read_b128 v[200:203], v147 offset:37888
	ds_read_b128 v[208:211], v147 offset:38912
	ds_read_b128 v[212:215], v147 offset:39936
	global_load_lds_dwordx4 v136, s[34:35]
	s_mov_b32 m0, s43
	s_nop 0
	global_load_lds_dwordx4 v132, s[34:35]
	s_waitcnt vmcnt(8)
	s_waitcnt lgkmcnt(0)
	s_barrier
	s_setprio 1
	s_waitcnt lgkmcnt(0)
	v_mfma_f32_16x16x32_bf16 v[126:129], v[148:151], v[180:183], v[126:129]
	v_mfma_f32_16x16x32_bf16 v[122:125], v[156:159], v[180:183], v[122:125]
	v_mfma_f32_16x16x32_bf16 v[118:121], v[148:151], v[188:191], v[118:121]
	v_mfma_f32_16x16x32_bf16 v[110:113], v[156:159], v[188:191], v[110:113]
	v_mfma_f32_16x16x32_bf16 v[102:105], v[148:151], v[196:199], v[102:105]
	v_mfma_f32_16x16x32_bf16 v[94:97], v[156:159], v[196:199], v[94:97]
	v_mfma_f32_16x16x32_bf16 v[86:89], v[148:151], v[208:211], v[86:89]
	v_mfma_f32_16x16x32_bf16 v[78:81], v[156:159], v[208:211], v[78:81]
	v_mfma_f32_16x16x32_bf16 v[126:129], v[152:155], v[184:187], v[126:129]
	v_mfma_f32_16x16x32_bf16 v[122:125], v[160:163], v[184:187], v[122:125]
	v_mfma_f32_16x16x32_bf16 v[118:121], v[152:155], v[192:195], v[118:121]
	v_mfma_f32_16x16x32_bf16 v[110:113], v[160:163], v[192:195], v[110:113]
	v_mfma_f32_16x16x32_bf16 v[102:105], v[152:155], v[200:203], v[102:105]
	v_mfma_f32_16x16x32_bf16 v[94:97], v[160:163], v[200:203], v[94:97]
	v_mfma_f32_16x16x32_bf16 v[86:89], v[152:155], v[212:215], v[86:89]
	v_mfma_f32_16x16x32_bf16 v[78:81], v[160:163], v[212:215], v[78:81]
	s_setprio 0
	s_setprio 1
	v_mfma_f32_16x16x32_bf16 v[114:117], v[164:167], v[180:183], v[114:117]
	v_mfma_f32_16x16x32_bf16 v[106:109], v[172:175], v[180:183], v[106:109]
	v_mfma_f32_16x16x32_bf16 v[98:101], v[164:167], v[188:191], v[98:101]
	v_mfma_f32_16x16x32_bf16 v[90:93], v[172:175], v[188:191], v[90:93]
	v_mfma_f32_16x16x32_bf16 v[82:85], v[164:167], v[196:199], v[82:85]
	v_mfma_f32_16x16x32_bf16 v[74:77], v[172:175], v[196:199], v[74:77]
	v_mfma_f32_16x16x32_bf16 v[70:73], v[164:167], v[208:211], v[70:73]
	v_mfma_f32_16x16x32_bf16 v[66:69], v[172:175], v[208:211], v[66:69]
	v_mfma_f32_16x16x32_bf16 v[114:117], v[168:171], v[184:187], v[114:117]
	v_mfma_f32_16x16x32_bf16 v[106:109], v[176:179], v[184:187], v[106:109]
	v_mfma_f32_16x16x32_bf16 v[98:101], v[168:171], v[192:195], v[98:101]
	v_mfma_f32_16x16x32_bf16 v[90:93], v[176:179], v[192:195], v[90:93]
	v_mfma_f32_16x16x32_bf16 v[82:85], v[168:171], v[200:203], v[82:85]
	v_mfma_f32_16x16x32_bf16 v[74:77], v[176:179], v[200:203], v[74:77]
	v_mfma_f32_16x16x32_bf16 v[70:73], v[168:171], v[212:215], v[70:73]
	v_mfma_f32_16x16x32_bf16 v[66:69], v[176:179], v[212:215], v[66:69]
	s_setprio 0
	s_barrier
; #define PG8_STAGE(bufoff, gbase, voff) do { _Pragma("unroll") for (int _i = 0; _i < 2; ++_i) \
;         __builtin_amdgcn_global_load_lds((const unsigned*)((const char*)(gbase) + (voff)[_i]), (PG8_LAS unsigned*)(lds + (bufoff) + ldsw + _i * 8192), 16, 0, 0); } while (0)
; #define PG8_LDA(dst, b, h) do { _Pragma("unroll") for (int m = 0; m < 4; ++m) _Pragma("unroll") for (int k = 0; k < 2; ++k) dst[m][k] = *(const PG8_LAS bf16x8*)(lds + PG8_SA(b, h) + aoff + m * 2048 + k * 1024); } while (0)
; #define PG8_MMA(ai, bj, At, Bt) do { __builtin_amdgcn_s_setprio(1); _Pragma("unroll") for (int m = 0; m < 4; ++m) _Pragma("unroll") for (int n = 0; n < 2; ++n) _Pragma("unroll") for (int k = 0; k < 2; ++k) \
;         acc[ai][bj][m][n] = __builtin_amdgcn_mfma_f32_16x16x32_bf16(Bt[n][k], At[m][k], acc[ai][bj][m][n], 0, 0, 0); __builtin_amdgcn_s_setprio(0); } while (0)
; #define PG8_WAIT_V(n) asm volatile("s_waitcnt vmcnt(" #n ")" ::: "memory")
; #define PG8_WAIT_L(n) asm volatile("s_waitcnt lgkmcnt(" #n ")" ::: "memory")
; #define PG8_BAR __builtin_amdgcn_s_barrier()
; #define PG8_SCHED __builtin_amdgcn_sched_barrier(0)
; template <class Epi, class Sched, bool ALIGN_EPI = false, bool SP2 = false>
; __device__ __forceinline__ void gemm_phase(PG8_LAS unsigned char* lds, const Gemm g, const Sched& S, const Epi& E, const int tid_in) {
;     ...
;             PG8_LDA(At, 1, 1); PG8_STAGE(PG8_SB(1, 0), b3, voffB); PG8_STAGE(PG8_SB(1, 1), b3 + hstep, voffB); PG8_STAGE(PG8_SA(1, 0), a3, voffA);
;             PG8_WAIT_V(8); PG8_WAIT_L(0); PG8_BAR; PG8_MMA(1, 0, At, B0); PG8_MMA(1, 1, At, B1); PG8_BAR; PG8_SCHED;
	s_add_i32 s34, s54, s19
	s_mov_b32 m0, s34
	ds_read_b128 v[180:183], v147 offset:49152
	ds_read_b128 v[184:187], v147 offset:50176
	ds_read_b128 v[188:191], v147 offset:51200
	ds_read_b128 v[192:195], v147 offset:52224
	ds_read_b128 v[196:199], v147 offset:53248
	ds_read_b128 v[200:203], v147 offset:54272
	ds_read_b128 v[208:211], v147 offset:55296
	ds_read_b128 v[212:215], v147 offset:56320
	global_load_lds_dwordx4 v134, s[98:99]
	s_add_i32 m0, s34, 0x2000
	s_add_u32 s30, s30, 0x80080
	s_addc_u32 s31, s31, 0
	s_add_i32 s34, s55, s19
	global_load_lds_dwordx4 v130, s[98:99]
	s_mov_b32 m0, s34
	s_nop 0
	global_load_lds_dwordx4 v134, s[30:31]
	s_add_i32 m0, s34, 0x2000
	s_nop 0
	global_load_lds_dwordx4 v130, s[30:31]
	s_mov_b32 m0, s44
	s_nop 0
	global_load_lds_dwordx4 v136, s[100:101]
	s_waitcnt vmcnt(7)
	s_waitcnt lgkmcnt(0)
	s_barrier
	s_setprio 1
	s_waitcnt lgkmcnt(0)
	v_mfma_f32_16x16x32_bf16 v[62:65], v[148:151], v[180:183], v[62:65]
	v_mfma_f32_16x16x32_bf16 v[58:61], v[156:159], v[180:183], v[58:61]
	v_mfma_f32_16x16x32_bf16 v[54:57], v[148:151], v[188:191], v[54:57]
	v_mfma_f32_16x16x32_bf16 v[46:49], v[156:159], v[188:191], v[46:49]
	v_mfma_f32_16x16x32_bf16 v[38:41], v[148:151], v[196:199], v[38:41]
	v_mfma_f32_16x16x32_bf16 v[30:33], v[156:159], v[196:199], v[30:33]
	v_mfma_f32_16x16x32_bf16 v[22:25], v[148:151], v[208:211], v[22:25]
	v_mfma_f32_16x16x32_bf16 v[12:15], v[156:159], v[208:211], v[12:15]
	v_mfma_f32_16x16x32_bf16 v[62:65], v[152:155], v[184:187], v[62:65]
	v_mfma_f32_16x16x32_bf16 v[58:61], v[160:163], v[184:187], v[58:61]
	v_mfma_f32_16x16x32_bf16 v[54:57], v[152:155], v[192:195], v[54:57]
	v_mfma_f32_16x16x32_bf16 v[46:49], v[160:163], v[192:195], v[46:49]
	v_mfma_f32_16x16x32_bf16 v[38:41], v[152:155], v[200:203], v[38:41]
	v_mfma_f32_16x16x32_bf16 v[30:33], v[160:163], v[200:203], v[30:33]
	v_mfma_f32_16x16x32_bf16 v[22:25], v[152:155], v[212:215], v[22:25]
	v_mfma_f32_16x16x32_bf16 v[12:15], v[160:163], v[212:215], v[12:15]
	s_setprio 0
	s_setprio 1
	v_mfma_f32_16x16x32_bf16 v[50:53], v[164:167], v[180:183], v[50:53]
	v_mfma_f32_16x16x32_bf16 v[42:45], v[172:175], v[180:183], v[42:45]
	v_mfma_f32_16x16x32_bf16 v[34:37], v[164:167], v[188:191], v[34:37]
	v_mfma_f32_16x16x32_bf16 v[26:29], v[172:175], v[188:191], v[26:29]
	v_mfma_f32_16x16x32_bf16 v[16:19], v[164:167], v[196:199], v[16:19]
	v_mfma_f32_16x16x32_bf16 v[8:11], v[172:175], v[196:199], v[8:11]
	v_mfma_f32_16x16x32_bf16 v[4:7], v[164:167], v[208:211], v[4:7]
	v_mfma_f32_16x16x32_bf16 v[0:3], v[172:175], v[208:211], v[0:3]
	v_mfma_f32_16x16x32_bf16 v[50:53], v[168:171], v[184:187], v[50:53]
	v_mfma_f32_16x16x32_bf16 v[42:45], v[176:179], v[184:187], v[42:45]
	v_mfma_f32_16x16x32_bf16 v[34:37], v[168:171], v[192:195], v[34:37]
	v_mfma_f32_16x16x32_bf16 v[26:29], v[176:179], v[192:195], v[26:29]
	v_mfma_f32_16x16x32_bf16 v[16:19], v[168:171], v[200:203], v[16:19]
	v_mfma_f32_16x16x32_bf16 v[8:11], v[176:179], v[200:203], v[8:11]
	v_mfma_f32_16x16x32_bf16 v[4:7], v[168:171], v[212:215], v[4:7]
	v_mfma_f32_16x16x32_bf16 v[0:3], v[176:179], v[212:215], v[0:3]
	s_setprio 0
	s_barrier
	s_add_i32 s53, s53, 2
	s_add_u32 s28, s28, 0x100
	s_addc_u32 s29, s29, 0
	s_add_u32 s51, s51, 0x100
	s_addc_u32 s52, s52, 0
	s_cmp_gt_u32 s53, 29
	s_cbranch_scc0 .LBB0_394
	s_and_b64 vcc, exec, s[6:7]
	v_readlane_b32 s52, v255, 9
	v_readlane_b32 s53, v255, 10
	s_cbranch_vccz .LBB0_397
	s_barrier

; #define PG8_STAGE(bufoff, gbase, voff) do { _Pragma("unroll") for (int _i = 0; _i < 2; ++_i) \
;         __builtin_amdgcn_global_load_lds((const unsigned*)((const char*)(gbase) + (voff)[_i]), (PG8_LAS unsigned*)(lds + (bufoff) + ldsw + _i * 8192), 16, 0, 0); } while (0)
; #define PG8_WAIT_V(n) asm volatile("s_waitcnt vmcnt(" #n ")" ::: "memory")
; template <class Epi, class Sched, bool ALIGN_EPI = false, bool SP2 = false>
; __device__ __forceinline__ void gemm_phase(PG8_LAS unsigned char* lds, const Gemm g, const Sched& S, const Epi& E, const int tid_in) {
;     ...
;     const int tid = tid_l, wid = __builtin_amdgcn_readfirstlane(tid >> 6), lane = tid & 63, wr = wid >> 2, wc = wid & 3, fr = lane & 15, fq = lane >> 4;
;     const int K = g.K, nt = K / BK;
;     unsigned voffA[2], voffB[2];
; #pragma unroll
;     for (int i = 0; i < 2; ++i) { int R, C; stage_rc(tid * 16 + i * 8192, R, C); const int Rb = perm_row<Epi::PMODE>(R);
;         voffA[i] = (unsigned)(R * K + C) * 2u; voffB[i] = (unsigned)(Rb * K + C) * 2u; }
;     const size_t kstep = (size_t)(BK * 2);
;     const size_t hstep = (size_t)HALF * K * 2;
;     const size_t tstep = 2 * hstep;
;     const unsigned ldsw = (unsigned)wid * 1024u;
;     const int aoff = lds_byte(wr * 64 + fr, fq * 8), boff = lds_byte(wc * 32 + fr, fq * 8);
;     ...
;     Unit cur, nxt; int ui = 0;
;     if (!S.next(0, cur)) return;
;     f32x4 acc[2][2][4][2];
; #pragma unroll
;     for (int a = 0; a < 2; ++a)
; #pragma unroll
;         for (int b = 0; b < 2; ++b)
; #pragma unroll
;             for (int m = 0; m < 4; ++m)
; #pragma unroll
;                 for (int n = 0; n < 2; ++n) acc[a][b][m][n] = (f32x4){0.f, 0.f, 0.f, 0.f};
;     bf16x8 At[4][2], B0[2][2], B1[2][2];
;     const char* cA = (const char*)g.A + (size_t)cur.pm * tstep; const char* cB = (const char*)g.Bt + (size_t)cur.pn * tstep;
;     S.a_ready(cur);
;     if constexpr (Epi::PREF) E.prefetch(cur, 0, lds, wid, lane);
;     if constexpr (SP2) {
;         PG8_STAGE(PG8_SB(0, 0), cB, voffB); PG8_STAGE(PG8_SB(0, 1), cB + hstep, voffB); PG8_STAGE(PG8_SA(0, 0), cA, voffA); PG8_STAGE(PG8_SA(0, 1), cA + hstep, voffA);
;         if (wr == 1) PG8_BAR;
;         PG8_WAIT_V(2); PG8_BAR;
;         PG8_STAGE(PG8_SB(1, 0), cB + kstep, voffB); PG8_STAGE(PG8_SA(1, 0), cA + kstep, voffA); PG8_STAGE(PG8_SB(1, 1), cB + hstep + kstep, voffB);
;         PG8_WAIT_V(6); PG8_BAR;
.LBB0_406:
	v_lshrrev_b32_e32 v3, 1, v13
	v_and_b32_e32 v19, 24, v3
	v_and_b32_e32 v1, 15, v13
	v_lshlrev_b32_e32 v3, 1, v19
	s_add_u32 s24, s2, 0x3e000000
	v_lshl_or_b32 v21, s28, 6, v1
	v_lshl_or_b32 v1, v1, 6, v3
	v_lshlrev_b32_e32 v3, 2, v13
	s_addc_u32 s25, s3, 0
	s_lshl_b32 s2, s28, 13
	v_and_b32_e32 v3, 32, v3
	v_bitop3_b32 v13, v1, s2, v3 bitop3:0xde
	s_lshl_b32 s2, s27, 5
	s_and_b32 s27, s2, 0x60
	s_add_i32 m0, s44, 0x18000
	v_lshl_add_u64 v[10:11], v[10:11], 0, s[12:13]
	s_lshl_b32 s2, s27, 7
	s_waitcnt vmcnt(2)
	s_barrier
	global_load_lds_dwordx4 v[10:11], off
	v_lshl_add_u64 v[8:9], v[8:9], 0, s[12:13]
	s_add_i32 m0, s44, 0x1a000
	s_add_i32 s48, s44, 0x8000
	s_add_i32 s49, s44, 0xa000
	v_bitop3_b32 v162, v1, s2, v3 bitop3:0xde
	global_load_lds_dwordx4 v[8:9], off
	v_lshl_add_u64 v[4:5], v[4:5], 0, s[12:13]
	s_mov_b32 m0, s48
	s_add_u32 s100, s34, 0x80
	s_addc_u32 s101, s35, 0
	s_add_u32 s2, s38, 0x80080
	global_load_lds_dwordx4 v[4:5], off
	v_lshl_add_u64 v[4:5], v[6:7], 0, s[12:13]
	s_mov_b32 m0, s49
	s_addc_u32 s3, s39, 0
	global_load_lds_dwordx4 v[4:5], off
	s_add_i32 m0, s44, 0x1c000
	v_lshl_add_u64 v[4:5], s[2:3], 0, v[148:149]
	global_load_lds_dwordx4 v[4:5], off
	v_lshl_add_u64 v[4:5], s[2:3], 0, v[152:153]
	s_add_i32 m0, s44, 0x1e000
	v_mov_b32_e32 v3, v20
	global_load_lds_dwordx4 v[4:5], off
	v_lshl_add_u64 v[2:3], s[6:7], 0, v[2:3]
	v_mov_b32_e32 v1, v20
	v_lshl_add_u64 v[154:155], v[2:3], 0, v[0:1]
	v_lshlrev_b32_e32 v0, 15, v12
	v_and_b32_e32 v0, 0xffff0000, v0
	v_lshl_add_u32 v0, v14, 12, v0
	v_and_b32_e32 v1, 1, v12
	v_lshl_or_b32 v0, v1, 6, v0
	s_lshl_b32 s2, s27, 2
	v_lshl_add_u32 v156, v15, 1, v0
	v_lshlrev_b32_e32 v0, 15, v16
	s_add_i32 s2, s2, 0
	v_and_b32_e32 v0, 0xffff0000, v0
	s_waitcnt vmcnt(6)
	s_add_i32 s2, s2, 0x22400
	v_lshl_add_u32 v0, v17, 12, v0
	v_and_b32_e32 v1, 1, v16
	s_cmpk_lt_u32 s26, 0x100
	v_lshl_or_b32 v0, v1, 6, v0
	v_readlane_b32 s6, v253, 59
	v_lshl_add_u32 v163, v19, 2, s2
	s_cselect_b64 s[2:3], -1, 0
	v_or_b32_e32 v164, s27, v19
	v_mov_b32_e32 v157, v20
	v_lshl_add_u32 v158, v18, 1, v0
	v_mov_b32_e32 v159, v20
	s_mov_b32 s53, 0
	v_add_u32_e32 v165, 0, v13
	v_readlane_b32 s51, v254, 3
	s_mov_b32 s52, s6
	s_barrier
	v_readlane_b32 s7, v253, 60
	s_branch .LBB0_409

; #define PG8_STAGE(bufoff, gbase, voff) do { _Pragma("unroll") for (int _i = 0; _i < 2; ++_i) \
;         __builtin_amdgcn_global_load_lds((const unsigned*)((const char*)(gbase) + (voff)[_i]), (PG8_LAS unsigned*)(lds + (bufoff) + ldsw + _i * 8192), 16, 0, 0); } while (0)
; #define PG8_LDA(dst, b, h) do { _Pragma("unroll") for (int m = 0; m < 4; ++m) _Pragma("unroll") for (int k = 0; k < 2; ++k) dst[m][k] = *(const PG8_LAS bf16x8*)(lds + PG8_SA(b, h) + aoff + m * 2048 + k * 1024); } while (0)
; #define PG8_LDB(dst, b, h) do { _Pragma("unroll") for (int n = 0; n < 2; ++n) _Pragma("unroll") for (int k = 0; k < 2; ++k) dst[n][k] = *(const PG8_LAS bf16x8*)(lds + PG8_SB(b, h) + boff + n * 2048 + k * 1024); } while (0)
; #define PG8_WAIT_V(n) asm volatile("s_waitcnt vmcnt(" #n ")" ::: "memory")
; #define PG8_WAIT_L(n) asm volatile("s_waitcnt lgkmcnt(" #n ")" ::: "memory")
; template <class Epi, class Sched, bool ALIGN_EPI = false, bool SP2 = false>
; __device__ __forceinline__ void gemm_phase(PG8_LAS unsigned char* lds, const Gemm g, const Sched& S, const Epi& E, const int tid_in) {
;     ...
;         const bool has_next = S.next(ui + 1, nxt);
;         const char* nA = has_next ? (const char*)g.A + (size_t)nxt.pm * tstep : cA; const char* nB = has_next ? (const char*)g.Bt + (size_t)nxt.pn * tstep : cB;
;         for (int t = 0; t < nt; t += 2) {
;             if constexpr (Epi::KSPLIT > 0) { if (t == Epi::KSPLIT / BK) E.midk(acc, cur, wr, wc, fr, fq); }
;             const bool last = (t == nt - 2);
;             const char* a1 = cA + (size_t)(t + 1) * kstep;
;             const char* a2 = last ? nA : cA + (size_t)(t + 2) * kstep; const char* b2 = last ? nB : cB + (size_t)(t + 2) * kstep;
;             const char* a3 = a2 + kstep; const char* b3 = b2 + kstep;
;             if (last && has_next) S.a_ready(nxt);
;             if constexpr (SP2) {
;             PG8_LDB(B0, 0, 0); PG8_LDB(B1, 0, 1); PG8_SCHED; PG8_LDA(At, 0, 0); PG8_STAGE(PG8_SA(1, 1), a1 + hstep, voffA);
;             PG8_WAIT_V(8); PG8_WAIT_L(0); PG8_BAR; PG8_MMA(0, 0, At, B0); PG8_MMA(0, 1, At, B1); PG8_BAR; PG8_SCHED;
;             PG8_LDA(At, 0, 1); PG8_STAGE(PG8_SB(0, 0), b2, voffB); PG8_STAGE(PG8_SB(0, 1), b2 + hstep, voffB); PG8_STAGE(PG8_SA(0, 0), a2, voffA);
;             PG8_WAIT_V(8); PG8_WAIT_L(0); PG8_BAR; PG8_MMA(1, 0, At, B0); PG8_MMA(1, 1, At, B1); PG8_BAR; PG8_SCHED;
.LBB0_412:
	s_mov_b32 m0, s49
	s_nop 0
	global_load_lds_dwordx4 v150, s[100:101]
	s_add_u32 s38, s34, 0xfff80080
	s_addc_u32 s39, s35, -1
	s_add_i32 s59, 0, 0x10000
	s_cmp_eq_u32 s58, 28
	s_cselect_b32 s43, s27, s39
	s_cselect_b32 s42, s54, s38
	s_cselect_b32 s39, s7, s57
	s_cselect_b32 s38, s55, s56
	s_add_i32 s62, 0, 0x14000
	v_add_u32_e32 v78, s59, v162
	v_add_u32_e32 v160, s62, v162
	ds_read_b128 v[66:69], v78
	ds_read_b128 v[70:73], v78 offset:1024
	ds_read_b128 v[74:77], v78 offset:2048
	ds_read_b128 v[78:81], v78 offset:3072
	ds_read_b128 v[166:169], v160
	ds_read_b128 v[170:173], v160 offset:1024
	ds_read_b128 v[174:177], v160 offset:2048
	ds_read_b128 v[178:181], v160 offset:3072
	s_add_i32 m0, s44, 0xc000
	ds_read_b128 v[182:185], v165
	ds_read_b128 v[186:189], v165 offset:1024
	ds_read_b128 v[190:193], v165 offset:2048
	ds_read_b128 v[194:197], v165 offset:3072
	ds_read_b128 v[198:201], v165 offset:4096
	ds_read_b128 v[202:205], v165 offset:5120
	ds_read_b128 v[208:211], v165 offset:6144
	ds_read_b128 v[212:215], v165 offset:7168
	global_load_lds_dwordx4 v156, s[34:35]
	s_add_i32 m0, s44, 0xe000
	s_nop 0
	global_load_lds_dwordx4 v158, s[34:35]
	s_waitcnt vmcnt(8)
	s_waitcnt lgkmcnt(0)
	s_barrier
	s_setprio 1
	s_waitcnt lgkmcnt(0)
	v_mfma_f32_16x16x32_bf16 v[142:145], v[66:69], v[182:185], v[142:145]
	v_mfma_f32_16x16x32_bf16 v[138:141], v[74:77], v[182:185], v[138:141]
	v_mfma_f32_16x16x32_bf16 v[126:129], v[66:69], v[190:193], v[126:129]
	v_mfma_f32_16x16x32_bf16 v[122:125], v[74:77], v[190:193], v[122:125]
	v_mfma_f32_16x16x32_bf16 v[110:113], v[66:69], v[198:201], v[110:113]
	v_mfma_f32_16x16x32_bf16 v[106:109], v[74:77], v[198:201], v[106:109]
	v_mfma_f32_16x16x32_bf16 v[94:97], v[66:69], v[208:211], v[94:97]
	v_mfma_f32_16x16x32_bf16 v[90:93], v[74:77], v[208:211], v[90:93]
	v_mfma_f32_16x16x32_bf16 v[142:145], v[70:73], v[186:189], v[142:145]
	v_mfma_f32_16x16x32_bf16 v[138:141], v[78:81], v[186:189], v[138:141]
	v_mfma_f32_16x16x32_bf16 v[126:129], v[70:73], v[194:197], v[126:129]
	v_mfma_f32_16x16x32_bf16 v[122:125], v[78:81], v[194:197], v[122:125]
	v_mfma_f32_16x16x32_bf16 v[110:113], v[70:73], v[202:205], v[110:113]
	v_mfma_f32_16x16x32_bf16 v[106:109], v[78:81], v[202:205], v[106:109]
	v_mfma_f32_16x16x32_bf16 v[94:97], v[70:73], v[212:215], v[94:97]
	v_mfma_f32_16x16x32_bf16 v[90:93], v[78:81], v[212:215], v[90:93]
	s_setprio 0
	s_setprio 1
	v_mfma_f32_16x16x32_bf16 v[134:137], v[166:169], v[182:185], v[134:137]
	v_mfma_f32_16x16x32_bf16 v[130:133], v[174:177], v[182:185], v[130:133]
	v_mfma_f32_16x16x32_bf16 v[118:121], v[166:169], v[190:193], v[118:121]
	v_mfma_f32_16x16x32_bf16 v[114:117], v[174:177], v[190:193], v[114:117]
	v_mfma_f32_16x16x32_bf16 v[102:105], v[166:169], v[198:201], v[102:105]
	v_mfma_f32_16x16x32_bf16 v[98:101], v[174:177], v[198:201], v[98:101]
	v_mfma_f32_16x16x32_bf16 v[86:89], v[166:169], v[208:211], v[86:89]
	v_mfma_f32_16x16x32_bf16 v[82:85], v[174:177], v[208:211], v[82:85]
	v_mfma_f32_16x16x32_bf16 v[134:137], v[170:173], v[186:189], v[134:137]
	v_mfma_f32_16x16x32_bf16 v[130:133], v[178:181], v[186:189], v[130:133]
	v_mfma_f32_16x16x32_bf16 v[118:121], v[170:173], v[194:197], v[118:121]
	v_mfma_f32_16x16x32_bf16 v[114:117], v[178:181], v[194:197], v[114:117]
	v_mfma_f32_16x16x32_bf16 v[102:105], v[170:173], v[202:205], v[102:105]
	v_mfma_f32_16x16x32_bf16 v[98:101], v[178:181], v[202:205], v[98:101]
	v_mfma_f32_16x16x32_bf16 v[86:89], v[170:173], v[212:215], v[86:89]
	v_mfma_f32_16x16x32_bf16 v[82:85], v[178:181], v[212:215], v[82:85]
	s_setprio 0
	s_barrier
	s_add_i32 s59, s59, s19
	s_add_u32 s98, s38, 0x80
	s_addc_u32 s99, s39, 0
	s_mov_b32 m0, s59
	ds_read_b128 v[182:185], v165 offset:16384
	ds_read_b128 v[186:189], v165 offset:17408
	ds_read_b128 v[190:193], v165 offset:18432
	ds_read_b128 v[194:197], v165 offset:19456
	ds_read_b128 v[198:201], v165 offset:20480
	ds_read_b128 v[202:205], v165 offset:21504
	ds_read_b128 v[208:211], v165 offset:22528
	ds_read_b128 v[212:215], v165 offset:23552
	global_load_lds_dwordx4 v148, s[38:39]
	s_add_i32 m0, s59, 0x2000
	s_add_u32 s60, s38, 0x80000
	s_addc_u32 s61, s39, 0
	s_add_i32 s59, s62, s19
	global_load_lds_dwordx4 v152, s[38:39]
	s_mov_b32 m0, s59
	s_add_u32 s100, s42, 0x80
	s_addc_u32 s101, s43, 0
	global_load_lds_dwordx4 v148, s[60:61]
	s_add_i32 m0, s59, 0x2000
	s_nop 0
	global_load_lds_dwordx4 v152, s[60:61]
	s_mov_b32 m0, s44
	s_nop 0
	global_load_lds_dwordx4 v146, s[42:43]
	s_waitcnt vmcnt(7)
	s_waitcnt lgkmcnt(0)
	s_barrier
	s_setprio 1
	s_waitcnt lgkmcnt(0)
	v_mfma_f32_16x16x32_bf16 v[62:65], v[66:69], v[182:185], v[62:65]
	v_mfma_f32_16x16x32_bf16 v[58:61], v[74:77], v[182:185], v[58:61]
	v_mfma_f32_16x16x32_bf16 v[46:49], v[66:69], v[190:193], v[46:49]
	v_mfma_f32_16x16x32_bf16 v[42:45], v[74:77], v[190:193], v[42:45]
	v_mfma_f32_16x16x32_bf16 v[30:33], v[66:69], v[198:201], v[30:33]
	v_mfma_f32_16x16x32_bf16 v[26:29], v[74:77], v[198:201], v[26:29]
	v_mfma_f32_16x16x32_bf16 v[12:15], v[66:69], v[208:211], v[12:15]
	v_mfma_f32_16x16x32_bf16 v[8:11], v[74:77], v[208:211], v[8:11]
	v_mfma_f32_16x16x32_bf16 v[62:65], v[70:73], v[186:189], v[62:65]
	v_mfma_f32_16x16x32_bf16 v[58:61], v[78:81], v[186:189], v[58:61]
	v_mfma_f32_16x16x32_bf16 v[46:49], v[70:73], v[194:197], v[46:49]
	v_mfma_f32_16x16x32_bf16 v[42:45], v[78:81], v[194:197], v[42:45]
	v_mfma_f32_16x16x32_bf16 v[30:33], v[70:73], v[202:205], v[30:33]
	v_mfma_f32_16x16x32_bf16 v[26:29], v[78:81], v[202:205], v[26:29]
	v_mfma_f32_16x16x32_bf16 v[12:15], v[70:73], v[212:215], v[12:15]
	v_mfma_f32_16x16x32_bf16 v[8:11], v[78:81], v[212:215], v[8:11]
	s_setprio 0
	s_setprio 1
	v_mfma_f32_16x16x32_bf16 v[54:57], v[166:169], v[182:185], v[54:57]
	v_mfma_f32_16x16x32_bf16 v[50:53], v[174:177], v[182:185], v[50:53]
	v_mfma_f32_16x16x32_bf16 v[38:41], v[166:169], v[190:193], v[38:41]
	v_mfma_f32_16x16x32_bf16 v[34:37], v[174:177], v[190:193], v[34:37]
	v_mfma_f32_16x16x32_bf16 v[22:25], v[166:169], v[198:201], v[22:25]
	v_mfma_f32_16x16x32_bf16 v[16:19], v[174:177], v[198:201], v[16:19]
	v_mfma_f32_16x16x32_bf16 v[4:7], v[166:169], v[208:211], v[4:7]
	v_mfma_f32_16x16x32_bf16 v[0:3], v[174:177], v[208:211], v[0:3]
	v_mfma_f32_16x16x32_bf16 v[54:57], v[170:173], v[186:189], v[54:57]
	v_mfma_f32_16x16x32_bf16 v[50:53], v[178:181], v[186:189], v[50:53]
	v_mfma_f32_16x16x32_bf16 v[38:41], v[170:173], v[194:197], v[38:41]
	v_mfma_f32_16x16x32_bf16 v[34:37], v[178:181], v[194:197], v[34:37]
	v_mfma_f32_16x16x32_bf16 v[22:25], v[170:173], v[202:205], v[22:25]
	v_mfma_f32_16x16x32_bf16 v[16:19], v[178:181], v[202:205], v[16:19]
	v_mfma_f32_16x16x32_bf16 v[4:7], v[170:173], v[212:215], v[4:7]
	v_mfma_f32_16x16x32_bf16 v[0:3], v[178:181], v[212:215], v[0:3]
	s_setprio 0
	s_barrier
; #define PG8_STAGE(bufoff, gbase, voff) do { _Pragma("unroll") for (int _i = 0; _i < 2; ++_i) \
;         __builtin_amdgcn_global_load_lds((const unsigned*)((const char*)(gbase) + (voff)[_i]), (PG8_LAS unsigned*)(lds + (bufoff) + ldsw + _i * 8192), 16, 0, 0); } while (0)
; #define PG8_LDA(dst, b, h) do { _Pragma("unroll") for (int m = 0; m < 4; ++m) _Pragma("unroll") for (int k = 0; k < 2; ++k) dst[m][k] = *(const PG8_LAS bf16x8*)(lds + PG8_SA(b, h) + aoff + m * 2048 + k * 1024); } while (0)
; #define PG8_LDB(dst, b, h) do { _Pragma("unroll") for (int n = 0; n < 2; ++n) _Pragma("unroll") for (int k = 0; k < 2; ++k) dst[n][k] = *(const PG8_LAS bf16x8*)(lds + PG8_SB(b, h) + boff + n * 2048 + k * 1024); } while (0)
; #define PG8_MMA(ai, bj, At, Bt) do { __builtin_amdgcn_s_setprio(1); _Pragma("unroll") for (int m = 0; m < 4; ++m) _Pragma("unroll") for (int n = 0; n < 2; ++n) _Pragma("unroll") for (int k = 0; k < 2; ++k) \
;         acc[ai][bj][m][n] = __builtin_amdgcn_mfma_f32_16x16x32_bf16(Bt[n][k], At[m][k], acc[ai][bj][m][n], 0, 0, 0); __builtin_amdgcn_s_setprio(0); } while (0)
; #define PG8_WAIT_V(n) asm volatile("s_waitcnt vmcnt(" #n ")" ::: "memory")
; #define PG8_WAIT_L(n) asm volatile("s_waitcnt lgkmcnt(" #n ")" ::: "memory")
; #define PG8_BAR __builtin_amdgcn_s_barrier()
; #define PG8_SCHED __builtin_amdgcn_sched_barrier(0)
; template <class Epi, class Sched, bool ALIGN_EPI = false, bool SP2 = false>
; __device__ __forceinline__ void gemm_phase(PG8_LAS unsigned char* lds, const Gemm g, const Sched& S, const Epi& E, const int tid_in) {
;     ...
;             PG8_LDB(B0, 1, 0); PG8_LDB(B1, 1, 1); PG8_SCHED; PG8_LDA(At, 1, 0); PG8_STAGE(PG8_SA(0, 1), a2 + hstep, voffA);
;             PG8_WAIT_V(8); PG8_WAIT_L(0); PG8_BAR; PG8_MMA(0, 0, At, B0); PG8_MMA(0, 1, At, B1); PG8_BAR; PG8_SCHED;
;             PG8_LDA(At, 1, 1); PG8_STAGE(PG8_SB(1, 0), b3, voffB); PG8_STAGE(PG8_SB(1, 1), b3 + hstep, voffB); PG8_STAGE(PG8_SA(1, 0), a3, voffA);
;             PG8_WAIT_V(8); PG8_WAIT_L(0); PG8_BAR; PG8_MMA(1, 0, At, B0); PG8_MMA(1, 1, At, B1); PG8_BAR; PG8_SCHED;
	s_add_i32 s59, 0, 0x18000
	s_add_i32 s60, 0, 0x1c000
	v_add_u32_e32 v78, s59, v162
	v_add_u32_e32 v178, s60, v162
	ds_read_b128 v[66:69], v78
	ds_read_b128 v[70:73], v78 offset:1024
	ds_read_b128 v[74:77], v78 offset:2048
	ds_read_b128 v[78:81], v78 offset:3072
	ds_read_b128 v[166:169], v178
	ds_read_b128 v[170:173], v178 offset:1024
	ds_read_b128 v[174:177], v178 offset:2048
	ds_read_b128 v[178:181], v178 offset:3072
	s_mov_b32 m0, s45
	s_nop 0
	global_load_lds_dwordx4 v150, s[42:43]
	s_add_u32 s42, s42, 0x80000
	s_addc_u32 s43, s43, 0
	s_mov_b32 m0, s46
	ds_read_b128 v[182:185], v165 offset:32768
	ds_read_b128 v[186:189], v165 offset:33792
	ds_read_b128 v[190:193], v165 offset:34816
	ds_read_b128 v[194:197], v165 offset:35840
	ds_read_b128 v[198:201], v165 offset:36864
	ds_read_b128 v[202:205], v165 offset:37888
	ds_read_b128 v[208:211], v165 offset:38912
	ds_read_b128 v[212:215], v165 offset:39936
	global_load_lds_dwordx4 v146, s[42:43]
	s_mov_b32 m0, s47
	s_nop 0
	global_load_lds_dwordx4 v150, s[42:43]
	s_waitcnt vmcnt(8)
	s_waitcnt lgkmcnt(0)
	s_barrier
	s_setprio 1
	s_waitcnt lgkmcnt(0)
	v_mfma_f32_16x16x32_bf16 v[142:145], v[66:69], v[182:185], v[142:145]
	v_mfma_f32_16x16x32_bf16 v[138:141], v[74:77], v[182:185], v[138:141]
	v_mfma_f32_16x16x32_bf16 v[126:129], v[66:69], v[190:193], v[126:129]
	v_mfma_f32_16x16x32_bf16 v[122:125], v[74:77], v[190:193], v[122:125]
	v_mfma_f32_16x16x32_bf16 v[110:113], v[66:69], v[198:201], v[110:113]
	v_mfma_f32_16x16x32_bf16 v[106:109], v[74:77], v[198:201], v[106:109]
	v_mfma_f32_16x16x32_bf16 v[94:97], v[66:69], v[208:211], v[94:97]
	v_mfma_f32_16x16x32_bf16 v[90:93], v[74:77], v[208:211], v[90:93]
	v_mfma_f32_16x16x32_bf16 v[142:145], v[70:73], v[186:189], v[142:145]
	v_mfma_f32_16x16x32_bf16 v[138:141], v[78:81], v[186:189], v[138:141]
	v_mfma_f32_16x16x32_bf16 v[126:129], v[70:73], v[194:197], v[126:129]
	v_mfma_f32_16x16x32_bf16 v[122:125], v[78:81], v[194:197], v[122:125]
	v_mfma_f32_16x16x32_bf16 v[110:113], v[70:73], v[202:205], v[110:113]
	v_mfma_f32_16x16x32_bf16 v[106:109], v[78:81], v[202:205], v[106:109]
	v_mfma_f32_16x16x32_bf16 v[94:97], v[70:73], v[212:215], v[94:97]
	v_mfma_f32_16x16x32_bf16 v[90:93], v[78:81], v[212:215], v[90:93]
	s_setprio 0
	s_setprio 1
	v_mfma_f32_16x16x32_bf16 v[134:137], v[166:169], v[182:185], v[134:137]
	v_mfma_f32_16x16x32_bf16 v[130:133], v[174:177], v[182:185], v[130:133]
	v_mfma_f32_16x16x32_bf16 v[118:121], v[166:169], v[190:193], v[118:121]
	v_mfma_f32_16x16x32_bf16 v[114:117], v[174:177], v[190:193], v[114:117]
	v_mfma_f32_16x16x32_bf16 v[102:105], v[166:169], v[198:201], v[102:105]
	v_mfma_f32_16x16x32_bf16 v[98:101], v[174:177], v[198:201], v[98:101]
	v_mfma_f32_16x16x32_bf16 v[86:89], v[166:169], v[208:211], v[86:89]
	v_mfma_f32_16x16x32_bf16 v[82:85], v[174:177], v[208:211], v[82:85]
	v_mfma_f32_16x16x32_bf16 v[134:137], v[170:173], v[186:189], v[134:137]
	v_mfma_f32_16x16x32_bf16 v[130:133], v[178:181], v[186:189], v[130:133]
	v_mfma_f32_16x16x32_bf16 v[118:121], v[170:173], v[194:197], v[118:121]
	v_mfma_f32_16x16x32_bf16 v[114:117], v[178:181], v[194:197], v[114:117]
	v_mfma_f32_16x16x32_bf16 v[102:105], v[170:173], v[202:205], v[102:105]
	v_mfma_f32_16x16x32_bf16 v[98:101], v[178:181], v[202:205], v[98:101]
	v_mfma_f32_16x16x32_bf16 v[86:89], v[170:173], v[212:215], v[86:89]
	v_mfma_f32_16x16x32_bf16 v[82:85], v[178:181], v[212:215], v[82:85]
	s_setprio 0
	s_barrier
	s_add_i32 s42, s59, s19
	s_mov_b32 m0, s42
	ds_read_b128 v[182:185], v165 offset:49152
	ds_read_b128 v[186:189], v165 offset:50176
	ds_read_b128 v[190:193], v165 offset:51200
	ds_read_b128 v[194:197], v165 offset:52224
	ds_read_b128 v[198:201], v165 offset:53248
	ds_read_b128 v[202:205], v165 offset:54272
	ds_read_b128 v[208:211], v165 offset:55296
	ds_read_b128 v[212:215], v165 offset:56320
	global_load_lds_dwordx4 v148, s[98:99]
	s_add_i32 m0, s42, 0x2000
	s_add_u32 s38, s38, 0x80080
	s_addc_u32 s39, s39, 0
	s_add_i32 s42, s60, s19
	global_load_lds_dwordx4 v152, s[98:99]
	s_mov_b32 m0, s42
	s_nop 0
	global_load_lds_dwordx4 v148, s[38:39]
	s_add_i32 m0, s42, 0x2000
	s_nop 0
	global_load_lds_dwordx4 v152, s[38:39]
	s_mov_b32 m0, s48
	s_nop 0
	global_load_lds_dwordx4 v146, s[100:101]
	s_waitcnt vmcnt(7)
	s_waitcnt lgkmcnt(0)
	s_barrier
	s_setprio 1
	s_waitcnt lgkmcnt(0)
	v_mfma_f32_16x16x32_bf16 v[62:65], v[66:69], v[182:185], v[62:65]
	v_mfma_f32_16x16x32_bf16 v[58:61], v[74:77], v[182:185], v[58:61]
	v_mfma_f32_16x16x32_bf16 v[46:49], v[66:69], v[190:193], v[46:49]
	v_mfma_f32_16x16x32_bf16 v[42:45], v[74:77], v[190:193], v[42:45]
	v_mfma_f32_16x16x32_bf16 v[30:33], v[66:69], v[198:201], v[30:33]
	v_mfma_f32_16x16x32_bf16 v[26:29], v[74:77], v[198:201], v[26:29]
	v_mfma_f32_16x16x32_bf16 v[12:15], v[66:69], v[208:211], v[12:15]
	v_mfma_f32_16x16x32_bf16 v[8:11], v[74:77], v[208:211], v[8:11]
	v_mfma_f32_16x16x32_bf16 v[62:65], v[70:73], v[186:189], v[62:65]
	v_mfma_f32_16x16x32_bf16 v[58:61], v[78:81], v[186:189], v[58:61]
	v_mfma_f32_16x16x32_bf16 v[46:49], v[70:73], v[194:197], v[46:49]
	v_mfma_f32_16x16x32_bf16 v[42:45], v[78:81], v[194:197], v[42:45]
	v_mfma_f32_16x16x32_bf16 v[30:33], v[70:73], v[202:205], v[30:33]
	v_mfma_f32_16x16x32_bf16 v[26:29], v[78:81], v[202:205], v[26:29]
	v_mfma_f32_16x16x32_bf16 v[12:15], v[70:73], v[212:215], v[12:15]
	v_mfma_f32_16x16x32_bf16 v[8:11], v[78:81], v[212:215], v[8:11]
	s_setprio 0
	s_setprio 1
	v_mfma_f32_16x16x32_bf16 v[54:57], v[166:169], v[182:185], v[54:57]
	v_mfma_f32_16x16x32_bf16 v[50:53], v[174:177], v[182:185], v[50:53]
	v_mfma_f32_16x16x32_bf16 v[38:41], v[166:169], v[190:193], v[38:41]
	v_mfma_f32_16x16x32_bf16 v[34:37], v[174:177], v[190:193], v[34:37]
	v_mfma_f32_16x16x32_bf16 v[22:25], v[166:169], v[198:201], v[22:25]
	v_mfma_f32_16x16x32_bf16 v[16:19], v[174:177], v[198:201], v[16:19]
	v_mfma_f32_16x16x32_bf16 v[4:7], v[166:169], v[208:211], v[4:7]
	v_mfma_f32_16x16x32_bf16 v[0:3], v[174:177], v[208:211], v[0:3]
	v_mfma_f32_16x16x32_bf16 v[54:57], v[170:173], v[186:189], v[54:57]
	v_mfma_f32_16x16x32_bf16 v[50:53], v[178:181], v[186:189], v[50:53]
	v_mfma_f32_16x16x32_bf16 v[38:41], v[170:173], v[194:197], v[38:41]
	v_mfma_f32_16x16x32_bf16 v[34:37], v[178:181], v[194:197], v[34:37]
	v_mfma_f32_16x16x32_bf16 v[22:25], v[170:173], v[202:205], v[22:25]
	v_mfma_f32_16x16x32_bf16 v[16:19], v[178:181], v[202:205], v[16:19]
	v_mfma_f32_16x16x32_bf16 v[4:7], v[170:173], v[212:215], v[4:7]
	v_mfma_f32_16x16x32_bf16 v[0:3], v[178:181], v[212:215], v[0:3]
	s_setprio 0
	s_barrier
	s_add_i32 s58, s58, 2
	s_add_u32 s34, s34, 0x100
	s_addc_u32 s35, s35, 0
	s_add_u32 s56, s56, 0x100
	s_addc_u32 s57, s57, 0
	s_cmp_gt_u32 s58, 29
	s_cbranch_scc0 .LBB0_412
	s_and_b64 vcc, exec, s[2:3]
	s_cbranch_vccz .LBB0_415
	s_barrier

; #define PG8_STAGE(bufoff, gbase, voff) do { _Pragma("unroll") for (int _i = 0; _i < 2; ++_i) \
;         __builtin_amdgcn_global_load_lds((const unsigned*)((const char*)(gbase) + (voff)[_i]), (PG8_LAS unsigned*)(lds + (bufoff) + ldsw + _i * 8192), 16, 0, 0); } while (0)
; #define PG8_WAIT_V(n) asm volatile("s_waitcnt vmcnt(" #n ")" ::: "memory")
; template <class Epi, class Sched, bool ALIGN_EPI = false, bool SP2 = false>
; __device__ __forceinline__ void gemm_phase(PG8_LAS unsigned char* lds, const Gemm g, const Sched& S, const Epi& E, const int tid_in) {
;     ...
;     const int tid = tid_l, wid = __builtin_amdgcn_readfirstlane(tid >> 6), lane = tid & 63, wr = wid >> 2, wc = wid & 3, fr = lane & 15, fq = lane >> 4;
;     const int K = g.K, nt = K / BK;
;     unsigned voffA[2], voffB[2];
; #pragma unroll
;     for (int i = 0; i < 2; ++i) { int R, C; stage_rc(tid * 16 + i * 8192, R, C); const int Rb = perm_row<Epi::PMODE>(R);
;         voffA[i] = (unsigned)(R * K + C) * 2u; voffB[i] = (unsigned)(Rb * K + C) * 2u; }
;     const size_t kstep = (size_t)(BK * 2);
;     const size_t hstep = (size_t)HALF * K * 2;
;     const size_t tstep = 2 * hstep;
;     const unsigned ldsw = (unsigned)wid * 1024u;
;     const int aoff = lds_byte(wr * 64 + fr, fq * 8), boff = lds_byte(wc * 32 + fr, fq * 8);
;     ...
;     Unit cur, nxt; int ui = 0;
;     if (!S.next(0, cur)) return;
;     f32x4 acc[2][2][4][2];
; #pragma unroll
;     for (int a = 0; a < 2; ++a)
; #pragma unroll
;         for (int b = 0; b < 2; ++b)
; #pragma unroll
;             for (int m = 0; m < 4; ++m)
; #pragma unroll
;                 for (int n = 0; n < 2; ++n) acc[a][b][m][n] = (f32x4){0.f, 0.f, 0.f, 0.f};
;     bf16x8 At[4][2], B0[2][2], B1[2][2];
;     const char* cA = (const char*)g.A + (size_t)cur.pm * tstep; const char* cB = (const char*)g.Bt + (size_t)cur.pn * tstep;
;     S.a_ready(cur);
;     if constexpr (Epi::PREF) E.prefetch(cur, 0, lds, wid, lane);
;     if constexpr (SP2) {
;         PG8_STAGE(PG8_SB(0, 0), cB, voffB); PG8_STAGE(PG8_SB(0, 1), cB + hstep, voffB); PG8_STAGE(PG8_SA(0, 0), cA, voffA); PG8_STAGE(PG8_SA(0, 1), cA + hstep, voffA);
;         if (wr == 1) PG8_BAR;
;         PG8_WAIT_V(2); PG8_BAR;
;         PG8_STAGE(PG8_SB(1, 0), cB + kstep, voffB); PG8_STAGE(PG8_SA(1, 0), cA + kstep, voffA); PG8_STAGE(PG8_SB(1, 1), cB + hstep + kstep, voffB);
;         PG8_WAIT_V(6); PG8_BAR;
.LBB0_946:
	s_add_u32 s20, s22, 0x3e000000
	s_addc_u32 s21, s23, 0
	s_add_u32 s22, s22, 0x31000000
	s_addc_u32 s23, s23, 0
	s_lshl_b32 s25, s25, 5
	s_and_b32 s25, s25, 0x60
	s_add_i32 m0, s42, 0x18000
	v_lshl_add_u64 v[6:7], v[6:7], 0, s[12:13]
	s_lshl_b32 s46, s26, 6
	s_lshl_b32 s28, s26, 13
	s_lshl_b32 s29, s25, 7
	s_waitcnt vmcnt(2)
	s_barrier
	global_load_lds_dwordx4 v[6:7], off
	v_lshl_add_u64 v[4:5], v[4:5], 0, s[12:13]
	s_add_i32 m0, s42, 0x1a000
	s_add_i32 s47, s42, 0x8000
	s_add_i32 s48, s42, 0xa000
	global_load_lds_dwordx4 v[4:5], off
	v_lshl_add_u64 v[0:1], v[0:1], 0, s[12:13]
	s_mov_b32 m0, s47
	s_add_u32 s100, s30, 0x80
	s_addc_u32 s101, s31, 0
	s_add_u32 s26, s34, 0x60080
	global_load_lds_dwordx4 v[0:1], off
	v_lshl_add_u64 v[0:1], v[2:3], 0, s[12:13]
	s_mov_b32 m0, s48
	s_addc_u32 s27, s35, 0
	global_load_lds_dwordx4 v[0:1], off
	s_add_i32 m0, s42, 0x1c000
	v_lshl_add_u64 v[0:1], s[26:27], 0, v[198:199]
	global_load_lds_dwordx4 v[0:1], off
	v_lshl_add_u64 v[0:1], s[26:27], 0, v[194:195]
	s_add_i32 m0, s42, 0x1e000
	v_bfe_u32 v208, v8, 4, 2
	global_load_lds_dwordx4 v[0:1], off
	v_and_b32_e32 v21, 15, v8
	v_lshlrev_b32_e32 v0, 4, v208
	v_lshlrev_b32_e32 v1, 2, v8
	v_lshl_or_b32 v0, v21, 6, v0
	v_and_b32_e32 v1, 32, v1
	v_bitop3_b32 v2, v0, s28, v1 bitop3:0xde
	s_movk_i32 s28, 0x600
	v_bitop3_b32 v230, v0, s29, v1 bitop3:0xde
	v_lshrrev_b32_e32 v1, 1, v14
	v_mul_lo_u32 v0, v13, s28
	s_movk_i32 s29, 0x6000
	v_mad_u64_u32 v[0:1], s[26:27], v1, s29, v[0:1]
	v_or_b32_e32 v0, v0, v15
	v_add_lshl_u32 v202, v0, v16, 1
	v_lshrrev_b32_e32 v1, 1, v9
	v_mul_lo_u32 v0, v10, s28
	s_waitcnt vmcnt(6)
	s_or_b32 s49, s25, 0xc00
	v_mad_u64_u32 v[0:1], s[26:27], v1, s29, v[0:1]
	v_lshl_or_b32 v231, v208, 3, s25
	s_cmpk_lt_u32 s24, 0x100
	v_or_b32_e32 v0, v0, v11
	v_or_b32_e32 v209, s46, v21
	v_or_b32_e32 v232, 0xc80, v231
	s_cselect_b64 s[24:25], -1, 0
	v_mov_b32_e32 v203, v20
	v_add_lshl_u32 v204, v0, v12, 1
	v_mov_b32_e32 v205, v20
	s_mov_b32 s50, 0
	v_add_u32_e32 v233, 0, v2
	v_readlane_b32 s53, v253, 58
	v_readlane_b32 s36, v253, 57
	s_barrier
	s_branch .LBB0_949

; #define PG8_STAGE(bufoff, gbase, voff) do { _Pragma("unroll") for (int _i = 0; _i < 2; ++_i) \
;         __builtin_amdgcn_global_load_lds((const unsigned*)((const char*)(gbase) + (voff)[_i]), (PG8_LAS unsigned*)(lds + (bufoff) + ldsw + _i * 8192), 16, 0, 0); } while (0)
; #define PG8_LDA(dst, b, h) do { _Pragma("unroll") for (int m = 0; m < 4; ++m) _Pragma("unroll") for (int k = 0; k < 2; ++k) dst[m][k] = *(const PG8_LAS bf16x8*)(lds + PG8_SA(b, h) + aoff + m * 2048 + k * 1024); } while (0)
; #define PG8_LDB(dst, b, h) do { _Pragma("unroll") for (int n = 0; n < 2; ++n) _Pragma("unroll") for (int k = 0; k < 2; ++k) dst[n][k] = *(const PG8_LAS bf16x8*)(lds + PG8_SB(b, h) + boff + n * 2048 + k * 1024); } while (0)
; #define PG8_WAIT_V(n) asm volatile("s_waitcnt vmcnt(" #n ")" ::: "memory")
; #define PG8_WAIT_L(n) asm volatile("s_waitcnt lgkmcnt(" #n ")" ::: "memory")
; template <class Epi, class Sched, bool ALIGN_EPI = false, bool SP2 = false>
; __device__ __forceinline__ void gemm_phase(PG8_LAS unsigned char* lds, const Gemm g, const Sched& S, const Epi& E, const int tid_in) {
;     ...
;         const bool has_next = S.next(ui + 1, nxt);
;         const char* nA = has_next ? (const char*)g.A + (size_t)nxt.pm * tstep : cA; const char* nB = has_next ? (const char*)g.Bt + (size_t)nxt.pn * tstep : cB;
;         for (int t = 0; t < nt; t += 2) {
;             if constexpr (Epi::KSPLIT > 0) { if (t == Epi::KSPLIT / BK) E.midk(acc, cur, wr, wc, fr, fq); }
;             const bool last = (t == nt - 2);
;             const char* a1 = cA + (size_t)(t + 1) * kstep;
;             const char* a2 = last ? nA : cA + (size_t)(t + 2) * kstep; const char* b2 = last ? nB : cB + (size_t)(t + 2) * kstep;
;             const char* a3 = a2 + kstep; const char* b3 = b2 + kstep;
;             if (last && has_next) S.a_ready(nxt);
;             if constexpr (SP2) {
;             PG8_LDB(B0, 0, 0); PG8_LDB(B1, 0, 1); PG8_SCHED; PG8_LDA(At, 0, 0); PG8_STAGE(PG8_SA(1, 1), a1 + hstep, voffA);
;             PG8_WAIT_V(8); PG8_WAIT_L(0); PG8_BAR; PG8_MMA(0, 0, At, B0); PG8_MMA(0, 1, At, B1); PG8_BAR; PG8_SCHED;
;             PG8_LDA(At, 0, 1); PG8_STAGE(PG8_SB(0, 0), b2, voffB); PG8_STAGE(PG8_SB(0, 1), b2 + hstep, voffB); PG8_STAGE(PG8_SA(0, 0), a2, voffA);
;             PG8_WAIT_V(8); PG8_WAIT_L(0); PG8_BAR; PG8_MMA(1, 0, At, B0); PG8_MMA(1, 1, At, B1); PG8_BAR; PG8_SCHED;
.LBB0_960:
	s_mov_b32 m0, s48
	s_nop 0
	global_load_lds_dwordx4 v196, s[100:101]
	s_add_u32 s36, s30, s34
	s_addc_u32 s37, s31, s35
	s_add_u32 s36, s36, 0x100
	s_addc_u32 s37, s37, 0
	s_add_u32 s61, s58, s34
	s_addc_u32 s62, s59, s35
	s_add_i32 s63, 0, 0x10000
	s_cmpk_eq_i32 s34, 0xb00
	s_cselect_b32 s41, s27, s37
	s_cselect_b32 s40, s26, s36
	s_cselect_b32 s37, s29, s62
	s_cselect_b32 s36, s28, s61
	s_add_i32 s61, 0, 0x14000
	v_add_u32_e32 v142, s63, v230
	v_add_u32_e32 v158, s61, v230
	ds_read_b128 v[130:133], v142
	ds_read_b128 v[134:137], v142 offset:1024
	ds_read_b128 v[138:141], v142 offset:2048
	ds_read_b128 v[142:145], v142 offset:3072
	ds_read_b128 v[146:149], v158
	ds_read_b128 v[150:153], v158 offset:1024
	ds_read_b128 v[154:157], v158 offset:2048
	ds_read_b128 v[158:161], v158 offset:3072
	v_lshl_add_u64 v[214:215], v[182:183], 0, s[34:35]
	s_add_i32 m0, s42, 0xc000
	ds_read_b128 v[162:165], v233
	ds_read_b128 v[166:169], v233 offset:1024
	ds_read_b128 v[170:173], v233 offset:2048
	ds_read_b128 v[174:177], v233 offset:3072
	ds_read_b128 v[178:181], v233 offset:4096
	ds_read_b128 v[186:189], v233 offset:5120
	ds_read_b128 v[190:193], v233 offset:6144
	ds_read_b128 v[210:213], v233 offset:7168
	global_load_lds_dwordx4 v[214:215], off
	v_lshl_add_u64 v[214:215], v[184:185], 0, s[34:35]
	s_add_i32 m0, s42, 0xe000
	s_nop 0
	global_load_lds_dwordx4 v[214:215], off
	s_waitcnt vmcnt(8)
	s_waitcnt lgkmcnt(0)
	s_barrier
	s_setprio 1
	s_waitcnt lgkmcnt(0)
	v_mfma_f32_16x16x32_bf16 v[126:129], v[130:133], v[162:165], v[126:129]
	v_mfma_f32_16x16x32_bf16 v[122:125], v[138:141], v[162:165], v[122:125]
	v_mfma_f32_16x16x32_bf16 v[110:113], v[130:133], v[170:173], v[110:113]
	v_mfma_f32_16x16x32_bf16 v[106:109], v[138:141], v[170:173], v[106:109]
	v_mfma_f32_16x16x32_bf16 v[102:105], v[130:133], v[178:181], v[102:105]
	v_mfma_f32_16x16x32_bf16 v[94:97], v[138:141], v[178:181], v[94:97]
	v_mfma_f32_16x16x32_bf16 v[86:89], v[130:133], v[190:193], v[86:89]
	v_mfma_f32_16x16x32_bf16 v[78:81], v[138:141], v[190:193], v[78:81]
	v_mfma_f32_16x16x32_bf16 v[126:129], v[134:137], v[166:169], v[126:129]
	v_mfma_f32_16x16x32_bf16 v[122:125], v[142:145], v[166:169], v[122:125]
	v_mfma_f32_16x16x32_bf16 v[110:113], v[134:137], v[174:177], v[110:113]
	v_mfma_f32_16x16x32_bf16 v[106:109], v[142:145], v[174:177], v[106:109]
	v_mfma_f32_16x16x32_bf16 v[102:105], v[134:137], v[186:189], v[102:105]
	v_mfma_f32_16x16x32_bf16 v[94:97], v[142:145], v[186:189], v[94:97]
	v_mfma_f32_16x16x32_bf16 v[86:89], v[134:137], v[210:213], v[86:89]
	v_mfma_f32_16x16x32_bf16 v[78:81], v[142:145], v[210:213], v[78:81]
	s_setprio 0
	s_setprio 1
	v_mfma_f32_16x16x32_bf16 v[118:121], v[146:149], v[162:165], v[118:121]
	v_mfma_f32_16x16x32_bf16 v[114:117], v[154:157], v[162:165], v[114:117]
	v_mfma_f32_16x16x32_bf16 v[98:101], v[146:149], v[170:173], v[98:101]
	v_mfma_f32_16x16x32_bf16 v[90:93], v[154:157], v[170:173], v[90:93]
	v_mfma_f32_16x16x32_bf16 v[82:85], v[146:149], v[178:181], v[82:85]
	v_mfma_f32_16x16x32_bf16 v[74:77], v[154:157], v[178:181], v[74:77]
	v_mfma_f32_16x16x32_bf16 v[70:73], v[146:149], v[190:193], v[70:73]
	v_mfma_f32_16x16x32_bf16 v[66:69], v[154:157], v[190:193], v[66:69]
	v_mfma_f32_16x16x32_bf16 v[118:121], v[150:153], v[166:169], v[118:121]
	v_mfma_f32_16x16x32_bf16 v[114:117], v[158:161], v[166:169], v[114:117]
	v_mfma_f32_16x16x32_bf16 v[98:101], v[150:153], v[174:177], v[98:101]
	v_mfma_f32_16x16x32_bf16 v[90:93], v[158:161], v[174:177], v[90:93]
	v_mfma_f32_16x16x32_bf16 v[82:85], v[150:153], v[186:189], v[82:85]
	v_mfma_f32_16x16x32_bf16 v[74:77], v[158:161], v[186:189], v[74:77]
	v_mfma_f32_16x16x32_bf16 v[70:73], v[150:153], v[210:213], v[70:73]
	v_mfma_f32_16x16x32_bf16 v[66:69], v[158:161], v[210:213], v[66:69]
	s_setprio 0
	s_barrier
	s_add_i32 s62, s63, s19
	s_add_u32 s98, s36, 0x80
	s_addc_u32 s99, s37, 0
	s_mov_b32 m0, s62
	ds_read_b128 v[162:165], v233 offset:16384
	ds_read_b128 v[166:169], v233 offset:17408
	ds_read_b128 v[170:173], v233 offset:18432
	ds_read_b128 v[174:177], v233 offset:19456
	ds_read_b128 v[178:181], v233 offset:20480
	ds_read_b128 v[186:189], v233 offset:21504
	ds_read_b128 v[190:193], v233 offset:22528
	ds_read_b128 v[210:213], v233 offset:23552
	global_load_lds_dwordx4 v198, s[36:37]
	s_add_i32 m0, s62, 0x2000
	s_add_u32 s62, s36, 0x60000
	s_addc_u32 s63, s37, 0
	s_add_i32 s61, s61, s19
	global_load_lds_dwordx4 v194, s[36:37]
	s_mov_b32 m0, s61
	s_add_u32 s100, s40, 0x80
	s_addc_u32 s101, s41, 0
	global_load_lds_dwordx4 v198, s[62:63]
	s_add_i32 m0, s61, 0x2000
	s_nop 0
	global_load_lds_dwordx4 v194, s[62:63]
	s_mov_b32 m0, s42
	s_nop 0
	global_load_lds_dwordx4 v200, s[40:41]
	s_waitcnt vmcnt(7)
	s_waitcnt lgkmcnt(0)
	s_barrier
; #define PG8_STAGE(bufoff, gbase, voff) do { _Pragma("unroll") for (int _i = 0; _i < 2; ++_i) \
;         __builtin_amdgcn_global_load_lds((const unsigned*)((const char*)(gbase) + (voff)[_i]), (PG8_LAS unsigned*)(lds + (bufoff) + ldsw + _i * 8192), 16, 0, 0); } while (0)
; #define PG8_LDA(dst, b, h) do { _Pragma("unroll") for (int m = 0; m < 4; ++m) _Pragma("unroll") for (int k = 0; k < 2; ++k) dst[m][k] = *(const PG8_LAS bf16x8*)(lds + PG8_SA(b, h) + aoff + m * 2048 + k * 1024); } while (0)
; #define PG8_LDB(dst, b, h) do { _Pragma("unroll") for (int n = 0; n < 2; ++n) _Pragma("unroll") for (int k = 0; k < 2; ++k) dst[n][k] = *(const PG8_LAS bf16x8*)(lds + PG8_SB(b, h) + boff + n * 2048 + k * 1024); } while (0)
; #define PG8_MMA(ai, bj, At, Bt) do { __builtin_amdgcn_s_setprio(1); _Pragma("unroll") for (int m = 0; m < 4; ++m) _Pragma("unroll") for (int n = 0; n < 2; ++n) _Pragma("unroll") for (int k = 0; k < 2; ++k) \
;         acc[ai][bj][m][n] = __builtin_amdgcn_mfma_f32_16x16x32_bf16(Bt[n][k], At[m][k], acc[ai][bj][m][n], 0, 0, 0); __builtin_amdgcn_s_setprio(0); } while (0)
; #define PG8_WAIT_V(n) asm volatile("s_waitcnt vmcnt(" #n ")" ::: "memory")
; #define PG8_WAIT_L(n) asm volatile("s_waitcnt lgkmcnt(" #n ")" ::: "memory")
; #define PG8_BAR __builtin_amdgcn_s_barrier()
; #define PG8_SCHED __builtin_amdgcn_sched_barrier(0)
; template <class Epi, class Sched, bool ALIGN_EPI = false, bool SP2 = false>
; __device__ __forceinline__ void gemm_phase(PG8_LAS unsigned char* lds, const Gemm g, const Sched& S, const Epi& E, const int tid_in) {
;     ...
;             PG8_WAIT_V(8); PG8_WAIT_L(0); PG8_BAR; PG8_MMA(1, 0, At, B0); PG8_MMA(1, 1, At, B1); PG8_BAR; PG8_SCHED;
;             PG8_LDB(B0, 1, 0); PG8_LDB(B1, 1, 1); PG8_SCHED; PG8_LDA(At, 1, 0); PG8_STAGE(PG8_SA(0, 1), a2 + hstep, voffA);
	s_setprio 1
	s_waitcnt lgkmcnt(0)
	v_mfma_f32_16x16x32_bf16 v[62:65], v[130:133], v[162:165], v[62:65]
	v_mfma_f32_16x16x32_bf16 v[58:61], v[138:141], v[162:165], v[58:61]
	v_mfma_f32_16x16x32_bf16 v[54:57], v[130:133], v[170:173], v[54:57]
	v_mfma_f32_16x16x32_bf16 v[46:49], v[138:141], v[170:173], v[46:49]
	v_mfma_f32_16x16x32_bf16 v[38:41], v[130:133], v[178:181], v[38:41]
	v_mfma_f32_16x16x32_bf16 v[30:33], v[138:141], v[178:181], v[30:33]
	v_mfma_f32_16x16x32_bf16 v[22:25], v[130:133], v[190:193], v[22:25]
	v_mfma_f32_16x16x32_bf16 v[12:15], v[138:141], v[190:193], v[12:15]
	v_mfma_f32_16x16x32_bf16 v[62:65], v[134:137], v[166:169], v[62:65]
	v_mfma_f32_16x16x32_bf16 v[58:61], v[142:145], v[166:169], v[58:61]
	v_mfma_f32_16x16x32_bf16 v[54:57], v[134:137], v[174:177], v[54:57]
	v_mfma_f32_16x16x32_bf16 v[46:49], v[142:145], v[174:177], v[46:49]
	v_mfma_f32_16x16x32_bf16 v[38:41], v[134:137], v[186:189], v[38:41]
	v_mfma_f32_16x16x32_bf16 v[30:33], v[142:145], v[186:189], v[30:33]
	v_mfma_f32_16x16x32_bf16 v[22:25], v[134:137], v[210:213], v[22:25]
	v_mfma_f32_16x16x32_bf16 v[12:15], v[142:145], v[210:213], v[12:15]
	s_setprio 0
	s_setprio 1
	v_mfma_f32_16x16x32_bf16 v[50:53], v[146:149], v[162:165], v[50:53]
	v_mfma_f32_16x16x32_bf16 v[42:45], v[154:157], v[162:165], v[42:45]
	v_mfma_f32_16x16x32_bf16 v[34:37], v[146:149], v[170:173], v[34:37]
	v_mfma_f32_16x16x32_bf16 v[26:29], v[154:157], v[170:173], v[26:29]
	v_mfma_f32_16x16x32_bf16 v[16:19], v[146:149], v[178:181], v[16:19]
	v_mfma_f32_16x16x32_bf16 v[8:11], v[154:157], v[178:181], v[8:11]
	v_mfma_f32_16x16x32_bf16 v[4:7], v[146:149], v[190:193], v[4:7]
	v_mfma_f32_16x16x32_bf16 v[0:3], v[154:157], v[190:193], v[0:3]
	v_mfma_f32_16x16x32_bf16 v[50:53], v[150:153], v[166:169], v[50:53]
	v_mfma_f32_16x16x32_bf16 v[42:45], v[158:161], v[166:169], v[42:45]
	v_mfma_f32_16x16x32_bf16 v[34:37], v[150:153], v[174:177], v[34:37]
	v_mfma_f32_16x16x32_bf16 v[26:29], v[158:161], v[174:177], v[26:29]
	v_mfma_f32_16x16x32_bf16 v[16:19], v[150:153], v[186:189], v[16:19]
	v_mfma_f32_16x16x32_bf16 v[8:11], v[158:161], v[186:189], v[8:11]
	v_mfma_f32_16x16x32_bf16 v[4:7], v[150:153], v[210:213], v[4:7]
	v_mfma_f32_16x16x32_bf16 v[0:3], v[158:161], v[210:213], v[0:3]
	s_setprio 0
	s_barrier
	s_add_i32 s61, 0, 0x18000
	s_add_i32 s62, 0, 0x1c000
	v_add_u32_e32 v142, s61, v230
	v_add_u32_e32 v158, s62, v230
	ds_read_b128 v[130:133], v142
	ds_read_b128 v[134:137], v142 offset:1024
	ds_read_b128 v[138:141], v142 offset:2048
	ds_read_b128 v[142:145], v142 offset:3072
	ds_read_b128 v[146:149], v158
	ds_read_b128 v[150:153], v158 offset:1024
	ds_read_b128 v[154:157], v158 offset:2048
	ds_read_b128 v[158:161], v158 offset:3072
	s_mov_b32 m0, s43
	s_nop 0
	global_load_lds_dwordx4 v196, s[40:41]
	s_add_u32 s40, s40, 0x60000
	s_addc_u32 s41, s41, 0
	s_mov_b32 m0, s44
	ds_read_b128 v[162:165], v233 offset:32768
	ds_read_b128 v[166:169], v233 offset:33792
	ds_read_b128 v[170:173], v233 offset:34816
	ds_read_b128 v[174:177], v233 offset:35840
	ds_read_b128 v[178:181], v233 offset:36864
	ds_read_b128 v[186:189], v233 offset:37888
	ds_read_b128 v[190:193], v233 offset:38912
	ds_read_b128 v[210:213], v233 offset:39936
	global_load_lds_dwordx4 v200, s[40:41]
	s_mov_b32 m0, s45
	s_nop 0
	global_load_lds_dwordx4 v196, s[40:41]
	s_waitcnt vmcnt(8)
	s_waitcnt lgkmcnt(0)
	s_barrier
; #define PG8_STAGE(bufoff, gbase, voff) do { _Pragma("unroll") for (int _i = 0; _i < 2; ++_i) \
;         __builtin_amdgcn_global_load_lds((const unsigned*)((const char*)(gbase) + (voff)[_i]), (PG8_LAS unsigned*)(lds + (bufoff) + ldsw + _i * 8192), 16, 0, 0); } while (0)
; #define PG8_LDA(dst, b, h) do { _Pragma("unroll") for (int m = 0; m < 4; ++m) _Pragma("unroll") for (int k = 0; k < 2; ++k) dst[m][k] = *(const PG8_LAS bf16x8*)(lds + PG8_SA(b, h) + aoff + m * 2048 + k * 1024); } while (0)
; #define PG8_MMA(ai, bj, At, Bt) do { __builtin_amdgcn_s_setprio(1); _Pragma("unroll") for (int m = 0; m < 4; ++m) _Pragma("unroll") for (int n = 0; n < 2; ++n) _Pragma("unroll") for (int k = 0; k < 2; ++k) \
;         acc[ai][bj][m][n] = __builtin_amdgcn_mfma_f32_16x16x32_bf16(Bt[n][k], At[m][k], acc[ai][bj][m][n], 0, 0, 0); __builtin_amdgcn_s_setprio(0); } while (0)
; #define PG8_WAIT_V(n) asm volatile("s_waitcnt vmcnt(" #n ")" ::: "memory")
; #define PG8_WAIT_L(n) asm volatile("s_waitcnt lgkmcnt(" #n ")" ::: "memory")
; #define PG8_BAR __builtin_amdgcn_s_barrier()
; #define PG8_SCHED __builtin_amdgcn_sched_barrier(0)
; template <class Epi, class Sched, bool ALIGN_EPI = false, bool SP2 = false>
; __device__ __forceinline__ void gemm_phase(PG8_LAS unsigned char* lds, const Gemm g, const Sched& S, const Epi& E, const int tid_in) {
;     ...
;             PG8_WAIT_V(8); PG8_WAIT_L(0); PG8_BAR; PG8_MMA(0, 0, At, B0); PG8_MMA(0, 1, At, B1); PG8_BAR; PG8_SCHED;
;             PG8_LDA(At, 1, 1); PG8_STAGE(PG8_SB(1, 0), b3, voffB); PG8_STAGE(PG8_SB(1, 1), b3 + hstep, voffB); PG8_STAGE(PG8_SA(1, 0), a3, voffA);
;             PG8_WAIT_V(8); PG8_WAIT_L(0); PG8_BAR; PG8_MMA(1, 0, At, B0); PG8_MMA(1, 1, At, B1); PG8_BAR; PG8_SCHED;
	s_setprio 1
	s_waitcnt lgkmcnt(0)
	v_mfma_f32_16x16x32_bf16 v[126:129], v[130:133], v[162:165], v[126:129]
	v_mfma_f32_16x16x32_bf16 v[122:125], v[138:141], v[162:165], v[122:125]
	v_mfma_f32_16x16x32_bf16 v[110:113], v[130:133], v[170:173], v[110:113]
	v_mfma_f32_16x16x32_bf16 v[106:109], v[138:141], v[170:173], v[106:109]
	v_mfma_f32_16x16x32_bf16 v[102:105], v[130:133], v[178:181], v[102:105]
	v_mfma_f32_16x16x32_bf16 v[94:97], v[138:141], v[178:181], v[94:97]
	v_mfma_f32_16x16x32_bf16 v[86:89], v[130:133], v[190:193], v[86:89]
	v_mfma_f32_16x16x32_bf16 v[78:81], v[138:141], v[190:193], v[78:81]
	v_mfma_f32_16x16x32_bf16 v[126:129], v[134:137], v[166:169], v[126:129]
	v_mfma_f32_16x16x32_bf16 v[122:125], v[142:145], v[166:169], v[122:125]
	v_mfma_f32_16x16x32_bf16 v[110:113], v[134:137], v[174:177], v[110:113]
	v_mfma_f32_16x16x32_bf16 v[106:109], v[142:145], v[174:177], v[106:109]
	v_mfma_f32_16x16x32_bf16 v[102:105], v[134:137], v[186:189], v[102:105]
	v_mfma_f32_16x16x32_bf16 v[94:97], v[142:145], v[186:189], v[94:97]
	v_mfma_f32_16x16x32_bf16 v[86:89], v[134:137], v[210:213], v[86:89]
	v_mfma_f32_16x16x32_bf16 v[78:81], v[142:145], v[210:213], v[78:81]
	s_setprio 0
	s_setprio 1
	v_mfma_f32_16x16x32_bf16 v[118:121], v[146:149], v[162:165], v[118:121]
	v_mfma_f32_16x16x32_bf16 v[114:117], v[154:157], v[162:165], v[114:117]
	v_mfma_f32_16x16x32_bf16 v[98:101], v[146:149], v[170:173], v[98:101]
	v_mfma_f32_16x16x32_bf16 v[90:93], v[154:157], v[170:173], v[90:93]
	v_mfma_f32_16x16x32_bf16 v[82:85], v[146:149], v[178:181], v[82:85]
	v_mfma_f32_16x16x32_bf16 v[74:77], v[154:157], v[178:181], v[74:77]
	v_mfma_f32_16x16x32_bf16 v[70:73], v[146:149], v[190:193], v[70:73]
	v_mfma_f32_16x16x32_bf16 v[66:69], v[154:157], v[190:193], v[66:69]
	v_mfma_f32_16x16x32_bf16 v[118:121], v[150:153], v[166:169], v[118:121]
	v_mfma_f32_16x16x32_bf16 v[114:117], v[158:161], v[166:169], v[114:117]
	v_mfma_f32_16x16x32_bf16 v[98:101], v[150:153], v[174:177], v[98:101]
	v_mfma_f32_16x16x32_bf16 v[90:93], v[158:161], v[174:177], v[90:93]
	v_mfma_f32_16x16x32_bf16 v[82:85], v[150:153], v[186:189], v[82:85]
	v_mfma_f32_16x16x32_bf16 v[74:77], v[158:161], v[186:189], v[74:77]
	v_mfma_f32_16x16x32_bf16 v[70:73], v[150:153], v[210:213], v[70:73]
	v_mfma_f32_16x16x32_bf16 v[66:69], v[158:161], v[210:213], v[66:69]
	s_setprio 0
	s_barrier
	s_add_i32 s40, s61, s19
	s_mov_b32 m0, s40
	ds_read_b128 v[162:165], v233 offset:49152
	ds_read_b128 v[166:169], v233 offset:50176
	ds_read_b128 v[170:173], v233 offset:51200
	ds_read_b128 v[174:177], v233 offset:52224
	ds_read_b128 v[178:181], v233 offset:53248
	ds_read_b128 v[186:189], v233 offset:54272
	ds_read_b128 v[190:193], v233 offset:55296
	ds_read_b128 v[210:213], v233 offset:56320
	global_load_lds_dwordx4 v198, s[98:99]
	s_add_i32 m0, s40, 0x2000
	s_add_u32 s36, s36, 0x60080
	s_addc_u32 s37, s37, 0
	s_add_i32 s40, s62, s19
	global_load_lds_dwordx4 v194, s[98:99]
	s_mov_b32 m0, s40
	s_nop 0
	global_load_lds_dwordx4 v198, s[36:37]
	s_add_i32 m0, s40, 0x2000
	s_nop 0
	global_load_lds_dwordx4 v194, s[36:37]
	s_mov_b32 m0, s47
	s_nop 0
	global_load_lds_dwordx4 v200, s[100:101]
	s_waitcnt vmcnt(7)
	s_waitcnt lgkmcnt(0)
	s_barrier
	s_setprio 1
	s_waitcnt lgkmcnt(0)
	v_mfma_f32_16x16x32_bf16 v[62:65], v[130:133], v[162:165], v[62:65]
	v_mfma_f32_16x16x32_bf16 v[58:61], v[138:141], v[162:165], v[58:61]
	v_mfma_f32_16x16x32_bf16 v[54:57], v[130:133], v[170:173], v[54:57]
	v_mfma_f32_16x16x32_bf16 v[46:49], v[138:141], v[170:173], v[46:49]
	v_mfma_f32_16x16x32_bf16 v[38:41], v[130:133], v[178:181], v[38:41]
	v_mfma_f32_16x16x32_bf16 v[30:33], v[138:141], v[178:181], v[30:33]
	v_mfma_f32_16x16x32_bf16 v[22:25], v[130:133], v[190:193], v[22:25]
	v_mfma_f32_16x16x32_bf16 v[12:15], v[138:141], v[190:193], v[12:15]
	v_mfma_f32_16x16x32_bf16 v[62:65], v[134:137], v[166:169], v[62:65]
	v_mfma_f32_16x16x32_bf16 v[58:61], v[142:145], v[166:169], v[58:61]
	v_mfma_f32_16x16x32_bf16 v[54:57], v[134:137], v[174:177], v[54:57]
	v_mfma_f32_16x16x32_bf16 v[46:49], v[142:145], v[174:177], v[46:49]
	v_mfma_f32_16x16x32_bf16 v[38:41], v[134:137], v[186:189], v[38:41]
	v_mfma_f32_16x16x32_bf16 v[30:33], v[142:145], v[186:189], v[30:33]
	v_mfma_f32_16x16x32_bf16 v[22:25], v[134:137], v[210:213], v[22:25]
	v_mfma_f32_16x16x32_bf16 v[12:15], v[142:145], v[210:213], v[12:15]
	s_setprio 0
	s_setprio 1
	v_mfma_f32_16x16x32_bf16 v[50:53], v[146:149], v[162:165], v[50:53]
	v_mfma_f32_16x16x32_bf16 v[42:45], v[154:157], v[162:165], v[42:45]
	v_mfma_f32_16x16x32_bf16 v[34:37], v[146:149], v[170:173], v[34:37]
	v_mfma_f32_16x16x32_bf16 v[26:29], v[154:157], v[170:173], v[26:29]
	v_mfma_f32_16x16x32_bf16 v[16:19], v[146:149], v[178:181], v[16:19]
	v_mfma_f32_16x16x32_bf16 v[8:11], v[154:157], v[178:181], v[8:11]
	v_mfma_f32_16x16x32_bf16 v[4:7], v[146:149], v[190:193], v[4:7]
	v_mfma_f32_16x16x32_bf16 v[0:3], v[154:157], v[190:193], v[0:3]
	v_mfma_f32_16x16x32_bf16 v[50:53], v[150:153], v[166:169], v[50:53]
	v_mfma_f32_16x16x32_bf16 v[42:45], v[158:161], v[166:169], v[42:45]
	v_mfma_f32_16x16x32_bf16 v[34:37], v[150:153], v[174:177], v[34:37]
	v_mfma_f32_16x16x32_bf16 v[26:29], v[158:161], v[174:177], v[26:29]
	v_mfma_f32_16x16x32_bf16 v[16:19], v[150:153], v[186:189], v[16:19]
	v_mfma_f32_16x16x32_bf16 v[8:11], v[158:161], v[186:189], v[8:11]
	v_mfma_f32_16x16x32_bf16 v[4:7], v[150:153], v[210:213], v[4:7]
	v_mfma_f32_16x16x32_bf16 v[0:3], v[158:161], v[210:213], v[0:3]
	s_setprio 0
	s_barrier
	s_add_i32 s60, s60, 2
	s_add_u32 s34, s34, 0x100
	s_addc_u32 s35, s35, 0
	s_cmp_gt_u32 s60, 21
	s_cbranch_scc1 .LBB0_963

; #define PG8_STAGE(bufoff, gbase, voff) do { _Pragma("unroll") for (int _i = 0; _i < 2; ++_i) \
;         __builtin_amdgcn_global_load_lds((const unsigned*)((const char*)(gbase) + (voff)[_i]), (PG8_LAS unsigned*)(lds + (bufoff) + ldsw + _i * 8192), 16, 0, 0); } while (0)
; #define PG8_WAIT_V(n) asm volatile("s_waitcnt vmcnt(" #n ")" ::: "memory")
; template <class Epi, class Sched, bool ALIGN_EPI = false, bool SP2 = false>
; __device__ __forceinline__ void gemm_phase(PG8_LAS unsigned char* lds, const Gemm g, const Sched& S, const Epi& E, const int tid_in) {
;     ...
;     const int tid = tid_l, wid = __builtin_amdgcn_readfirstlane(tid >> 6), lane = tid & 63, wr = wid >> 2, wc = wid & 3, fr = lane & 15, fq = lane >> 4;
;     const int K = g.K, nt = K / BK;
;     unsigned voffA[2], voffB[2];
; #pragma unroll
;     for (int i = 0; i < 2; ++i) { int R, C; stage_rc(tid * 16 + i * 8192, R, C); const int Rb = perm_row<Epi::PMODE>(R);
;         voffA[i] = (unsigned)(R * K + C) * 2u; voffB[i] = (unsigned)(Rb * K + C) * 2u; }
;     const size_t kstep = (size_t)(BK * 2);
;     const size_t hstep = (size_t)HALF * K * 2;
;     const size_t tstep = 2 * hstep;
;     const unsigned ldsw = (unsigned)wid * 1024u;
;     const int aoff = lds_byte(wr * 64 + fr, fq * 8), boff = lds_byte(wc * 32 + fr, fq * 8);
;     ...
;     Unit cur, nxt; int ui = 0;
;     if (!S.next(0, cur)) return;
;     f32x4 acc[2][2][4][2];
; #pragma unroll
;     for (int a = 0; a < 2; ++a)
; #pragma unroll
;         for (int b = 0; b < 2; ++b)
; #pragma unroll
;             for (int m = 0; m < 4; ++m)
; #pragma unroll
;                 for (int n = 0; n < 2; ++n) acc[a][b][m][n] = (f32x4){0.f, 0.f, 0.f, 0.f};
;     bf16x8 At[4][2], B0[2][2], B1[2][2];
;     const char* cA = (const char*)g.A + (size_t)cur.pm * tstep; const char* cB = (const char*)g.Bt + (size_t)cur.pn * tstep;
;     S.a_ready(cur);
;     if constexpr (Epi::PREF) E.prefetch(cur, 0, lds, wid, lane);
;     if constexpr (SP2) {
;         PG8_STAGE(PG8_SB(0, 0), cB, voffB); PG8_STAGE(PG8_SB(0, 1), cB + hstep, voffB); PG8_STAGE(PG8_SA(0, 0), cA, voffA); PG8_STAGE(PG8_SA(0, 1), cA + hstep, voffA);
;         if (wr == 1) PG8_BAR;
;         PG8_WAIT_V(2); PG8_BAR;
;         PG8_STAGE(PG8_SB(1, 0), cB + kstep, voffB); PG8_STAGE(PG8_SA(1, 0), cA + kstep, voffA); PG8_STAGE(PG8_SB(1, 1), cB + hstep + kstep, voffB);
;         PG8_WAIT_V(6); PG8_BAR;
.LBB0_1031:
	s_ashr_i32 s7, s6, 31
	s_lshl_b64 s[40:41], s[6:7], 26
	s_add_u32 s3, s36, s40
	s_addc_u32 s7, s37, s41
	s_add_u32 s42, s3, 0x53200000
	s_mul_i32 s3, s34, 3
	s_addc_u32 s43, s7, 0
	s_add_i32 s6, s3, s6
	s_bitcmp0_b32 s6, 0
	s_mov_b32 s7, 0x4f200000
	s_cselect_b32 s7, 0x28000000, s7
	s_add_u32 s44, s36, s7
	s_addc_u32 s45, s37, 0
	s_add_u32 s68, s36, 0x6a200000
	s_addc_u32 s69, s37, 0
	s_add_u32 s70, s36, 0x80000
	s_addc_u32 s71, s37, 0
	s_lshl_b32 s6, s6, 5
	s_add_i32 s72, s6, 32
	s_add_u32 s6, s36, 0x84000
	s_addc_u32 s7, s37, 0
	v_writelane_b32 v255, s6, 26
	v_and_b32_e32 v15, 48, v8
	v_lshlrev_b32_e32 v16, 6, v8
	v_writelane_b32 v255, s7, 27
	s_movk_i32 s7, 0x3c0
	v_lshlrev_b32_e32 v8, 2, v8
	s_and_b32 s34, s39, 3
	s_lshl_b32 s6, s35, 13
	v_and_or_b32 v15, v16, s7, v15
	v_and_b32_e32 v8, 32, v8
	s_add_i32 m0, s64, 0x18000
	v_lshl_add_u64 v[6:7], v[6:7], 0, s[12:13]
	s_lshl_b32 s73, s35, 6
	v_bitop3_b32 v16, v15, s6, v8 bitop3:0xde
	s_lshl_b32 s74, s34, 5
	s_lshl_b32 s6, s34, 12
	s_waitcnt vmcnt(2)
	s_barrier
	global_load_lds_dwordx4 v[6:7], off
	v_lshl_add_u64 v[4:5], v[4:5], 0, s[12:13]
	s_add_i32 m0, s64, 0x1a000
	s_add_i32 s75, s64, 0x8000
	s_add_i32 s76, s64, 0xa000
	v_bitop3_b32 v21, v15, s6, v8 bitop3:0xde
	global_load_lds_dwordx4 v[4:5], off
	v_lshl_add_u64 v[0:1], v[0:1], 0, s[12:13]
	s_mov_b32 m0, s75
	s_add_u32 s100, s28, 0x80
	s_addc_u32 s101, s29, 0
	s_add_u32 s6, s30, 0x80080
	global_load_lds_dwordx4 v[0:1], off
	v_lshl_add_u64 v[0:1], v[2:3], 0, s[12:13]
	s_mov_b32 m0, s76
	s_addc_u32 s7, s31, 0
	global_load_lds_dwordx4 v[0:1], off
	s_add_i32 m0, s64, 0x1c000
	v_lshl_add_u64 v[0:1], s[6:7], 0, v[204:205]
	global_load_lds_dwordx4 v[0:1], off
	v_lshl_add_u64 v[0:1], s[6:7], 0, v[216:217]
	s_add_i32 m0, s64, 0x1e000
	v_readlane_b32 s6, v254, 55
	global_load_lds_dwordx4 v[0:1], off
	s_mov_b32 s7, s6
	s_add_i32 s77, s6, s8
	s_lshl_b32 s6, s34, 7
	s_add_i32 s78, s7, s6
	s_cmpk_lt_u32 s38, 0x100
	s_cselect_b64 s[48:49], -1, 0
	s_cmp_lg_u32 s39, 1
	s_cselect_b64 s[50:51], -1, 0
	s_cmp_eq_u32 s39, 2
	s_movk_i32 s6, 0x2000
	s_cselect_b32 s6, s6, 0x1800
	s_lshl_b32 s7, s35, 2
	s_lshl_b32 s36, s34, 2
	s_add_i32 s79, s36, 0
	s_or_b32 s7, s7, s34
	v_lshlrev_b32_e32 v0, 15, v9
	s_add_i32 s79, s79, 0x24400
	s_lshl_b32 s80, s7, 6
	v_and_b32_e32 v0, 0xffff0000, v0
	s_cmp_lt_i32 s7, 4
	v_lshl_add_u32 v0, v10, 12, v0
	v_and_b32_e32 v1, 1, v9
	s_cselect_b64 s[52:53], -1, 0
	s_cmp_eq_u32 s7, 0
	v_lshl_or_b32 v0, v1, 6, v0
	s_cselect_b64 s[54:55], -1, 0
	s_lshl_b32 s7, s35, 8
	v_lshl_add_u32 v218, v11, 1, v0
	v_lshlrev_b32_e32 v0, 15, v12
	s_add_i32 s81, s7, 0
	v_and_b32_e32 v0, 0xffff0000, v0
	s_waitcnt vmcnt(6)
	s_add_i32 s81, s81, 0x25400
	v_lshl_add_u32 v0, v13, 12, v0
	v_and_b32_e32 v1, 1, v12
	s_cmp_gt_u32 s38, 63
	v_lshl_or_b32 v0, v1, 6, v0
	s_mov_b32 s3, 0
	s_cselect_b32 s83, s6, 0x1000
	v_mov_b32_e32 v219, v20
	v_lshl_add_u32 v220, v14, 1, v0
	v_mov_b32_e32 v221, v20
	v_add_u32_e32 v208, 0, v16
	s_barrier
	s_branch .LBB0_1034

; #define PG8_STAGE(bufoff, gbase, voff) do { _Pragma("unroll") for (int _i = 0; _i < 2; ++_i) \
;         __builtin_amdgcn_global_load_lds((const unsigned*)((const char*)(gbase) + (voff)[_i]), (PG8_LAS unsigned*)(lds + (bufoff) + ldsw + _i * 8192), 16, 0, 0); } while (0)
; #define PG8_LDA(dst, b, h) do { _Pragma("unroll") for (int m = 0; m < 4; ++m) _Pragma("unroll") for (int k = 0; k < 2; ++k) dst[m][k] = *(const PG8_LAS bf16x8*)(lds + PG8_SA(b, h) + aoff + m * 2048 + k * 1024); } while (0)
; #define PG8_LDB(dst, b, h) do { _Pragma("unroll") for (int n = 0; n < 2; ++n) _Pragma("unroll") for (int k = 0; k < 2; ++k) dst[n][k] = *(const PG8_LAS bf16x8*)(lds + PG8_SB(b, h) + boff + n * 2048 + k * 1024); } while (0)
; #define PG8_WAIT_V(n) asm volatile("s_waitcnt vmcnt(" #n ")" ::: "memory")
; #define PG8_WAIT_L(n) asm volatile("s_waitcnt lgkmcnt(" #n ")" ::: "memory")
; template <class Epi, class Sched, bool ALIGN_EPI = false, bool SP2 = false>
; __device__ __forceinline__ void gemm_phase(PG8_LAS unsigned char* lds, const Gemm g, const Sched& S, const Epi& E, const int tid_in) {
;     ...
;         const bool has_next = S.next(ui + 1, nxt);
;         const char* nA = has_next ? (const char*)g.A + (size_t)nxt.pm * tstep : cA; const char* nB = has_next ? (const char*)g.Bt + (size_t)nxt.pn * tstep : cB;
;         for (int t = 0; t < nt; t += 2) {
;             if constexpr (Epi::KSPLIT > 0) { if (t == Epi::KSPLIT / BK) E.midk(acc, cur, wr, wc, fr, fq); }
;             const bool last = (t == nt - 2);
;             const char* a1 = cA + (size_t)(t + 1) * kstep;
;             const char* a2 = last ? nA : cA + (size_t)(t + 2) * kstep; const char* b2 = last ? nB : cB + (size_t)(t + 2) * kstep;
;             const char* a3 = a2 + kstep; const char* b3 = b2 + kstep;
;             if (last && has_next) S.a_ready(nxt);
;             if constexpr (SP2) {
;             PG8_LDB(B0, 0, 0); PG8_LDB(B1, 0, 1); PG8_SCHED; PG8_LDA(At, 0, 0); PG8_STAGE(PG8_SA(1, 1), a1 + hstep, voffA);
;             PG8_WAIT_V(8); PG8_WAIT_L(0); PG8_BAR; PG8_MMA(0, 0, At, B0); PG8_MMA(0, 1, At, B1); PG8_BAR; PG8_SCHED;
;             PG8_LDA(At, 0, 1); PG8_STAGE(PG8_SB(0, 0), b2, voffB); PG8_STAGE(PG8_SB(0, 1), b2 + hstep, voffB); PG8_STAGE(PG8_SA(0, 0), a2, voffA);
;             PG8_WAIT_V(8); PG8_WAIT_L(0); PG8_BAR; PG8_MMA(1, 0, At, B0); PG8_MMA(1, 1, At, B1); PG8_BAR; PG8_SCHED;
.LBB0_1037:
	s_mov_b32 m0, s76
	s_nop 0
	global_load_lds_dwordx4 v214, s[100:101]
	s_add_u32 s30, s28, 0xfff80080
	s_addc_u32 s31, s29, -1
	s_add_i32 s46, 0, 0x10000
	s_cmp_eq_u32 vcc_lo, 28
	s_cselect_b32 s35, s38, s31
	s_cselect_b32 s34, s39, s30
	s_cselect_b32 s31, s40, s92
	s_cselect_b32 s30, s41, s57
	s_add_i32 vcc_hi, 0, 0x14000
	v_add_u32_e32 v142, s46, v21
	v_add_u32_e32 v158, vcc_hi, v21
	ds_read_b128 v[130:133], v142
	ds_read_b128 v[134:137], v142 offset:1024
	ds_read_b128 v[138:141], v142 offset:2048
	ds_read_b128 v[142:145], v142 offset:3072
	ds_read_b128 v[146:149], v158
	ds_read_b128 v[150:153], v158 offset:1024
	ds_read_b128 v[154:157], v158 offset:2048
	ds_read_b128 v[158:161], v158 offset:3072
	s_add_i32 m0, s64, 0xc000
	ds_read_b128 v[162:165], v208
	ds_read_b128 v[166:169], v208 offset:1024
	ds_read_b128 v[170:173], v208 offset:2048
	ds_read_b128 v[174:177], v208 offset:3072
	ds_read_b128 v[178:181], v208 offset:4096
	ds_read_b128 v[182:185], v208 offset:5120
	ds_read_b128 v[186:189], v208 offset:6144
	ds_read_b128 v[190:193], v208 offset:7168
	global_load_lds_dwordx4 v218, s[28:29]
	s_add_i32 m0, s64, 0xe000
	s_nop 0
	global_load_lds_dwordx4 v220, s[28:29]
	s_waitcnt vmcnt(8)
	s_waitcnt lgkmcnt(0)
	s_barrier
	s_setprio 1
	s_waitcnt lgkmcnt(0)
	v_mfma_f32_16x16x32_bf16 v[126:129], v[130:133], v[162:165], v[126:129]
	v_mfma_f32_16x16x32_bf16 v[122:125], v[138:141], v[162:165], v[122:125]
	v_mfma_f32_16x16x32_bf16 v[110:113], v[130:133], v[170:173], v[110:113]
	v_mfma_f32_16x16x32_bf16 v[106:109], v[138:141], v[170:173], v[106:109]
	v_mfma_f32_16x16x32_bf16 v[94:97], v[130:133], v[178:181], v[94:97]
	v_mfma_f32_16x16x32_bf16 v[90:93], v[138:141], v[178:181], v[90:93]
	v_mfma_f32_16x16x32_bf16 v[78:81], v[130:133], v[186:189], v[78:81]
	v_mfma_f32_16x16x32_bf16 v[74:77], v[138:141], v[186:189], v[74:77]
	v_mfma_f32_16x16x32_bf16 v[126:129], v[134:137], v[166:169], v[126:129]
	v_mfma_f32_16x16x32_bf16 v[122:125], v[142:145], v[166:169], v[122:125]
	v_mfma_f32_16x16x32_bf16 v[110:113], v[134:137], v[174:177], v[110:113]
	v_mfma_f32_16x16x32_bf16 v[106:109], v[142:145], v[174:177], v[106:109]
	v_mfma_f32_16x16x32_bf16 v[94:97], v[134:137], v[182:185], v[94:97]
	v_mfma_f32_16x16x32_bf16 v[90:93], v[142:145], v[182:185], v[90:93]
	v_mfma_f32_16x16x32_bf16 v[78:81], v[134:137], v[190:193], v[78:81]
	v_mfma_f32_16x16x32_bf16 v[74:77], v[142:145], v[190:193], v[74:77]
	s_setprio 0
	s_setprio 1
	v_mfma_f32_16x16x32_bf16 v[118:121], v[146:149], v[162:165], v[118:121]
	v_mfma_f32_16x16x32_bf16 v[114:117], v[154:157], v[162:165], v[114:117]
	v_mfma_f32_16x16x32_bf16 v[102:105], v[146:149], v[170:173], v[102:105]
	v_mfma_f32_16x16x32_bf16 v[98:101], v[154:157], v[170:173], v[98:101]
	v_mfma_f32_16x16x32_bf16 v[86:89], v[146:149], v[178:181], v[86:89]
	v_mfma_f32_16x16x32_bf16 v[82:85], v[154:157], v[178:181], v[82:85]
	v_mfma_f32_16x16x32_bf16 v[70:73], v[146:149], v[186:189], v[70:73]
	v_mfma_f32_16x16x32_bf16 v[66:69], v[154:157], v[186:189], v[66:69]
	v_mfma_f32_16x16x32_bf16 v[118:121], v[150:153], v[166:169], v[118:121]
	v_mfma_f32_16x16x32_bf16 v[114:117], v[158:161], v[166:169], v[114:117]
	v_mfma_f32_16x16x32_bf16 v[102:105], v[150:153], v[174:177], v[102:105]
	v_mfma_f32_16x16x32_bf16 v[98:101], v[158:161], v[174:177], v[98:101]
	v_mfma_f32_16x16x32_bf16 v[86:89], v[150:153], v[182:185], v[86:89]
	v_mfma_f32_16x16x32_bf16 v[82:85], v[158:161], v[182:185], v[82:85]
	v_mfma_f32_16x16x32_bf16 v[70:73], v[150:153], v[190:193], v[70:73]
	v_mfma_f32_16x16x32_bf16 v[66:69], v[158:161], v[190:193], v[66:69]
	s_setprio 0
	s_barrier
	s_add_i32 s46, s46, s8
	s_add_u32 s98, s30, 0x80
	s_addc_u32 s99, s31, 0
	s_mov_b32 m0, s46
	ds_read_b128 v[162:165], v208 offset:16384
	ds_read_b128 v[166:169], v208 offset:17408
	ds_read_b128 v[170:173], v208 offset:18432
	ds_read_b128 v[174:177], v208 offset:19456
	ds_read_b128 v[178:181], v208 offset:20480
	ds_read_b128 v[182:185], v208 offset:21504
	ds_read_b128 v[186:189], v208 offset:22528
	ds_read_b128 v[190:193], v208 offset:23552
	global_load_lds_dwordx4 v204, s[30:31]
	s_add_i32 m0, s46, 0x2000
	s_add_u32 s46, s30, 0x80000
	s_addc_u32 s47, s31, 0
	s_add_i32 vcc_hi, vcc_hi, s8
	global_load_lds_dwordx4 v216, s[30:31]
	s_mov_b32 m0, vcc_hi
	s_add_u32 s100, s34, 0x80
	s_addc_u32 s101, s35, 0
	global_load_lds_dwordx4 v204, s[46:47]
	s_add_i32 m0, vcc_hi, 0x2000
	s_nop 0
	global_load_lds_dwordx4 v216, s[46:47]
	s_mov_b32 m0, s64
	s_nop 0
	global_load_lds_dwordx4 v202, s[34:35]
	s_waitcnt vmcnt(7)
	s_waitcnt lgkmcnt(0)
	s_barrier
; #define PG8_STAGE(bufoff, gbase, voff) do { _Pragma("unroll") for (int _i = 0; _i < 2; ++_i) \
;         __builtin_amdgcn_global_load_lds((const unsigned*)((const char*)(gbase) + (voff)[_i]), (PG8_LAS unsigned*)(lds + (bufoff) + ldsw + _i * 8192), 16, 0, 0); } while (0)
; #define PG8_LDA(dst, b, h) do { _Pragma("unroll") for (int m = 0; m < 4; ++m) _Pragma("unroll") for (int k = 0; k < 2; ++k) dst[m][k] = *(const PG8_LAS bf16x8*)(lds + PG8_SA(b, h) + aoff + m * 2048 + k * 1024); } while (0)
; #define PG8_LDB(dst, b, h) do { _Pragma("unroll") for (int n = 0; n < 2; ++n) _Pragma("unroll") for (int k = 0; k < 2; ++k) dst[n][k] = *(const PG8_LAS bf16x8*)(lds + PG8_SB(b, h) + boff + n * 2048 + k * 1024); } while (0)
; #define PG8_MMA(ai, bj, At, Bt) do { __builtin_amdgcn_s_setprio(1); _Pragma("unroll") for (int m = 0; m < 4; ++m) _Pragma("unroll") for (int n = 0; n < 2; ++n) _Pragma("unroll") for (int k = 0; k < 2; ++k) \
;         acc[ai][bj][m][n] = __builtin_amdgcn_mfma_f32_16x16x32_bf16(Bt[n][k], At[m][k], acc[ai][bj][m][n], 0, 0, 0); __builtin_amdgcn_s_setprio(0); } while (0)
; #define PG8_WAIT_V(n) asm volatile("s_waitcnt vmcnt(" #n ")" ::: "memory")
; #define PG8_WAIT_L(n) asm volatile("s_waitcnt lgkmcnt(" #n ")" ::: "memory")
; #define PG8_BAR __builtin_amdgcn_s_barrier()
; #define PG8_SCHED __builtin_amdgcn_sched_barrier(0)
; template <class Epi, class Sched, bool ALIGN_EPI = false, bool SP2 = false>
; __device__ __forceinline__ void gemm_phase(PG8_LAS unsigned char* lds, const Gemm g, const Sched& S, const Epi& E, const int tid_in) {
;     ...
;             PG8_WAIT_V(8); PG8_WAIT_L(0); PG8_BAR; PG8_MMA(1, 0, At, B0); PG8_MMA(1, 1, At, B1); PG8_BAR; PG8_SCHED;
;             PG8_LDB(B0, 1, 0); PG8_LDB(B1, 1, 1); PG8_SCHED; PG8_LDA(At, 1, 0); PG8_STAGE(PG8_SA(0, 1), a2 + hstep, voffA);
;             PG8_WAIT_V(8); PG8_WAIT_L(0); PG8_BAR; PG8_MMA(0, 0, At, B0); PG8_MMA(0, 1, At, B1); PG8_BAR; PG8_SCHED;
	s_setprio 1
	s_waitcnt lgkmcnt(0)
	v_mfma_f32_16x16x32_bf16 v[62:65], v[130:133], v[162:165], v[62:65]
	v_mfma_f32_16x16x32_bf16 v[58:61], v[138:141], v[162:165], v[58:61]
	v_mfma_f32_16x16x32_bf16 v[46:49], v[130:133], v[170:173], v[46:49]
	v_mfma_f32_16x16x32_bf16 v[42:45], v[138:141], v[170:173], v[42:45]
	v_mfma_f32_16x16x32_bf16 v[30:33], v[130:133], v[178:181], v[30:33]
	v_mfma_f32_16x16x32_bf16 v[26:29], v[138:141], v[178:181], v[26:29]
	v_mfma_f32_16x16x32_bf16 v[12:15], v[130:133], v[186:189], v[12:15]
	v_mfma_f32_16x16x32_bf16 v[8:11], v[138:141], v[186:189], v[8:11]
	v_mfma_f32_16x16x32_bf16 v[62:65], v[134:137], v[166:169], v[62:65]
	v_mfma_f32_16x16x32_bf16 v[58:61], v[142:145], v[166:169], v[58:61]
	v_mfma_f32_16x16x32_bf16 v[46:49], v[134:137], v[174:177], v[46:49]
	v_mfma_f32_16x16x32_bf16 v[42:45], v[142:145], v[174:177], v[42:45]
	v_mfma_f32_16x16x32_bf16 v[30:33], v[134:137], v[182:185], v[30:33]
	v_mfma_f32_16x16x32_bf16 v[26:29], v[142:145], v[182:185], v[26:29]
	v_mfma_f32_16x16x32_bf16 v[12:15], v[134:137], v[190:193], v[12:15]
	v_mfma_f32_16x16x32_bf16 v[8:11], v[142:145], v[190:193], v[8:11]
	s_setprio 0
	s_setprio 1
	v_mfma_f32_16x16x32_bf16 v[54:57], v[146:149], v[162:165], v[54:57]
	v_mfma_f32_16x16x32_bf16 v[50:53], v[154:157], v[162:165], v[50:53]
	v_mfma_f32_16x16x32_bf16 v[38:41], v[146:149], v[170:173], v[38:41]
	v_mfma_f32_16x16x32_bf16 v[34:37], v[154:157], v[170:173], v[34:37]
	v_mfma_f32_16x16x32_bf16 v[22:25], v[146:149], v[178:181], v[22:25]
	v_mfma_f32_16x16x32_bf16 v[16:19], v[154:157], v[178:181], v[16:19]
	v_mfma_f32_16x16x32_bf16 v[4:7], v[146:149], v[186:189], v[4:7]
	v_mfma_f32_16x16x32_bf16 v[0:3], v[154:157], v[186:189], v[0:3]
	v_mfma_f32_16x16x32_bf16 v[54:57], v[150:153], v[166:169], v[54:57]
	v_mfma_f32_16x16x32_bf16 v[50:53], v[158:161], v[166:169], v[50:53]
	v_mfma_f32_16x16x32_bf16 v[38:41], v[150:153], v[174:177], v[38:41]
	v_mfma_f32_16x16x32_bf16 v[34:37], v[158:161], v[174:177], v[34:37]
	v_mfma_f32_16x16x32_bf16 v[22:25], v[150:153], v[182:185], v[22:25]
	v_mfma_f32_16x16x32_bf16 v[16:19], v[158:161], v[182:185], v[16:19]
	v_mfma_f32_16x16x32_bf16 v[4:7], v[150:153], v[190:193], v[4:7]
	v_mfma_f32_16x16x32_bf16 v[0:3], v[158:161], v[190:193], v[0:3]
	s_setprio 0
	s_barrier
	s_add_i32 s46, 0, 0x18000
	s_add_i32 s47, 0, 0x1c000
	v_add_u32_e32 v142, s46, v21
	v_add_u32_e32 v158, s47, v21
	ds_read_b128 v[130:133], v142
	ds_read_b128 v[134:137], v142 offset:1024
	ds_read_b128 v[138:141], v142 offset:2048
	ds_read_b128 v[142:145], v142 offset:3072
	ds_read_b128 v[146:149], v158
	ds_read_b128 v[150:153], v158 offset:1024
	ds_read_b128 v[154:157], v158 offset:2048
	ds_read_b128 v[158:161], v158 offset:3072
	s_mov_b32 m0, s65
	s_nop 0
	global_load_lds_dwordx4 v214, s[34:35]
	s_add_u32 s34, s34, 0x80000
	s_addc_u32 s35, s35, 0
	s_mov_b32 m0, s66
	ds_read_b128 v[162:165], v208 offset:32768
	ds_read_b128 v[166:169], v208 offset:33792
	ds_read_b128 v[170:173], v208 offset:34816
	ds_read_b128 v[174:177], v208 offset:35840
	ds_read_b128 v[178:181], v208 offset:36864
	ds_read_b128 v[182:185], v208 offset:37888
	ds_read_b128 v[186:189], v208 offset:38912
	ds_read_b128 v[190:193], v208 offset:39936
	global_load_lds_dwordx4 v202, s[34:35]
	s_mov_b32 m0, s67
	s_nop 0
	global_load_lds_dwordx4 v214, s[34:35]
	s_waitcnt vmcnt(8)
	s_waitcnt lgkmcnt(0)
	s_barrier
	s_setprio 1
	s_waitcnt lgkmcnt(0)
	v_mfma_f32_16x16x32_bf16 v[126:129], v[130:133], v[162:165], v[126:129]
	v_mfma_f32_16x16x32_bf16 v[122:125], v[138:141], v[162:165], v[122:125]
	v_mfma_f32_16x16x32_bf16 v[110:113], v[130:133], v[170:173], v[110:113]
	v_mfma_f32_16x16x32_bf16 v[106:109], v[138:141], v[170:173], v[106:109]
	v_mfma_f32_16x16x32_bf16 v[94:97], v[130:133], v[178:181], v[94:97]
	v_mfma_f32_16x16x32_bf16 v[90:93], v[138:141], v[178:181], v[90:93]
	v_mfma_f32_16x16x32_bf16 v[78:81], v[130:133], v[186:189], v[78:81]
	v_mfma_f32_16x16x32_bf16 v[74:77], v[138:141], v[186:189], v[74:77]
	v_mfma_f32_16x16x32_bf16 v[126:129], v[134:137], v[166:169], v[126:129]
	v_mfma_f32_16x16x32_bf16 v[122:125], v[142:145], v[166:169], v[122:125]
	v_mfma_f32_16x16x32_bf16 v[110:113], v[134:137], v[174:177], v[110:113]
	v_mfma_f32_16x16x32_bf16 v[106:109], v[142:145], v[174:177], v[106:109]
	v_mfma_f32_16x16x32_bf16 v[94:97], v[134:137], v[182:185], v[94:97]
	v_mfma_f32_16x16x32_bf16 v[90:93], v[142:145], v[182:185], v[90:93]
	v_mfma_f32_16x16x32_bf16 v[78:81], v[134:137], v[190:193], v[78:81]
	v_mfma_f32_16x16x32_bf16 v[74:77], v[142:145], v[190:193], v[74:77]
	s_setprio 0
	s_setprio 1
	v_mfma_f32_16x16x32_bf16 v[118:121], v[146:149], v[162:165], v[118:121]
	v_mfma_f32_16x16x32_bf16 v[114:117], v[154:157], v[162:165], v[114:117]
	v_mfma_f32_16x16x32_bf16 v[102:105], v[146:149], v[170:173], v[102:105]
	v_mfma_f32_16x16x32_bf16 v[98:101], v[154:157], v[170:173], v[98:101]
	v_mfma_f32_16x16x32_bf16 v[86:89], v[146:149], v[178:181], v[86:89]
	v_mfma_f32_16x16x32_bf16 v[82:85], v[154:157], v[178:181], v[82:85]
	v_mfma_f32_16x16x32_bf16 v[70:73], v[146:149], v[186:189], v[70:73]
	v_mfma_f32_16x16x32_bf16 v[66:69], v[154:157], v[186:189], v[66:69]
	v_mfma_f32_16x16x32_bf16 v[118:121], v[150:153], v[166:169], v[118:121]
	v_mfma_f32_16x16x32_bf16 v[114:117], v[158:161], v[166:169], v[114:117]
	v_mfma_f32_16x16x32_bf16 v[102:105], v[150:153], v[174:177], v[102:105]
	v_mfma_f32_16x16x32_bf16 v[98:101], v[158:161], v[174:177], v[98:101]
	v_mfma_f32_16x16x32_bf16 v[86:89], v[150:153], v[182:185], v[86:89]
	v_mfma_f32_16x16x32_bf16 v[82:85], v[158:161], v[182:185], v[82:85]
	v_mfma_f32_16x16x32_bf16 v[70:73], v[150:153], v[190:193], v[70:73]
	v_mfma_f32_16x16x32_bf16 v[66:69], v[158:161], v[190:193], v[66:69]
	s_setprio 0
	s_barrier
; #define PG8_STAGE(bufoff, gbase, voff) do { _Pragma("unroll") for (int _i = 0; _i < 2; ++_i) \
;         __builtin_amdgcn_global_load_lds((const unsigned*)((const char*)(gbase) + (voff)[_i]), (PG8_LAS unsigned*)(lds + (bufoff) + ldsw + _i * 8192), 16, 0, 0); } while (0)
; #define PG8_LDA(dst, b, h) do { _Pragma("unroll") for (int m = 0; m < 4; ++m) _Pragma("unroll") for (int k = 0; k < 2; ++k) dst[m][k] = *(const PG8_LAS bf16x8*)(lds + PG8_SA(b, h) + aoff + m * 2048 + k * 1024); } while (0)
; #define PG8_MMA(ai, bj, At, Bt) do { __builtin_amdgcn_s_setprio(1); _Pragma("unroll") for (int m = 0; m < 4; ++m) _Pragma("unroll") for (int n = 0; n < 2; ++n) _Pragma("unroll") for (int k = 0; k < 2; ++k) \
;         acc[ai][bj][m][n] = __builtin_amdgcn_mfma_f32_16x16x32_bf16(Bt[n][k], At[m][k], acc[ai][bj][m][n], 0, 0, 0); __builtin_amdgcn_s_setprio(0); } while (0)
; #define PG8_WAIT_V(n) asm volatile("s_waitcnt vmcnt(" #n ")" ::: "memory")
; #define PG8_WAIT_L(n) asm volatile("s_waitcnt lgkmcnt(" #n ")" ::: "memory")
; #define PG8_BAR __builtin_amdgcn_s_barrier()
; #define PG8_SCHED __builtin_amdgcn_sched_barrier(0)
; template <class Epi, class Sched, bool ALIGN_EPI = false, bool SP2 = false>
; __device__ __forceinline__ void gemm_phase(PG8_LAS unsigned char* lds, const Gemm g, const Sched& S, const Epi& E, const int tid_in) {
;     ...
;             PG8_LDA(At, 1, 1); PG8_STAGE(PG8_SB(1, 0), b3, voffB); PG8_STAGE(PG8_SB(1, 1), b3 + hstep, voffB); PG8_STAGE(PG8_SA(1, 0), a3, voffA);
;             PG8_WAIT_V(8); PG8_WAIT_L(0); PG8_BAR; PG8_MMA(1, 0, At, B0); PG8_MMA(1, 1, At, B1); PG8_BAR; PG8_SCHED;
	s_add_i32 s34, s46, s8
	s_mov_b32 m0, s34
	ds_read_b128 v[162:165], v208 offset:49152
	ds_read_b128 v[166:169], v208 offset:50176
	ds_read_b128 v[170:173], v208 offset:51200
	ds_read_b128 v[174:177], v208 offset:52224
	ds_read_b128 v[178:181], v208 offset:53248
	ds_read_b128 v[182:185], v208 offset:54272
	ds_read_b128 v[186:189], v208 offset:55296
	ds_read_b128 v[190:193], v208 offset:56320
	global_load_lds_dwordx4 v204, s[98:99]
	s_add_i32 m0, s34, 0x2000
	s_add_u32 s30, s30, 0x80080
	s_addc_u32 s31, s31, 0
	s_add_i32 s34, s47, s8
	global_load_lds_dwordx4 v216, s[98:99]
	s_mov_b32 m0, s34
	s_nop 0
	global_load_lds_dwordx4 v204, s[30:31]
	s_add_i32 m0, s34, 0x2000
	s_nop 0
	global_load_lds_dwordx4 v216, s[30:31]
	s_mov_b32 m0, s75
	s_nop 0
	global_load_lds_dwordx4 v202, s[100:101]
	s_waitcnt vmcnt(7)
	s_waitcnt lgkmcnt(0)
	s_barrier
	s_setprio 1
	s_waitcnt lgkmcnt(0)
	v_mfma_f32_16x16x32_bf16 v[62:65], v[130:133], v[162:165], v[62:65]
	v_mfma_f32_16x16x32_bf16 v[58:61], v[138:141], v[162:165], v[58:61]
	v_mfma_f32_16x16x32_bf16 v[46:49], v[130:133], v[170:173], v[46:49]
	v_mfma_f32_16x16x32_bf16 v[42:45], v[138:141], v[170:173], v[42:45]
	v_mfma_f32_16x16x32_bf16 v[30:33], v[130:133], v[178:181], v[30:33]
	v_mfma_f32_16x16x32_bf16 v[26:29], v[138:141], v[178:181], v[26:29]
	v_mfma_f32_16x16x32_bf16 v[12:15], v[130:133], v[186:189], v[12:15]
	v_mfma_f32_16x16x32_bf16 v[8:11], v[138:141], v[186:189], v[8:11]
	v_mfma_f32_16x16x32_bf16 v[62:65], v[134:137], v[166:169], v[62:65]
	v_mfma_f32_16x16x32_bf16 v[58:61], v[142:145], v[166:169], v[58:61]
	v_mfma_f32_16x16x32_bf16 v[46:49], v[134:137], v[174:177], v[46:49]
	v_mfma_f32_16x16x32_bf16 v[42:45], v[142:145], v[174:177], v[42:45]
	v_mfma_f32_16x16x32_bf16 v[30:33], v[134:137], v[182:185], v[30:33]
	v_mfma_f32_16x16x32_bf16 v[26:29], v[142:145], v[182:185], v[26:29]
	v_mfma_f32_16x16x32_bf16 v[12:15], v[134:137], v[190:193], v[12:15]
	v_mfma_f32_16x16x32_bf16 v[8:11], v[142:145], v[190:193], v[8:11]
	s_setprio 0
	s_setprio 1
	v_mfma_f32_16x16x32_bf16 v[54:57], v[146:149], v[162:165], v[54:57]
	v_mfma_f32_16x16x32_bf16 v[50:53], v[154:157], v[162:165], v[50:53]
	v_mfma_f32_16x16x32_bf16 v[38:41], v[146:149], v[170:173], v[38:41]
	v_mfma_f32_16x16x32_bf16 v[34:37], v[154:157], v[170:173], v[34:37]
	v_mfma_f32_16x16x32_bf16 v[22:25], v[146:149], v[178:181], v[22:25]
	v_mfma_f32_16x16x32_bf16 v[16:19], v[154:157], v[178:181], v[16:19]
	v_mfma_f32_16x16x32_bf16 v[4:7], v[146:149], v[186:189], v[4:7]
	v_mfma_f32_16x16x32_bf16 v[0:3], v[154:157], v[186:189], v[0:3]
	v_mfma_f32_16x16x32_bf16 v[54:57], v[150:153], v[166:169], v[54:57]
	v_mfma_f32_16x16x32_bf16 v[50:53], v[158:161], v[166:169], v[50:53]
	v_mfma_f32_16x16x32_bf16 v[38:41], v[150:153], v[174:177], v[38:41]
	v_mfma_f32_16x16x32_bf16 v[34:37], v[158:161], v[174:177], v[34:37]
	v_mfma_f32_16x16x32_bf16 v[22:25], v[150:153], v[182:185], v[22:25]
	v_mfma_f32_16x16x32_bf16 v[16:19], v[158:161], v[182:185], v[16:19]
	v_mfma_f32_16x16x32_bf16 v[4:7], v[150:153], v[190:193], v[4:7]
	v_mfma_f32_16x16x32_bf16 v[0:3], v[158:161], v[190:193], v[0:3]
	s_setprio 0
	s_barrier
	s_add_i32 vcc_lo, vcc_lo, 2
	s_add_u32 s28, s28, 0x100
	s_addc_u32 s29, s29, 0
	s_add_u32 s57, s57, 0x100
	s_addc_u32 s92, s92, 0
	s_cmp_gt_u32 vcc_lo, 29
	s_cbranch_scc0 .LBB0_1037
	s_and_b64 vcc, exec, s[48:49]
	s_cbranch_vccz .LBB0_1040
	s_barrier

; #define PG8_STAGE(bufoff, gbase, voff) do { _Pragma("unroll") for (int _i = 0; _i < 2; ++_i) \
;         __builtin_amdgcn_global_load_lds((const unsigned*)((const char*)(gbase) + (voff)[_i]), (PG8_LAS unsigned*)(lds + (bufoff) + ldsw + _i * 8192), 16, 0, 0); } while (0)
; #define PG8_WAIT_V(n) asm volatile("s_waitcnt vmcnt(" #n ")" ::: "memory")
; template <class Epi, class Sched, bool ALIGN_EPI = false, bool SP2 = false>
; __device__ __forceinline__ void gemm_phase(PG8_LAS unsigned char* lds, const Gemm g, const Sched& S, const Epi& E, const int tid_in) {
;     ...
;     const int tid = tid_l, wid = __builtin_amdgcn_readfirstlane(tid >> 6), lane = tid & 63, wr = wid >> 2, wc = wid & 3, fr = lane & 15, fq = lane >> 4;
;     const int K = g.K, nt = K / BK;
;     unsigned voffA[2], voffB[2];
; #pragma unroll
;     for (int i = 0; i < 2; ++i) { int R, C; stage_rc(tid * 16 + i * 8192, R, C); const int Rb = perm_row<Epi::PMODE>(R);
;         voffA[i] = (unsigned)(R * K + C) * 2u; voffB[i] = (unsigned)(Rb * K + C) * 2u; }
;     const size_t kstep = (size_t)(BK * 2);
;     const size_t hstep = (size_t)HALF * K * 2;
;     const size_t tstep = 2 * hstep;
;     const unsigned ldsw = (unsigned)wid * 1024u;
;     const int aoff = lds_byte(wr * 64 + fr, fq * 8), boff = lds_byte(wc * 32 + fr, fq * 8);
;     ...
;     Unit cur, nxt; int ui = 0;
;     if (!S.next(0, cur)) return;
;     f32x4 acc[2][2][4][2];
; #pragma unroll
;     for (int a = 0; a < 2; ++a)
; #pragma unroll
;         for (int b = 0; b < 2; ++b)
; #pragma unroll
;             for (int m = 0; m < 4; ++m)
; #pragma unroll
;                 for (int n = 0; n < 2; ++n) acc[a][b][m][n] = (f32x4){0.f, 0.f, 0.f, 0.f};
;     bf16x8 At[4][2], B0[2][2], B1[2][2];
;     const char* cA = (const char*)g.A + (size_t)cur.pm * tstep; const char* cB = (const char*)g.Bt + (size_t)cur.pn * tstep;
;     S.a_ready(cur);
;     if constexpr (Epi::PREF) E.prefetch(cur, 0, lds, wid, lane);
;     if constexpr (SP2) {
;         PG8_STAGE(PG8_SB(0, 0), cB, voffB); PG8_STAGE(PG8_SB(0, 1), cB + hstep, voffB); PG8_STAGE(PG8_SA(0, 0), cA, voffA); PG8_STAGE(PG8_SA(0, 1), cA + hstep, voffA);
;         if (wr == 1) PG8_BAR;
;         PG8_WAIT_V(2); PG8_BAR;
;         PG8_STAGE(PG8_SB(1, 0), cB + kstep, voffB); PG8_STAGE(PG8_SA(1, 0), cA + kstep, voffA); PG8_STAGE(PG8_SB(1, 1), cB + hstep + kstep, voffB);
;         PG8_WAIT_V(6); PG8_BAR;
.LBB0_1151:
	s_add_u32 s26, s20, 0x5f200000
	s_addc_u32 s27, s21, 0
	s_add_u32 s36, s20, 0x35000000
	s_addc_u32 s37, s21, 0
	s_lshl_b32 s20, s24, 5
	s_and_b32 s31, s20, 0x60
	s_add_i32 m0, s89, 0x18000
	v_lshl_add_u64 v[6:7], v[6:7], 0, s[12:13]
	s_lshl_b32 s28, s83, 13
	s_lshl_b32 s29, s31, 7
	s_waitcnt vmcnt(2)
	s_barrier
	global_load_lds_dwordx4 v[6:7], off
	v_lshl_add_u64 v[4:5], v[4:5], 0, s[12:13]
	s_add_i32 m0, s89, 0x1a000
	s_add_i32 s24, s89, 0x8000
	s_add_i32 s25, s89, 0xa000
	global_load_lds_dwordx4 v[4:5], off
	v_lshl_add_u64 v[2:3], v[2:3], 0, s[12:13]
	s_mov_b32 m0, s24
	s_add_u32 s100, s50, 0x80
	s_addc_u32 s101, s51, 0
	s_add_u32 s20, s52, 0x80080
	global_load_lds_dwordx4 v[2:3], off
	v_lshl_add_u64 v[2:3], v[8:9], 0, s[12:13]
	s_mov_b32 m0, s25
	s_addc_u32 s21, s53, 0
	global_load_lds_dwordx4 v[2:3], off
	s_add_i32 m0, s89, 0x1c000
	v_lshl_add_u64 v[2:3], s[20:21], 0, v[164:165]
	global_load_lds_dwordx4 v[2:3], off
	v_lshl_add_u64 v[2:3], s[20:21], 0, v[168:169]
	s_add_i32 m0, s89, 0x1e000
	v_readlane_b32 s20, v254, 55
	global_load_lds_dwordx4 v[2:3], off
	v_lshrrev_b32_e32 v1, 1, v10
	s_mov_b32 s21, s20
	s_add_i32 s20, s20, s1
	v_and_b32_e32 v4, 24, v1
	v_writelane_b32 v255, s20, 20
	s_lshl_b32 s20, s31, 2
	v_and_b32_e32 v21, 15, v10
	v_lshlrev_b32_e32 v1, 1, v4
	v_lshlrev_b32_e32 v2, 2, v10
	s_add_i32 s20, s21, s20
	v_lshl_or_b32 v1, v21, 6, v1
	v_and_b32_e32 v2, 32, v2
	v_lshl_add_u32 v179, v4, 2, s20
	s_movk_i32 s20, 0x1600
	v_bitop3_b32 v5, v1, s28, v2 bitop3:0xde
	v_bitop3_b32 v177, v1, s29, v2 bitop3:0xde
	v_mul_lo_u32 v2, v11, s20
	v_ashrrev_i32_e32 v3, 31, v2
	v_lshl_add_u64 v[2:3], v[2:3], 2, s[6:7]
	v_mov_b32_e32 v1, s30
	v_cmp_gt_i32_e32 vcc, 3, v11
	s_waitcnt vmcnt(6)
	s_cmpk_lt_u32 s23, 0x100
	v_cmp_eq_u32_e64 s[42:43], 15, v21
	v_cndmask_b32_e32 v3, v1, v3, vcc
	v_mov_b32_e32 v1, s22
	v_cndmask_b32_e32 v2, v1, v2, vcc
	v_mov_b32_e32 v1, v20
	v_lshl_add_u64 v[182:183], v[2:3], 0, v[0:1]
	v_lshlrev_b32_e32 v0, 15, v12
	v_and_b32_e32 v0, 0xffff0000, v0
	v_lshl_add_u32 v0, v13, 12, v0
	v_and_b32_e32 v1, 1, v12
	v_lshl_or_b32 v0, v1, 6, v0
	v_lshl_add_u32 v184, v14, 1, v0
	v_lshlrev_b32_e32 v0, 15, v15
	v_and_b32_e32 v0, 0xffff0000, v0
	v_lshl_add_u32 v0, v16, 12, v0
	v_and_b32_e32 v1, 1, v15
	v_cmp_ne_u32_e64 s[44:45], 0, v21
	v_lshl_or_b32 v0, v1, 6, v0
	v_readlane_b32 s6, v254, 4
	v_lshl_or_b32 v175, s83, 6, v21
	s_cselect_b64 s[28:29], -1, 0
	s_mov_b32 s23, 0
	v_cmp_gt_u32_e64 s[38:39], 2, v21
	v_cmp_lt_u32_e64 s[40:41], 13, v21
	v_add_u32_e32 v181, -12, v21
	v_cndmask_b32_e64 v170, 0, 1, s[42:43]
	v_mov_b32_e32 v171, s93
	v_cndmask_b32_e64 v172, 0, 1, s[44:45]
	v_mov_b32_e32 v173, s93
	v_cndmask_b32_e64 v174, 1, 2, s[42:43]
	v_cndmask_b32_e64 v176, 1, 2, s[44:45]
	v_cndmask_b32_e64 v178, 2, 3, s[42:43]
	v_cndmask_b32_e64 v180, 2, 3, s[44:45]
	v_or_b32_e32 v192, s31, v4
	v_mov_b32_e32 v185, v20
	v_lshl_add_u32 v186, v17, 1, v0
	v_mov_b32_e32 v187, v20
	v_add_u32_e32 v193, 0, v5
	v_readlane_b32 s57, v254, 10
	s_mov_b32 s56, s6
	s_barrier
	v_readlane_b32 s7, v254, 5
	s_branch .LBB0_1154

; #define PG8_STAGE(bufoff, gbase, voff) do { _Pragma("unroll") for (int _i = 0; _i < 2; ++_i) \
;         __builtin_amdgcn_global_load_lds((const unsigned*)((const char*)(gbase) + (voff)[_i]), (PG8_LAS unsigned*)(lds + (bufoff) + ldsw + _i * 8192), 16, 0, 0); } while (0)
; #define PG8_LDA(dst, b, h) do { _Pragma("unroll") for (int m = 0; m < 4; ++m) _Pragma("unroll") for (int k = 0; k < 2; ++k) dst[m][k] = *(const PG8_LAS bf16x8*)(lds + PG8_SA(b, h) + aoff + m * 2048 + k * 1024); } while (0)
; #define PG8_LDB(dst, b, h) do { _Pragma("unroll") for (int n = 0; n < 2; ++n) _Pragma("unroll") for (int k = 0; k < 2; ++k) dst[n][k] = *(const PG8_LAS bf16x8*)(lds + PG8_SB(b, h) + boff + n * 2048 + k * 1024); } while (0)
; #define PG8_WAIT_V(n) asm volatile("s_waitcnt vmcnt(" #n ")" ::: "memory")
; #define PG8_WAIT_L(n) asm volatile("s_waitcnt lgkmcnt(" #n ")" ::: "memory")
; template <class Epi, class Sched, bool ALIGN_EPI = false, bool SP2 = false>
; __device__ __forceinline__ void gemm_phase(PG8_LAS unsigned char* lds, const Gemm g, const Sched& S, const Epi& E, const int tid_in) {
;     ...
;         const bool has_next = S.next(ui + 1, nxt);
;         const char* nA = has_next ? (const char*)g.A + (size_t)nxt.pm * tstep : cA; const char* nB = has_next ? (const char*)g.Bt + (size_t)nxt.pn * tstep : cB;
;         for (int t = 0; t < nt; t += 2) {
;             if constexpr (Epi::KSPLIT > 0) { if (t == Epi::KSPLIT / BK) E.midk(acc, cur, wr, wc, fr, fq); }
;             const bool last = (t == nt - 2);
;             const char* a1 = cA + (size_t)(t + 1) * kstep;
;             const char* a2 = last ? nA : cA + (size_t)(t + 2) * kstep; const char* b2 = last ? nB : cB + (size_t)(t + 2) * kstep;
;             const char* a3 = a2 + kstep; const char* b3 = b2 + kstep;
;             if (last && has_next) S.a_ready(nxt);
;             if constexpr (SP2) {
;             PG8_LDB(B0, 0, 0); PG8_LDB(B1, 0, 1); PG8_SCHED; PG8_LDA(At, 0, 0); PG8_STAGE(PG8_SA(1, 1), a1 + hstep, voffA);
;             PG8_WAIT_V(8); PG8_WAIT_L(0); PG8_BAR; PG8_MMA(0, 0, At, B0); PG8_MMA(0, 1, At, B1); PG8_BAR; PG8_SCHED;
;             PG8_LDA(At, 0, 1); PG8_STAGE(PG8_SB(0, 0), b2, voffB); PG8_STAGE(PG8_SB(0, 1), b2 + hstep, voffB); PG8_STAGE(PG8_SA(0, 0), a2, voffA);
;             PG8_WAIT_V(8); PG8_WAIT_L(0); PG8_BAR; PG8_MMA(1, 0, At, B0); PG8_MMA(1, 1, At, B1); PG8_BAR; PG8_SCHED;
.LBB0_1157:
	s_mov_b32 m0, s25
	s_nop 0
	global_load_lds_dwordx4 v166, s[100:101]
	s_add_u32 s52, s50, 0xfff80080
	s_addc_u32 s53, s51, -1
	s_add_i32 s63, 0, 0x10000
	s_cmp_eq_u32 s62, 28
	s_cselect_b32 s55, s35, s53
	s_cselect_b32 s54, s58, s52
	s_cselect_b32 s53, s31, s61
	s_cselect_b32 s52, s59, s60
	s_add_i32 s66, 0, 0x14000
	v_add_u32_e32 v78, s63, v177
	v_add_u32_e32 v134, s66, v177
	ds_read_b128 v[66:69], v78
	ds_read_b128 v[70:73], v78 offset:1024
	ds_read_b128 v[74:77], v78 offset:2048
	ds_read_b128 v[78:81], v78 offset:3072
	ds_read_b128 v[122:125], v134
	ds_read_b128 v[126:129], v134 offset:1024
	ds_read_b128 v[130:133], v134 offset:2048
	ds_read_b128 v[134:137], v134 offset:3072
	s_add_i32 m0, s89, 0xc000
	ds_read_b128 v[188:191], v193
	ds_read_b128 v[194:197], v193 offset:1024
	ds_read_b128 v[198:201], v193 offset:2048
	ds_read_b128 v[202:205], v193 offset:3072
	ds_read_b128 v[208:211], v193 offset:4096
	ds_read_b128 v[212:215], v193 offset:5120
	ds_read_b128 v[216:219], v193 offset:6144
	ds_read_b128 v[220:223], v193 offset:7168
	global_load_lds_dwordx4 v184, s[50:51]
	s_add_i32 m0, s89, 0xe000
	s_nop 0
	global_load_lds_dwordx4 v186, s[50:51]
	s_waitcnt vmcnt(8)
	s_waitcnt lgkmcnt(0)
	s_barrier
	s_setprio 1
	s_waitcnt lgkmcnt(0)
	v_mfma_f32_16x16x32_bf16 v[150:153], v[66:69], v[188:191], v[150:153]
	v_mfma_f32_16x16x32_bf16 v[110:113], v[74:77], v[188:191], v[110:113]
	v_mfma_f32_16x16x32_bf16 v[146:149], v[66:69], v[198:201], v[146:149]
	v_mfma_f32_16x16x32_bf16 v[106:109], v[74:77], v[198:201], v[106:109]
	v_mfma_f32_16x16x32_bf16 v[142:145], v[66:69], v[208:211], v[142:145]
	v_mfma_f32_16x16x32_bf16 v[102:105], v[74:77], v[208:211], v[102:105]
	v_mfma_f32_16x16x32_bf16 v[138:141], v[66:69], v[216:219], v[138:141]
	v_mfma_f32_16x16x32_bf16 v[98:101], v[74:77], v[216:219], v[98:101]
	v_mfma_f32_16x16x32_bf16 v[150:153], v[70:73], v[194:197], v[150:153]
	v_mfma_f32_16x16x32_bf16 v[110:113], v[78:81], v[194:197], v[110:113]
	v_mfma_f32_16x16x32_bf16 v[146:149], v[70:73], v[202:205], v[146:149]
	v_mfma_f32_16x16x32_bf16 v[106:109], v[78:81], v[202:205], v[106:109]
	v_mfma_f32_16x16x32_bf16 v[142:145], v[70:73], v[212:215], v[142:145]
	v_mfma_f32_16x16x32_bf16 v[102:105], v[78:81], v[212:215], v[102:105]
	v_mfma_f32_16x16x32_bf16 v[138:141], v[70:73], v[220:223], v[138:141]
	v_mfma_f32_16x16x32_bf16 v[98:101], v[78:81], v[220:223], v[98:101]
	s_setprio 0
	s_setprio 1
	v_mfma_f32_16x16x32_bf16 v[94:97], v[122:125], v[188:191], v[94:97]
	v_mfma_f32_16x16x32_bf16 v[90:93], v[130:133], v[188:191], v[90:93]
	v_mfma_f32_16x16x32_bf16 v[158:161], v[122:125], v[198:201], v[158:161]
	v_mfma_f32_16x16x32_bf16 v[118:121], v[130:133], v[198:201], v[118:121]
	v_mfma_f32_16x16x32_bf16 v[154:157], v[122:125], v[208:211], v[154:157]
	v_mfma_f32_16x16x32_bf16 v[114:117], v[130:133], v[208:211], v[114:117]
	v_mfma_f32_16x16x32_bf16 v[86:89], v[122:125], v[216:219], v[86:89]
	v_mfma_f32_16x16x32_bf16 v[82:85], v[130:133], v[216:219], v[82:85]
	v_mfma_f32_16x16x32_bf16 v[94:97], v[126:129], v[194:197], v[94:97]
	v_mfma_f32_16x16x32_bf16 v[90:93], v[134:137], v[194:197], v[90:93]
	v_mfma_f32_16x16x32_bf16 v[158:161], v[126:129], v[202:205], v[158:161]
	v_mfma_f32_16x16x32_bf16 v[118:121], v[134:137], v[202:205], v[118:121]
	v_mfma_f32_16x16x32_bf16 v[154:157], v[126:129], v[212:215], v[154:157]
	v_mfma_f32_16x16x32_bf16 v[114:117], v[134:137], v[212:215], v[114:117]
	v_mfma_f32_16x16x32_bf16 v[86:89], v[126:129], v[220:223], v[86:89]
	v_mfma_f32_16x16x32_bf16 v[82:85], v[134:137], v[220:223], v[82:85]
	s_setprio 0
	s_barrier
	s_add_i32 s63, s63, s1
	s_add_u32 s98, s52, 0x80
	s_addc_u32 s99, s53, 0
	s_mov_b32 m0, s63
	ds_read_b128 v[188:191], v193 offset:16384
	ds_read_b128 v[194:197], v193 offset:17408
	ds_read_b128 v[198:201], v193 offset:18432
	ds_read_b128 v[202:205], v193 offset:19456
	ds_read_b128 v[208:211], v193 offset:20480
	ds_read_b128 v[212:215], v193 offset:21504
	ds_read_b128 v[216:219], v193 offset:22528
	ds_read_b128 v[220:223], v193 offset:23552
	global_load_lds_dwordx4 v164, s[52:53]
	s_add_i32 m0, s63, 0x2000
	s_add_u32 s64, s52, 0x80000
	s_addc_u32 s65, s53, 0
	s_add_i32 s63, s66, s1
	global_load_lds_dwordx4 v168, s[52:53]
	s_mov_b32 m0, s63
	s_add_u32 s100, s54, 0x80
	s_addc_u32 s101, s55, 0
	global_load_lds_dwordx4 v164, s[64:65]
	s_add_i32 m0, s63, 0x2000
	s_nop 0
	global_load_lds_dwordx4 v168, s[64:65]
	s_mov_b32 m0, s89
	s_nop 0
	global_load_lds_dwordx4 v162, s[54:55]
	s_waitcnt vmcnt(7)
	s_waitcnt lgkmcnt(0)
	s_barrier
	s_setprio 1
	s_waitcnt lgkmcnt(0)
	v_mfma_f32_16x16x32_bf16 v[54:57], v[66:69], v[188:191], v[54:57]
	v_mfma_f32_16x16x32_bf16 v[30:33], v[74:77], v[188:191], v[30:33]
	v_mfma_f32_16x16x32_bf16 v[50:53], v[66:69], v[198:201], v[50:53]
	v_mfma_f32_16x16x32_bf16 v[26:29], v[74:77], v[198:201], v[26:29]
	v_mfma_f32_16x16x32_bf16 v[46:49], v[66:69], v[208:211], v[46:49]
	v_mfma_f32_16x16x32_bf16 v[22:25], v[74:77], v[208:211], v[22:25]
	v_mfma_f32_16x16x32_bf16 v[42:45], v[66:69], v[216:219], v[42:45]
	v_mfma_f32_16x16x32_bf16 v[16:19], v[74:77], v[216:219], v[16:19]
	v_mfma_f32_16x16x32_bf16 v[54:57], v[70:73], v[194:197], v[54:57]
	v_mfma_f32_16x16x32_bf16 v[30:33], v[78:81], v[194:197], v[30:33]
	v_mfma_f32_16x16x32_bf16 v[50:53], v[70:73], v[202:205], v[50:53]
	v_mfma_f32_16x16x32_bf16 v[26:29], v[78:81], v[202:205], v[26:29]
	v_mfma_f32_16x16x32_bf16 v[46:49], v[70:73], v[212:215], v[46:49]
	v_mfma_f32_16x16x32_bf16 v[22:25], v[78:81], v[212:215], v[22:25]
	v_mfma_f32_16x16x32_bf16 v[42:45], v[70:73], v[220:223], v[42:45]
	v_mfma_f32_16x16x32_bf16 v[16:19], v[78:81], v[220:223], v[16:19]
	s_setprio 0
	s_setprio 1
	v_mfma_f32_16x16x32_bf16 v[12:15], v[122:125], v[188:191], v[12:15]
	v_mfma_f32_16x16x32_bf16 v[8:11], v[130:133], v[188:191], v[8:11]
	v_mfma_f32_16x16x32_bf16 v[62:65], v[122:125], v[198:201], v[62:65]
	v_mfma_f32_16x16x32_bf16 v[38:41], v[130:133], v[198:201], v[38:41]
	v_mfma_f32_16x16x32_bf16 v[58:61], v[122:125], v[208:211], v[58:61]
	v_mfma_f32_16x16x32_bf16 v[34:37], v[130:133], v[208:211], v[34:37]
	v_mfma_f32_16x16x32_bf16 v[4:7], v[122:125], v[216:219], v[4:7]
	v_mfma_f32_16x16x32_bf16 v[0:3], v[130:133], v[216:219], v[0:3]
	v_mfma_f32_16x16x32_bf16 v[12:15], v[126:129], v[194:197], v[12:15]
	v_mfma_f32_16x16x32_bf16 v[8:11], v[134:137], v[194:197], v[8:11]
	v_mfma_f32_16x16x32_bf16 v[62:65], v[126:129], v[202:205], v[62:65]
	v_mfma_f32_16x16x32_bf16 v[38:41], v[134:137], v[202:205], v[38:41]
	v_mfma_f32_16x16x32_bf16 v[58:61], v[126:129], v[212:215], v[58:61]
	v_mfma_f32_16x16x32_bf16 v[34:37], v[134:137], v[212:215], v[34:37]
	v_mfma_f32_16x16x32_bf16 v[4:7], v[126:129], v[220:223], v[4:7]
	v_mfma_f32_16x16x32_bf16 v[0:3], v[134:137], v[220:223], v[0:3]
	s_setprio 0
	s_barrier
; #define PG8_STAGE(bufoff, gbase, voff) do { _Pragma("unroll") for (int _i = 0; _i < 2; ++_i) \
;         __builtin_amdgcn_global_load_lds((const unsigned*)((const char*)(gbase) + (voff)[_i]), (PG8_LAS unsigned*)(lds + (bufoff) + ldsw + _i * 8192), 16, 0, 0); } while (0)
; #define PG8_LDA(dst, b, h) do { _Pragma("unroll") for (int m = 0; m < 4; ++m) _Pragma("unroll") for (int k = 0; k < 2; ++k) dst[m][k] = *(const PG8_LAS bf16x8*)(lds + PG8_SA(b, h) + aoff + m * 2048 + k * 1024); } while (0)
; #define PG8_LDB(dst, b, h) do { _Pragma("unroll") for (int n = 0; n < 2; ++n) _Pragma("unroll") for (int k = 0; k < 2; ++k) dst[n][k] = *(const PG8_LAS bf16x8*)(lds + PG8_SB(b, h) + boff + n * 2048 + k * 1024); } while (0)
; #define PG8_MMA(ai, bj, At, Bt) do { __builtin_amdgcn_s_setprio(1); _Pragma("unroll") for (int m = 0; m < 4; ++m) _Pragma("unroll") for (int n = 0; n < 2; ++n) _Pragma("unroll") for (int k = 0; k < 2; ++k) \
;         acc[ai][bj][m][n] = __builtin_amdgcn_mfma_f32_16x16x32_bf16(Bt[n][k], At[m][k], acc[ai][bj][m][n], 0, 0, 0); __builtin_amdgcn_s_setprio(0); } while (0)
; #define PG8_WAIT_V(n) asm volatile("s_waitcnt vmcnt(" #n ")" ::: "memory")
; #define PG8_WAIT_L(n) asm volatile("s_waitcnt lgkmcnt(" #n ")" ::: "memory")
; #define PG8_BAR __builtin_amdgcn_s_barrier()
; #define PG8_SCHED __builtin_amdgcn_sched_barrier(0)
; template <class Epi, class Sched, bool ALIGN_EPI = false, bool SP2 = false>
; __device__ __forceinline__ void gemm_phase(PG8_LAS unsigned char* lds, const Gemm g, const Sched& S, const Epi& E, const int tid_in) {
;     ...
;             PG8_LDB(B0, 1, 0); PG8_LDB(B1, 1, 1); PG8_SCHED; PG8_LDA(At, 1, 0); PG8_STAGE(PG8_SA(0, 1), a2 + hstep, voffA);
;             PG8_WAIT_V(8); PG8_WAIT_L(0); PG8_BAR; PG8_MMA(0, 0, At, B0); PG8_MMA(0, 1, At, B1); PG8_BAR; PG8_SCHED;
;             PG8_LDA(At, 1, 1); PG8_STAGE(PG8_SB(1, 0), b3, voffB); PG8_STAGE(PG8_SB(1, 1), b3 + hstep, voffB); PG8_STAGE(PG8_SA(1, 0), a3, voffA);
;             PG8_WAIT_V(8); PG8_WAIT_L(0); PG8_BAR; PG8_MMA(1, 0, At, B0); PG8_MMA(1, 1, At, B1); PG8_BAR; PG8_SCHED;
	s_add_i32 s63, 0, 0x18000
	s_add_i32 s64, 0, 0x1c000
	v_add_u32_e32 v78, s63, v177
	v_add_u32_e32 v134, s64, v177
	ds_read_b128 v[66:69], v78
	ds_read_b128 v[70:73], v78 offset:1024
	ds_read_b128 v[74:77], v78 offset:2048
	ds_read_b128 v[78:81], v78 offset:3072
	ds_read_b128 v[122:125], v134
	ds_read_b128 v[126:129], v134 offset:1024
	ds_read_b128 v[130:133], v134 offset:2048
	ds_read_b128 v[134:137], v134 offset:3072
	s_mov_b32 m0, s92
	s_nop 0
	global_load_lds_dwordx4 v166, s[54:55]
	s_add_u32 s54, s54, 0x80000
	s_addc_u32 s55, s55, 0
	s_mov_b32 m0, s2
	ds_read_b128 v[188:191], v193 offset:32768
	ds_read_b128 v[194:197], v193 offset:33792
	ds_read_b128 v[198:201], v193 offset:34816
	ds_read_b128 v[202:205], v193 offset:35840
	ds_read_b128 v[208:211], v193 offset:36864
	ds_read_b128 v[212:215], v193 offset:37888
	ds_read_b128 v[216:219], v193 offset:38912
	ds_read_b128 v[220:223], v193 offset:39936
	global_load_lds_dwordx4 v162, s[54:55]
	s_mov_b32 m0, s3
	s_nop 0
	global_load_lds_dwordx4 v166, s[54:55]
	s_waitcnt vmcnt(8)
	s_waitcnt lgkmcnt(0)
	s_barrier
	s_setprio 1
	s_waitcnt lgkmcnt(0)
	v_mfma_f32_16x16x32_bf16 v[150:153], v[66:69], v[188:191], v[150:153]
	v_mfma_f32_16x16x32_bf16 v[110:113], v[74:77], v[188:191], v[110:113]
	v_mfma_f32_16x16x32_bf16 v[146:149], v[66:69], v[198:201], v[146:149]
	v_mfma_f32_16x16x32_bf16 v[106:109], v[74:77], v[198:201], v[106:109]
	v_mfma_f32_16x16x32_bf16 v[142:145], v[66:69], v[208:211], v[142:145]
	v_mfma_f32_16x16x32_bf16 v[102:105], v[74:77], v[208:211], v[102:105]
	v_mfma_f32_16x16x32_bf16 v[138:141], v[66:69], v[216:219], v[138:141]
	v_mfma_f32_16x16x32_bf16 v[98:101], v[74:77], v[216:219], v[98:101]
	v_mfma_f32_16x16x32_bf16 v[150:153], v[70:73], v[194:197], v[150:153]
	v_mfma_f32_16x16x32_bf16 v[110:113], v[78:81], v[194:197], v[110:113]
	v_mfma_f32_16x16x32_bf16 v[146:149], v[70:73], v[202:205], v[146:149]
	v_mfma_f32_16x16x32_bf16 v[106:109], v[78:81], v[202:205], v[106:109]
	v_mfma_f32_16x16x32_bf16 v[142:145], v[70:73], v[212:215], v[142:145]
	v_mfma_f32_16x16x32_bf16 v[102:105], v[78:81], v[212:215], v[102:105]
	v_mfma_f32_16x16x32_bf16 v[138:141], v[70:73], v[220:223], v[138:141]
	v_mfma_f32_16x16x32_bf16 v[98:101], v[78:81], v[220:223], v[98:101]
	s_setprio 0
	s_setprio 1
	v_mfma_f32_16x16x32_bf16 v[94:97], v[122:125], v[188:191], v[94:97]
	v_mfma_f32_16x16x32_bf16 v[90:93], v[130:133], v[188:191], v[90:93]
	v_mfma_f32_16x16x32_bf16 v[158:161], v[122:125], v[198:201], v[158:161]
	v_mfma_f32_16x16x32_bf16 v[118:121], v[130:133], v[198:201], v[118:121]
	v_mfma_f32_16x16x32_bf16 v[154:157], v[122:125], v[208:211], v[154:157]
	v_mfma_f32_16x16x32_bf16 v[114:117], v[130:133], v[208:211], v[114:117]
	v_mfma_f32_16x16x32_bf16 v[86:89], v[122:125], v[216:219], v[86:89]
	v_mfma_f32_16x16x32_bf16 v[82:85], v[130:133], v[216:219], v[82:85]
	v_mfma_f32_16x16x32_bf16 v[94:97], v[126:129], v[194:197], v[94:97]
	v_mfma_f32_16x16x32_bf16 v[90:93], v[134:137], v[194:197], v[90:93]
	v_mfma_f32_16x16x32_bf16 v[158:161], v[126:129], v[202:205], v[158:161]
	v_mfma_f32_16x16x32_bf16 v[118:121], v[134:137], v[202:205], v[118:121]
	v_mfma_f32_16x16x32_bf16 v[154:157], v[126:129], v[212:215], v[154:157]
	v_mfma_f32_16x16x32_bf16 v[114:117], v[134:137], v[212:215], v[114:117]
	v_mfma_f32_16x16x32_bf16 v[86:89], v[126:129], v[220:223], v[86:89]
	v_mfma_f32_16x16x32_bf16 v[82:85], v[134:137], v[220:223], v[82:85]
	s_setprio 0
	s_barrier
	s_add_i32 s54, s63, s1
	s_mov_b32 m0, s54
	ds_read_b128 v[188:191], v193 offset:49152
	ds_read_b128 v[194:197], v193 offset:50176
	ds_read_b128 v[198:201], v193 offset:51200
	ds_read_b128 v[202:205], v193 offset:52224
	ds_read_b128 v[208:211], v193 offset:53248
	ds_read_b128 v[212:215], v193 offset:54272
	ds_read_b128 v[216:219], v193 offset:55296
	ds_read_b128 v[220:223], v193 offset:56320
	global_load_lds_dwordx4 v164, s[98:99]
	s_add_i32 m0, s54, 0x2000
	s_add_u32 s52, s52, 0x80080
	s_addc_u32 s53, s53, 0
	s_add_i32 s54, s64, s1
	global_load_lds_dwordx4 v168, s[98:99]
	s_mov_b32 m0, s54
	s_nop 0
	global_load_lds_dwordx4 v164, s[52:53]
	s_add_i32 m0, s54, 0x2000
	s_nop 0
	global_load_lds_dwordx4 v168, s[52:53]
	s_mov_b32 m0, s24
	s_nop 0
	global_load_lds_dwordx4 v162, s[100:101]
	s_waitcnt vmcnt(7)
	s_waitcnt lgkmcnt(0)
	s_barrier
	s_setprio 1
	s_waitcnt lgkmcnt(0)
	v_mfma_f32_16x16x32_bf16 v[54:57], v[66:69], v[188:191], v[54:57]
	v_mfma_f32_16x16x32_bf16 v[30:33], v[74:77], v[188:191], v[30:33]
	v_mfma_f32_16x16x32_bf16 v[50:53], v[66:69], v[198:201], v[50:53]
	v_mfma_f32_16x16x32_bf16 v[26:29], v[74:77], v[198:201], v[26:29]
	v_mfma_f32_16x16x32_bf16 v[46:49], v[66:69], v[208:211], v[46:49]
	v_mfma_f32_16x16x32_bf16 v[22:25], v[74:77], v[208:211], v[22:25]
	v_mfma_f32_16x16x32_bf16 v[42:45], v[66:69], v[216:219], v[42:45]
	v_mfma_f32_16x16x32_bf16 v[16:19], v[74:77], v[216:219], v[16:19]
	v_mfma_f32_16x16x32_bf16 v[54:57], v[70:73], v[194:197], v[54:57]
	v_mfma_f32_16x16x32_bf16 v[30:33], v[78:81], v[194:197], v[30:33]
	v_mfma_f32_16x16x32_bf16 v[50:53], v[70:73], v[202:205], v[50:53]
	v_mfma_f32_16x16x32_bf16 v[26:29], v[78:81], v[202:205], v[26:29]
	v_mfma_f32_16x16x32_bf16 v[46:49], v[70:73], v[212:215], v[46:49]
	v_mfma_f32_16x16x32_bf16 v[22:25], v[78:81], v[212:215], v[22:25]
	v_mfma_f32_16x16x32_bf16 v[42:45], v[70:73], v[220:223], v[42:45]
	v_mfma_f32_16x16x32_bf16 v[16:19], v[78:81], v[220:223], v[16:19]
	s_setprio 0
	s_setprio 1
	v_mfma_f32_16x16x32_bf16 v[12:15], v[122:125], v[188:191], v[12:15]
	v_mfma_f32_16x16x32_bf16 v[8:11], v[130:133], v[188:191], v[8:11]
	v_mfma_f32_16x16x32_bf16 v[62:65], v[122:125], v[198:201], v[62:65]
	v_mfma_f32_16x16x32_bf16 v[38:41], v[130:133], v[198:201], v[38:41]
	v_mfma_f32_16x16x32_bf16 v[58:61], v[122:125], v[208:211], v[58:61]
	v_mfma_f32_16x16x32_bf16 v[34:37], v[130:133], v[208:211], v[34:37]
	v_mfma_f32_16x16x32_bf16 v[4:7], v[122:125], v[216:219], v[4:7]
	v_mfma_f32_16x16x32_bf16 v[0:3], v[130:133], v[216:219], v[0:3]
	v_mfma_f32_16x16x32_bf16 v[12:15], v[126:129], v[194:197], v[12:15]
	v_mfma_f32_16x16x32_bf16 v[8:11], v[134:137], v[194:197], v[8:11]
	v_mfma_f32_16x16x32_bf16 v[62:65], v[126:129], v[202:205], v[62:65]
	v_mfma_f32_16x16x32_bf16 v[38:41], v[134:137], v[202:205], v[38:41]
	v_mfma_f32_16x16x32_bf16 v[58:61], v[126:129], v[212:215], v[58:61]
	v_mfma_f32_16x16x32_bf16 v[34:37], v[134:137], v[212:215], v[34:37]
	v_mfma_f32_16x16x32_bf16 v[4:7], v[126:129], v[220:223], v[4:7]
	v_mfma_f32_16x16x32_bf16 v[0:3], v[134:137], v[220:223], v[0:3]
	s_setprio 0
	s_barrier
	s_add_i32 s62, s62, 2
	s_add_u32 s50, s50, 0x100
	s_addc_u32 s51, s51, 0
	s_add_u32 s60, s60, 0x100
	s_addc_u32 s61, s61, 0
	s_cmp_gt_u32 s62, 29
	s_cbranch_scc0 .LBB0_1157
	s_and_b64 vcc, exec, s[28:29]
	s_cbranch_vccz .LBB0_1160
	s_barrier

; #define PG8_STAGE(bufoff, gbase, voff) do { _Pragma("unroll") for (int _i = 0; _i < 2; ++_i) \
;         __builtin_amdgcn_global_load_lds((const unsigned*)((const char*)(gbase) + (voff)[_i]), (PG8_LAS unsigned*)(lds + (bufoff) + ldsw + _i * 8192), 16, 0, 0); } while (0)
; #define PG8_WAIT_V(n) asm volatile("s_waitcnt vmcnt(" #n ")" ::: "memory")
; template <class Epi, class Sched, bool ALIGN_EPI = false, bool SP2 = false>
; __device__ __forceinline__ void gemm_phase(PG8_LAS unsigned char* lds, const Gemm g, const Sched& S, const Epi& E, const int tid_in) {
;     ...
;     const int tid = tid_l, wid = __builtin_amdgcn_readfirstlane(tid >> 6), lane = tid & 63, wr = wid >> 2, wc = wid & 3, fr = lane & 15, fq = lane >> 4;
;     const int K = g.K, nt = K / BK;
;     unsigned voffA[2], voffB[2];
; #pragma unroll
;     for (int i = 0; i < 2; ++i) { int R, C; stage_rc(tid * 16 + i * 8192, R, C); const int Rb = perm_row<Epi::PMODE>(R);
;         voffA[i] = (unsigned)(R * K + C) * 2u; voffB[i] = (unsigned)(Rb * K + C) * 2u; }
;     const size_t kstep = (size_t)(BK * 2);
;     const size_t hstep = (size_t)HALF * K * 2;
;     const size_t tstep = 2 * hstep;
;     const unsigned ldsw = (unsigned)wid * 1024u;
;     const int aoff = lds_byte(wr * 64 + fr, fq * 8), boff = lds_byte(wc * 32 + fr, fq * 8);
;     ...
;     Unit cur, nxt; int ui = 0;
;     if (!S.next(0, cur)) return;
;     f32x4 acc[2][2][4][2];
; #pragma unroll
;     for (int a = 0; a < 2; ++a)
; #pragma unroll
;         for (int b = 0; b < 2; ++b)
; #pragma unroll
;             for (int m = 0; m < 4; ++m)
; #pragma unroll
;                 for (int n = 0; n < 2; ++n) acc[a][b][m][n] = (f32x4){0.f, 0.f, 0.f, 0.f};
;     bf16x8 At[4][2], B0[2][2], B1[2][2];
;     const char* cA = (const char*)g.A + (size_t)cur.pm * tstep; const char* cB = (const char*)g.Bt + (size_t)cur.pn * tstep;
;     S.a_ready(cur);
;     if constexpr (Epi::PREF) E.prefetch(cur, 0, lds, wid, lane);
;     if constexpr (SP2) {
;         PG8_STAGE(PG8_SB(0, 0), cB, voffB); PG8_STAGE(PG8_SB(0, 1), cB + hstep, voffB); PG8_STAGE(PG8_SA(0, 0), cA, voffA); PG8_STAGE(PG8_SA(0, 1), cA + hstep, voffA);
;         if (wr == 1) PG8_BAR;
;         PG8_WAIT_V(2); PG8_BAR;
;         PG8_STAGE(PG8_SB(1, 0), cB + kstep, voffB); PG8_STAGE(PG8_SA(1, 0), cA + kstep, voffA); PG8_STAGE(PG8_SB(1, 1), cB + hstep + kstep, voffB);
;         PG8_WAIT_V(6); PG8_BAR;
.LBB0_1291:
	s_ashr_i32 s23, s22, 31
	s_lshl_b64 s[6:7], s[22:23], 26
	s_add_u32 s6, s24, s6
	s_addc_u32 s7, s25, s7
	s_add_u32 s6, s6, 0x53200000
	s_addc_u32 s7, s7, 0
	s_lshl_b32 s22, s22, 2
	s_mul_hi_i32 s23, s35, 12
	s_mul_i32 s35, s35, 12
	s_ashr_i32 s36, s22, 31
	s_add_u32 s22, s35, s22
	s_addc_u32 s23, s23, s36
	s_mul_i32 s23, s23, 0xc000
	s_mul_hi_u32 s35, s22, 0xc000
	s_add_i32 s35, s35, s23
	s_mul_i32 s22, s22, 0xc000
	s_add_u32 s22, s24, s22
	v_lshrrev_b32_e32 v18, 1, v16
	s_addc_u32 s23, s25, s35
	v_and_b32_e32 v18, 24, v18
	s_add_u32 s44, s22, 0x10a000
	v_and_b32_e32 v17, 15, v16
	v_lshlrev_b32_e32 v19, 1, v18
	v_lshlrev_b32_e32 v16, 2, v16
	s_addc_u32 s45, s23, 0
	v_lshl_or_b32 v21, s34, 6, v17
	v_lshl_or_b32 v17, v17, 6, v19
	s_lshl_b32 s22, s34, 13
	v_and_b32_e32 v16, 32, v16
	v_bitop3_b32 v19, v17, s22, v16 bitop3:0xde
	s_lshl_b32 s22, s27, 5
	s_and_b32 s24, s22, 0x60
	s_add_i32 m0, s40, 0x18000
	v_lshl_add_u64 v[6:7], v[6:7], 0, s[12:13]
	s_lshl_b32 s22, s24, 7
	s_waitcnt vmcnt(2)
	s_barrier
	global_load_lds_dwordx4 v[6:7], off
	v_lshl_add_u64 v[4:5], v[4:5], 0, s[12:13]
	s_add_i32 m0, s40, 0x1a000
	s_add_i32 s46, s40, 0x8000
	s_add_i32 s47, s40, 0xa000
	v_bitop3_b32 v208, v17, s22, v16 bitop3:0xde
	global_load_lds_dwordx4 v[4:5], off
	v_lshl_add_u64 v[0:1], v[0:1], 0, s[12:13]
	s_mov_b32 m0, s46
	s_add_u32 s100, s28, 0x80
	s_addc_u32 s101, s29, 0
	s_add_u32 s22, s30, 0x160080
	global_load_lds_dwordx4 v[0:1], off
	v_lshl_add_u64 v[0:1], v[2:3], 0, s[12:13]
	s_mov_b32 m0, s47
	s_addc_u32 s23, s31, 0
	global_load_lds_dwordx4 v[0:1], off
	s_add_i32 m0, s40, 0x1c000
	v_lshl_add_u64 v[0:1], s[22:23], 0, v[218:219]
	global_load_lds_dwordx4 v[0:1], off
	v_lshl_add_u64 v[0:1], s[22:23], 0, v[214:215]
	s_add_i32 m0, s40, 0x1e000
	s_cmpk_lt_u32 s26, 0x100
	global_load_lds_dwordx4 v[0:1], off
	s_movk_i32 s26, 0x1600
	v_lshrrev_b32_e32 v1, 1, v13
	v_mul_lo_u32 v0, v12, s26
	s_mov_b32 s27, 0x16000
	v_or_b32_e32 v209, s24, v18
	v_mad_u64_u32 v[0:1], s[24:25], v1, s27, v[0:1]
	v_or_b32_e32 v0, v0, v14
	v_add_lshl_u32 v0, v0, v15, 1
	v_mov_b32_e32 v1, v20
	s_mov_b64 s[34:35], 0x160080
	v_lshl_add_u64 v[222:223], v[0:1], 0, s[34:35]
	v_lshrrev_b32_e32 v1, 1, v8
	v_mul_lo_u32 v0, v9, s26
	v_mad_u64_u32 v[0:1], s[24:25], v1, s27, v[0:1]
	s_waitcnt vmcnt(6)
	v_or_b32_e32 v0, v0, v10
	v_add_lshl_u32 v0, v0, v11, 1
	v_mov_b32_e32 v1, v20
	s_cselect_b64 s[22:23], -1, 0
	v_lshl_add_u64 v[224:225], v[0:1], 0, s[34:35]
	s_mov_b32 s49, 0
	v_add_u32_e32 v244, 0, v19
	v_readlane_b32 s53, v253, 58
	v_readlane_b32 s52, v253, 57
	s_barrier
	s_branch .LBB0_1294

; #define PG8_STAGE(bufoff, gbase, voff) do { _Pragma("unroll") for (int _i = 0; _i < 2; ++_i) \
;         __builtin_amdgcn_global_load_lds((const unsigned*)((const char*)(gbase) + (voff)[_i]), (PG8_LAS unsigned*)(lds + (bufoff) + ldsw + _i * 8192), 16, 0, 0); } while (0)
; #define PG8_LDA(dst, b, h) do { _Pragma("unroll") for (int m = 0; m < 4; ++m) _Pragma("unroll") for (int k = 0; k < 2; ++k) dst[m][k] = *(const PG8_LAS bf16x8*)(lds + PG8_SA(b, h) + aoff + m * 2048 + k * 1024); } while (0)
; #define PG8_LDB(dst, b, h) do { _Pragma("unroll") for (int n = 0; n < 2; ++n) _Pragma("unroll") for (int k = 0; k < 2; ++k) dst[n][k] = *(const PG8_LAS bf16x8*)(lds + PG8_SB(b, h) + boff + n * 2048 + k * 1024); } while (0)
; #define PG8_WAIT_V(n) asm volatile("s_waitcnt vmcnt(" #n ")" ::: "memory")
; #define PG8_WAIT_L(n) asm volatile("s_waitcnt lgkmcnt(" #n ")" ::: "memory")
; template <class Epi, class Sched, bool ALIGN_EPI = false, bool SP2 = false>
; __device__ __forceinline__ void gemm_phase(PG8_LAS unsigned char* lds, const Gemm g, const Sched& S, const Epi& E, const int tid_in) {
;     ...
;         const bool has_next = S.next(ui + 1, nxt);
;         const char* nA = has_next ? (const char*)g.A + (size_t)nxt.pm * tstep : cA; const char* nB = has_next ? (const char*)g.Bt + (size_t)nxt.pn * tstep : cB;
;         for (int t = 0; t < nt; t += 2) {
;             if constexpr (Epi::KSPLIT > 0) { if (t == Epi::KSPLIT / BK) E.midk(acc, cur, wr, wc, fr, fq); }
;             const bool last = (t == nt - 2);
;             const char* a1 = cA + (size_t)(t + 1) * kstep;
;             const char* a2 = last ? nA : cA + (size_t)(t + 2) * kstep; const char* b2 = last ? nB : cB + (size_t)(t + 2) * kstep;
;             const char* a3 = a2 + kstep; const char* b3 = b2 + kstep;
;             if (last && has_next) S.a_ready(nxt);
;             if constexpr (SP2) {
;             PG8_LDB(B0, 0, 0); PG8_LDB(B1, 0, 1); PG8_SCHED; PG8_LDA(At, 0, 0); PG8_STAGE(PG8_SA(1, 1), a1 + hstep, voffA);
;             PG8_WAIT_V(8); PG8_WAIT_L(0); PG8_BAR; PG8_MMA(0, 0, At, B0); PG8_MMA(0, 1, At, B1); PG8_BAR; PG8_SCHED;
;             PG8_LDA(At, 0, 1); PG8_STAGE(PG8_SB(0, 0), b2, voffB); PG8_STAGE(PG8_SB(0, 1), b2 + hstep, voffB); PG8_STAGE(PG8_SA(0, 0), a2, voffA);
;             PG8_WAIT_V(8); PG8_WAIT_L(0); PG8_BAR; PG8_MMA(1, 0, At, B0); PG8_MMA(1, 1, At, B1); PG8_BAR; PG8_SCHED;
.LBB0_1305:
	s_mov_b32 m0, s47
	s_nop 0
	global_load_lds_dwordx4 v216, s[100:101]
	s_add_u32 s30, s28, 0x100
	s_addc_u32 s31, s29, 0
	s_add_i32 s57, 0, 0x10000
	s_cmpk_eq_i32 s56, 0x54
	s_cselect_b32 s39, s25, s31
	s_cselect_b32 s38, s24, s30
	s_cselect_b32 s35, s27, s55
	s_cselect_b32 s34, s26, s54
	s_add_i32 s58, 0, 0x14000
	v_add_u32_e32 v102, s57, v208
	v_add_u32_e32 v142, s58, v208
	ds_read_b128 v[78:81], v102
	ds_read_b128 v[86:89], v102 offset:1024
	ds_read_b128 v[94:97], v102 offset:2048
	ds_read_b128 v[102:105], v102 offset:3072
	ds_read_b128 v[118:121], v142
	ds_read_b128 v[126:129], v142 offset:1024
	ds_read_b128 v[134:137], v142 offset:2048
	ds_read_b128 v[142:145], v142 offset:3072
	v_lshl_add_u64 v[194:195], s[28:29], 0, v[222:223]
	s_add_i32 m0, s40, 0xc000
	ds_read_b128 v[154:157], v244
	ds_read_b128 v[158:161], v244 offset:1024
	ds_read_b128 v[162:165], v244 offset:2048
	ds_read_b128 v[166:169], v244 offset:3072
	ds_read_b128 v[170:173], v244 offset:4096
	ds_read_b128 v[182:185], v244 offset:5120
	ds_read_b128 v[186:189], v244 offset:6144
	ds_read_b128 v[190:193], v244 offset:7168
	global_load_lds_dwordx4 v[194:195], off
	v_lshl_add_u64 v[194:195], s[28:29], 0, v[224:225]
	s_add_i32 m0, s40, 0xe000
	s_nop 0
	global_load_lds_dwordx4 v[194:195], off
	s_waitcnt vmcnt(8)
	s_waitcnt lgkmcnt(0)
	s_barrier
	s_setprio 1
	s_waitcnt lgkmcnt(0)
	v_mfma_f32_16x16x32_bf16 v[178:181], v[78:81], v[154:157], v[178:181]
	v_mfma_f32_16x16x32_bf16 v[174:177], v[94:97], v[154:157], v[174:177]
	v_mfma_f32_16x16x32_bf16 v[138:141], v[78:81], v[162:165], v[138:141]
	v_mfma_f32_16x16x32_bf16 v[130:133], v[94:97], v[162:165], v[130:133]
	v_mfma_f32_16x16x32_bf16 v[110:113], v[78:81], v[170:173], v[110:113]
	v_mfma_f32_16x16x32_bf16 v[106:109], v[94:97], v[170:173], v[106:109]
	v_mfma_f32_16x16x32_bf16 v[82:85], v[78:81], v[186:189], v[82:85]
	v_mfma_f32_16x16x32_bf16 v[74:77], v[94:97], v[186:189], v[74:77]
	v_mfma_f32_16x16x32_bf16 v[178:181], v[86:89], v[158:161], v[178:181]
	v_mfma_f32_16x16x32_bf16 v[174:177], v[102:105], v[158:161], v[174:177]
	v_mfma_f32_16x16x32_bf16 v[138:141], v[86:89], v[166:169], v[138:141]
	v_mfma_f32_16x16x32_bf16 v[130:133], v[102:105], v[166:169], v[130:133]
	v_mfma_f32_16x16x32_bf16 v[110:113], v[86:89], v[182:185], v[110:113]
	v_mfma_f32_16x16x32_bf16 v[106:109], v[102:105], v[182:185], v[106:109]
	v_mfma_f32_16x16x32_bf16 v[82:85], v[86:89], v[190:193], v[82:85]
	v_mfma_f32_16x16x32_bf16 v[74:77], v[102:105], v[190:193], v[74:77]
	s_setprio 0
	s_setprio 1
	v_mfma_f32_16x16x32_bf16 v[150:153], v[118:121], v[154:157], v[150:153]
	v_mfma_f32_16x16x32_bf16 v[146:149], v[134:137], v[154:157], v[146:149]
	v_mfma_f32_16x16x32_bf16 v[122:125], v[118:121], v[162:165], v[122:125]
	v_mfma_f32_16x16x32_bf16 v[114:117], v[134:137], v[162:165], v[114:117]
	v_mfma_f32_16x16x32_bf16 v[98:101], v[118:121], v[170:173], v[98:101]
	v_mfma_f32_16x16x32_bf16 v[90:93], v[134:137], v[170:173], v[90:93]
	v_mfma_f32_16x16x32_bf16 v[70:73], v[118:121], v[186:189], v[70:73]
	v_mfma_f32_16x16x32_bf16 v[66:69], v[134:137], v[186:189], v[66:69]
	v_mfma_f32_16x16x32_bf16 v[150:153], v[126:129], v[158:161], v[150:153]
	v_mfma_f32_16x16x32_bf16 v[146:149], v[142:145], v[158:161], v[146:149]
	v_mfma_f32_16x16x32_bf16 v[122:125], v[126:129], v[166:169], v[122:125]
	v_mfma_f32_16x16x32_bf16 v[114:117], v[142:145], v[166:169], v[114:117]
	v_mfma_f32_16x16x32_bf16 v[98:101], v[126:129], v[182:185], v[98:101]
	v_mfma_f32_16x16x32_bf16 v[90:93], v[142:145], v[182:185], v[90:93]
	v_mfma_f32_16x16x32_bf16 v[70:73], v[126:129], v[190:193], v[70:73]
	v_mfma_f32_16x16x32_bf16 v[66:69], v[142:145], v[190:193], v[66:69]
	s_setprio 0
	s_barrier
	s_add_i32 s28, s57, s19
	s_add_u32 s98, s34, 0x80
	s_addc_u32 s99, s35, 0
	s_mov_b32 m0, s28
	ds_read_b128 v[154:157], v244 offset:16384
	ds_read_b128 v[158:161], v244 offset:17408
	ds_read_b128 v[162:165], v244 offset:18432
	ds_read_b128 v[166:169], v244 offset:19456
	ds_read_b128 v[170:173], v244 offset:20480
	ds_read_b128 v[182:185], v244 offset:21504
	ds_read_b128 v[186:189], v244 offset:22528
	ds_read_b128 v[190:193], v244 offset:23552
	global_load_lds_dwordx4 v218, s[34:35]
	s_add_i32 m0, s28, 0x2000
	s_add_u32 s28, s34, 0x160000
	s_addc_u32 s29, s35, 0
	s_add_i32 s57, s58, s19
	global_load_lds_dwordx4 v214, s[34:35]
	s_mov_b32 m0, s57
	s_add_u32 s100, s38, 0x80
	s_addc_u32 s101, s39, 0
	global_load_lds_dwordx4 v218, s[28:29]
	s_add_i32 m0, s57, 0x2000
	s_nop 0
	global_load_lds_dwordx4 v214, s[28:29]
	s_mov_b32 m0, s40
	s_nop 0
	global_load_lds_dwordx4 v220, s[38:39]
	s_waitcnt vmcnt(7)
	s_waitcnt lgkmcnt(0)
	s_barrier
; #define PG8_STAGE(bufoff, gbase, voff) do { _Pragma("unroll") for (int _i = 0; _i < 2; ++_i) \
;         __builtin_amdgcn_global_load_lds((const unsigned*)((const char*)(gbase) + (voff)[_i]), (PG8_LAS unsigned*)(lds + (bufoff) + ldsw + _i * 8192), 16, 0, 0); } while (0)
; #define PG8_LDA(dst, b, h) do { _Pragma("unroll") for (int m = 0; m < 4; ++m) _Pragma("unroll") for (int k = 0; k < 2; ++k) dst[m][k] = *(const PG8_LAS bf16x8*)(lds + PG8_SA(b, h) + aoff + m * 2048 + k * 1024); } while (0)
; #define PG8_LDB(dst, b, h) do { _Pragma("unroll") for (int n = 0; n < 2; ++n) _Pragma("unroll") for (int k = 0; k < 2; ++k) dst[n][k] = *(const PG8_LAS bf16x8*)(lds + PG8_SB(b, h) + boff + n * 2048 + k * 1024); } while (0)
; #define PG8_MMA(ai, bj, At, Bt) do { __builtin_amdgcn_s_setprio(1); _Pragma("unroll") for (int m = 0; m < 4; ++m) _Pragma("unroll") for (int n = 0; n < 2; ++n) _Pragma("unroll") for (int k = 0; k < 2; ++k) \
;         acc[ai][bj][m][n] = __builtin_amdgcn_mfma_f32_16x16x32_bf16(Bt[n][k], At[m][k], acc[ai][bj][m][n], 0, 0, 0); __builtin_amdgcn_s_setprio(0); } while (0)
; #define PG8_WAIT_V(n) asm volatile("s_waitcnt vmcnt(" #n ")" ::: "memory")
; #define PG8_WAIT_L(n) asm volatile("s_waitcnt lgkmcnt(" #n ")" ::: "memory")
; #define PG8_BAR __builtin_amdgcn_s_barrier()
; #define PG8_SCHED __builtin_amdgcn_sched_barrier(0)
; template <class Epi, class Sched, bool ALIGN_EPI = false, bool SP2 = false>
; __device__ __forceinline__ void gemm_phase(PG8_LAS unsigned char* lds, const Gemm g, const Sched& S, const Epi& E, const int tid_in) {
;     ...
;             PG8_WAIT_V(8); PG8_WAIT_L(0); PG8_BAR; PG8_MMA(1, 0, At, B0); PG8_MMA(1, 1, At, B1); PG8_BAR; PG8_SCHED;
;             PG8_LDB(B0, 1, 0); PG8_LDB(B1, 1, 1); PG8_SCHED; PG8_LDA(At, 1, 0); PG8_STAGE(PG8_SA(0, 1), a2 + hstep, voffA);
;             PG8_WAIT_V(8); PG8_WAIT_L(0); PG8_BAR; PG8_MMA(0, 0, At, B0); PG8_MMA(0, 1, At, B1); PG8_BAR; PG8_SCHED;
	s_setprio 1
	s_waitcnt lgkmcnt(0)
	v_mfma_f32_16x16x32_bf16 v[62:65], v[78:81], v[154:157], v[62:65]
	v_mfma_f32_16x16x32_bf16 v[58:61], v[94:97], v[154:157], v[58:61]
	v_mfma_f32_16x16x32_bf16 v[46:49], v[78:81], v[162:165], v[46:49]
	v_mfma_f32_16x16x32_bf16 v[42:45], v[94:97], v[162:165], v[42:45]
	v_mfma_f32_16x16x32_bf16 v[30:33], v[78:81], v[170:173], v[30:33]
	v_mfma_f32_16x16x32_bf16 v[26:29], v[94:97], v[170:173], v[26:29]
	v_mfma_f32_16x16x32_bf16 v[12:15], v[78:81], v[186:189], v[12:15]
	v_mfma_f32_16x16x32_bf16 v[8:11], v[94:97], v[186:189], v[8:11]
	v_mfma_f32_16x16x32_bf16 v[62:65], v[86:89], v[158:161], v[62:65]
	v_mfma_f32_16x16x32_bf16 v[58:61], v[102:105], v[158:161], v[58:61]
	v_mfma_f32_16x16x32_bf16 v[46:49], v[86:89], v[166:169], v[46:49]
	v_mfma_f32_16x16x32_bf16 v[42:45], v[102:105], v[166:169], v[42:45]
	v_mfma_f32_16x16x32_bf16 v[30:33], v[86:89], v[182:185], v[30:33]
	v_mfma_f32_16x16x32_bf16 v[26:29], v[102:105], v[182:185], v[26:29]
	v_mfma_f32_16x16x32_bf16 v[12:15], v[86:89], v[190:193], v[12:15]
	v_mfma_f32_16x16x32_bf16 v[8:11], v[102:105], v[190:193], v[8:11]
	s_setprio 0
	s_setprio 1
	v_mfma_f32_16x16x32_bf16 v[54:57], v[118:121], v[154:157], v[54:57]
	v_mfma_f32_16x16x32_bf16 v[50:53], v[134:137], v[154:157], v[50:53]
	v_mfma_f32_16x16x32_bf16 v[38:41], v[118:121], v[162:165], v[38:41]
	v_mfma_f32_16x16x32_bf16 v[34:37], v[134:137], v[162:165], v[34:37]
	v_mfma_f32_16x16x32_bf16 v[22:25], v[118:121], v[170:173], v[22:25]
	v_mfma_f32_16x16x32_bf16 v[16:19], v[134:137], v[170:173], v[16:19]
	v_mfma_f32_16x16x32_bf16 v[4:7], v[118:121], v[186:189], v[4:7]
	v_mfma_f32_16x16x32_bf16 v[0:3], v[134:137], v[186:189], v[0:3]
	v_mfma_f32_16x16x32_bf16 v[54:57], v[126:129], v[158:161], v[54:57]
	v_mfma_f32_16x16x32_bf16 v[50:53], v[142:145], v[158:161], v[50:53]
	v_mfma_f32_16x16x32_bf16 v[38:41], v[126:129], v[166:169], v[38:41]
	v_mfma_f32_16x16x32_bf16 v[34:37], v[142:145], v[166:169], v[34:37]
	v_mfma_f32_16x16x32_bf16 v[22:25], v[126:129], v[182:185], v[22:25]
	v_mfma_f32_16x16x32_bf16 v[16:19], v[142:145], v[182:185], v[16:19]
	v_mfma_f32_16x16x32_bf16 v[4:7], v[126:129], v[190:193], v[4:7]
	v_mfma_f32_16x16x32_bf16 v[0:3], v[142:145], v[190:193], v[0:3]
	s_setprio 0
	s_barrier
	s_add_i32 s57, 0, 0x18000
	s_add_i32 s58, 0, 0x1c000
	v_add_u32_e32 v102, s57, v208
	v_add_u32_e32 v142, s58, v208
	ds_read_b128 v[78:81], v102
	ds_read_b128 v[86:89], v102 offset:1024
	ds_read_b128 v[94:97], v102 offset:2048
	ds_read_b128 v[102:105], v102 offset:3072
	ds_read_b128 v[118:121], v142
	ds_read_b128 v[126:129], v142 offset:1024
	ds_read_b128 v[134:137], v142 offset:2048
	ds_read_b128 v[142:145], v142 offset:3072
	s_add_u32 s28, s38, 0x160000
	s_addc_u32 s29, s39, 0
	s_mov_b32 m0, s41
	s_nop 0
	global_load_lds_dwordx4 v216, s[38:39]
	s_mov_b32 m0, s42
	ds_read_b128 v[154:157], v244 offset:32768
	ds_read_b128 v[158:161], v244 offset:33792
	ds_read_b128 v[162:165], v244 offset:34816
	ds_read_b128 v[166:169], v244 offset:35840
	ds_read_b128 v[170:173], v244 offset:36864
	ds_read_b128 v[182:185], v244 offset:37888
	ds_read_b128 v[186:189], v244 offset:38912
	ds_read_b128 v[190:193], v244 offset:39936
	global_load_lds_dwordx4 v220, s[28:29]
	s_mov_b32 m0, s43
	s_nop 0
	global_load_lds_dwordx4 v216, s[28:29]
	s_waitcnt vmcnt(8)
	s_waitcnt lgkmcnt(0)
	s_barrier
	s_setprio 1
	s_waitcnt lgkmcnt(0)
	v_mfma_f32_16x16x32_bf16 v[178:181], v[78:81], v[154:157], v[178:181]
	v_mfma_f32_16x16x32_bf16 v[174:177], v[94:97], v[154:157], v[174:177]
	v_mfma_f32_16x16x32_bf16 v[138:141], v[78:81], v[162:165], v[138:141]
	v_mfma_f32_16x16x32_bf16 v[130:133], v[94:97], v[162:165], v[130:133]
	v_mfma_f32_16x16x32_bf16 v[110:113], v[78:81], v[170:173], v[110:113]
	v_mfma_f32_16x16x32_bf16 v[106:109], v[94:97], v[170:173], v[106:109]
	v_mfma_f32_16x16x32_bf16 v[82:85], v[78:81], v[186:189], v[82:85]
	v_mfma_f32_16x16x32_bf16 v[74:77], v[94:97], v[186:189], v[74:77]
	v_mfma_f32_16x16x32_bf16 v[178:181], v[86:89], v[158:161], v[178:181]
	v_mfma_f32_16x16x32_bf16 v[174:177], v[102:105], v[158:161], v[174:177]
	v_mfma_f32_16x16x32_bf16 v[138:141], v[86:89], v[166:169], v[138:141]
	v_mfma_f32_16x16x32_bf16 v[130:133], v[102:105], v[166:169], v[130:133]
	v_mfma_f32_16x16x32_bf16 v[110:113], v[86:89], v[182:185], v[110:113]
	v_mfma_f32_16x16x32_bf16 v[106:109], v[102:105], v[182:185], v[106:109]
	v_mfma_f32_16x16x32_bf16 v[82:85], v[86:89], v[190:193], v[82:85]
	v_mfma_f32_16x16x32_bf16 v[74:77], v[102:105], v[190:193], v[74:77]
	s_setprio 0
	s_setprio 1
	v_mfma_f32_16x16x32_bf16 v[150:153], v[118:121], v[154:157], v[150:153]
	v_mfma_f32_16x16x32_bf16 v[146:149], v[134:137], v[154:157], v[146:149]
	v_mfma_f32_16x16x32_bf16 v[122:125], v[118:121], v[162:165], v[122:125]
	v_mfma_f32_16x16x32_bf16 v[114:117], v[134:137], v[162:165], v[114:117]
	v_mfma_f32_16x16x32_bf16 v[98:101], v[118:121], v[170:173], v[98:101]
	v_mfma_f32_16x16x32_bf16 v[90:93], v[134:137], v[170:173], v[90:93]
	v_mfma_f32_16x16x32_bf16 v[70:73], v[118:121], v[186:189], v[70:73]
	v_mfma_f32_16x16x32_bf16 v[66:69], v[134:137], v[186:189], v[66:69]
	v_mfma_f32_16x16x32_bf16 v[150:153], v[126:129], v[158:161], v[150:153]
	v_mfma_f32_16x16x32_bf16 v[146:149], v[142:145], v[158:161], v[146:149]
	v_mfma_f32_16x16x32_bf16 v[122:125], v[126:129], v[166:169], v[122:125]
	v_mfma_f32_16x16x32_bf16 v[114:117], v[142:145], v[166:169], v[114:117]
	v_mfma_f32_16x16x32_bf16 v[98:101], v[126:129], v[182:185], v[98:101]
	v_mfma_f32_16x16x32_bf16 v[90:93], v[142:145], v[182:185], v[90:93]
	v_mfma_f32_16x16x32_bf16 v[70:73], v[126:129], v[190:193], v[70:73]
	v_mfma_f32_16x16x32_bf16 v[66:69], v[142:145], v[190:193], v[66:69]
	s_setprio 0
	s_barrier
; #define PG8_STAGE(bufoff, gbase, voff) do { _Pragma("unroll") for (int _i = 0; _i < 2; ++_i) \
;         __builtin_amdgcn_global_load_lds((const unsigned*)((const char*)(gbase) + (voff)[_i]), (PG8_LAS unsigned*)(lds + (bufoff) + ldsw + _i * 8192), 16, 0, 0); } while (0)
; #define PG8_LDA(dst, b, h) do { _Pragma("unroll") for (int m = 0; m < 4; ++m) _Pragma("unroll") for (int k = 0; k < 2; ++k) dst[m][k] = *(const PG8_LAS bf16x8*)(lds + PG8_SA(b, h) + aoff + m * 2048 + k * 1024); } while (0)
; #define PG8_MMA(ai, bj, At, Bt) do { __builtin_amdgcn_s_setprio(1); _Pragma("unroll") for (int m = 0; m < 4; ++m) _Pragma("unroll") for (int n = 0; n < 2; ++n) _Pragma("unroll") for (int k = 0; k < 2; ++k) \
;         acc[ai][bj][m][n] = __builtin_amdgcn_mfma_f32_16x16x32_bf16(Bt[n][k], At[m][k], acc[ai][bj][m][n], 0, 0, 0); __builtin_amdgcn_s_setprio(0); } while (0)
; #define PG8_WAIT_V(n) asm volatile("s_waitcnt vmcnt(" #n ")" ::: "memory")
; #define PG8_WAIT_L(n) asm volatile("s_waitcnt lgkmcnt(" #n ")" ::: "memory")
; #define PG8_BAR __builtin_amdgcn_s_barrier()
; #define PG8_SCHED __builtin_amdgcn_sched_barrier(0)
; template <class Epi, class Sched, bool ALIGN_EPI = false, bool SP2 = false>
; __device__ __forceinline__ void gemm_phase(PG8_LAS unsigned char* lds, const Gemm g, const Sched& S, const Epi& E, const int tid_in) {
;     ...
;             PG8_LDA(At, 1, 1); PG8_STAGE(PG8_SB(1, 0), b3, voffB); PG8_STAGE(PG8_SB(1, 1), b3 + hstep, voffB); PG8_STAGE(PG8_SA(1, 0), a3, voffA);
;             PG8_WAIT_V(8); PG8_WAIT_L(0); PG8_BAR; PG8_MMA(1, 0, At, B0); PG8_MMA(1, 1, At, B1); PG8_BAR; PG8_SCHED;
	s_add_i32 s28, s57, s19
	s_mov_b32 m0, s28
	ds_read_b128 v[154:157], v244 offset:49152
	ds_read_b128 v[158:161], v244 offset:50176
	ds_read_b128 v[162:165], v244 offset:51200
	ds_read_b128 v[166:169], v244 offset:52224
	ds_read_b128 v[170:173], v244 offset:53248
	ds_read_b128 v[182:185], v244 offset:54272
	ds_read_b128 v[186:189], v244 offset:55296
	ds_read_b128 v[190:193], v244 offset:56320
	global_load_lds_dwordx4 v218, s[98:99]
	s_add_i32 m0, s28, 0x2000
	s_add_u32 s28, s34, 0x160080
	s_addc_u32 s29, s35, 0
	s_add_i32 s34, s58, s19
	global_load_lds_dwordx4 v214, s[98:99]
	s_mov_b32 m0, s34
	s_nop 0
	global_load_lds_dwordx4 v218, s[28:29]
	s_add_i32 m0, s34, 0x2000
	s_nop 0
	global_load_lds_dwordx4 v214, s[28:29]
	s_mov_b32 m0, s46
	s_nop 0
	global_load_lds_dwordx4 v220, s[100:101]
	s_waitcnt vmcnt(7)
	s_waitcnt lgkmcnt(0)
	s_barrier
	s_setprio 1
	s_waitcnt lgkmcnt(0)
	v_mfma_f32_16x16x32_bf16 v[62:65], v[78:81], v[154:157], v[62:65]
	v_mfma_f32_16x16x32_bf16 v[58:61], v[94:97], v[154:157], v[58:61]
	v_mfma_f32_16x16x32_bf16 v[46:49], v[78:81], v[162:165], v[46:49]
	v_mfma_f32_16x16x32_bf16 v[42:45], v[94:97], v[162:165], v[42:45]
	v_mfma_f32_16x16x32_bf16 v[30:33], v[78:81], v[170:173], v[30:33]
	v_mfma_f32_16x16x32_bf16 v[26:29], v[94:97], v[170:173], v[26:29]
	v_mfma_f32_16x16x32_bf16 v[12:15], v[78:81], v[186:189], v[12:15]
	v_mfma_f32_16x16x32_bf16 v[8:11], v[94:97], v[186:189], v[8:11]
	v_mfma_f32_16x16x32_bf16 v[62:65], v[86:89], v[158:161], v[62:65]
	v_mfma_f32_16x16x32_bf16 v[58:61], v[102:105], v[158:161], v[58:61]
	v_mfma_f32_16x16x32_bf16 v[46:49], v[86:89], v[166:169], v[46:49]
	v_mfma_f32_16x16x32_bf16 v[42:45], v[102:105], v[166:169], v[42:45]
	v_mfma_f32_16x16x32_bf16 v[30:33], v[86:89], v[182:185], v[30:33]
	v_mfma_f32_16x16x32_bf16 v[26:29], v[102:105], v[182:185], v[26:29]
	v_mfma_f32_16x16x32_bf16 v[12:15], v[86:89], v[190:193], v[12:15]
	v_mfma_f32_16x16x32_bf16 v[8:11], v[102:105], v[190:193], v[8:11]
	s_setprio 0
	s_setprio 1
	v_mfma_f32_16x16x32_bf16 v[54:57], v[118:121], v[154:157], v[54:57]
	v_mfma_f32_16x16x32_bf16 v[50:53], v[134:137], v[154:157], v[50:53]
	v_mfma_f32_16x16x32_bf16 v[38:41], v[118:121], v[162:165], v[38:41]
	v_mfma_f32_16x16x32_bf16 v[34:37], v[134:137], v[162:165], v[34:37]
	v_mfma_f32_16x16x32_bf16 v[22:25], v[118:121], v[170:173], v[22:25]
	v_mfma_f32_16x16x32_bf16 v[16:19], v[134:137], v[170:173], v[16:19]
	v_mfma_f32_16x16x32_bf16 v[4:7], v[118:121], v[186:189], v[4:7]
	v_mfma_f32_16x16x32_bf16 v[0:3], v[134:137], v[186:189], v[0:3]
	v_mfma_f32_16x16x32_bf16 v[54:57], v[126:129], v[158:161], v[54:57]
	v_mfma_f32_16x16x32_bf16 v[50:53], v[142:145], v[158:161], v[50:53]
	v_mfma_f32_16x16x32_bf16 v[38:41], v[126:129], v[166:169], v[38:41]
	v_mfma_f32_16x16x32_bf16 v[34:37], v[142:145], v[166:169], v[34:37]
	v_mfma_f32_16x16x32_bf16 v[22:25], v[126:129], v[182:185], v[22:25]
	v_mfma_f32_16x16x32_bf16 v[16:19], v[142:145], v[182:185], v[16:19]
	v_mfma_f32_16x16x32_bf16 v[4:7], v[126:129], v[190:193], v[4:7]
	v_mfma_f32_16x16x32_bf16 v[0:3], v[142:145], v[190:193], v[0:3]
	s_setprio 0
	s_barrier
	s_add_i32 s56, s56, 2
	s_add_u32 s54, s54, 0x100
	s_addc_u32 s55, s55, 0
	s_cmpk_gt_u32 s56, 0x55
	s_mov_b64 s[28:29], s[30:31]
	s_cbranch_scc0 .LBB0_1305
	v_mov_b32_e32 v207, 0x7f800000
	s_and_b64 vcc, exec, s[22:23]
	s_cbranch_vccz .LBB0_1308
	s_barrier
